# static priority strategy: all per-segment s_setprio in the GEMM loops deleted, one s_setprio 1 for waves 0-3 at each GEMM phase start (v31 base)
# speedup vs baseline: 1.0105x; 1.0105x over previous
; #define LAS __attribute__((address_space(3)))
; __device__ __forceinline__ void p0_prologue(const Args& a, LAS unsigned char* lds, int gw, int NGW, int wave, int lane) {
;     LAS float* scr = (LAS float*)(lds + wave * 16384);
;     unsigned char* ws = a.ws;
;     constexpr int I_G = (D / 64) * (FF / 32), I_D = (FF / 64) * (D / 32), I_FFN = 2 * I_G + I_D;
;     constexpr int I_FOX = (D / 64) * (NQKV_FOX / 32), I_F = D / 64, I_O = (D / 64) * (D / 32), I_SWA = (D / 64) * (NQKV_SWA / 32);
;     constexpr int NITEMS = 4 * I_FFN + I_FOX + I_F + I_O + I_SWA + I_O;
;     for (int it = gw; it < NITEMS; it += NGW) {
;         int r = it;
;         if (r < 4 * I_FFN) {
;             const int f = r / I_FFN; r -= f * I_FFN;
;             const int kind = r / I_G; r -= kind * I_G;
;             const int ib = f == 0 ? 1 : f == 1 ? 9 : f == 2 ? 13 : 21;
;             const float* gain = a.in[ib]; const float* wg = a.in[ib + 1]; const float* wu = a.in[ib + 2]; const float* wd = a.in[ib + 3];
;             bf16* Wgu = (bf16*)(ws + WS_W + f * FFN_STRIDE); bf16* Wd = (bf16*)(ws + WS_W + f * FFN_STRIDE + WD_OFF);
;             if (kind < 2) { const int nblk = FF / 32, kb = r / nblk, nb = r % nblk, n0 = 32 * nb;
;                 p0_item(kind == 0 ? wg : wu, FF, 64 * kb, n0, 32, gain, Wgu, D, 256 * (n0 / 128) + 128 * kind + (n0 % 128), scr, lane); }
;             else { const int nblk = D / 32, kb = r / nblk, nb = r % nblk; p0_item(wd, D, 64 * kb, 32 * nb, 32, nullptr, Wd, FF, 32 * nb, scr, lane); }
;             continue;
;         }
;         r -= 4 * I_FFN;
;         if (r < I_FOX) { const int nblk = NQKV_FOX / 32, kb = r / nblk, nb = r % nblk; p0_item(a.in[6], NFOX_IN, 64 * kb, 32 * nb, 32, a.in[5], (bf16*)(ws + WS_WFOX), D, 32 * nb, scr, lane); continue; }
;         r -= I_FOX;
;         if (r < I_F) { p0_item(a.in[6], NFOX_IN, 64 * r, NQKV_FOX, 16, a.in[5], (bf16*)(ws + WS_WF), D, 0, scr, lane); continue; }
;         r -= I_F;
;         if (r < I_O) { const int nblk = D / 32, kb = r / nblk, nb = r % nblk; p0_item(a.in[8], D, 64 * kb, 32 * nb, 32, nullptr, (bf16*)(ws + WS_WOFOX), D, 32 * nb, scr, lane); continue; }
;         r -= I_O;
;         if (r < I_SWA) { const int nblk = NQKV_SWA / 32, kb = r / nblk, nb = r % nblk; p0_item(a.in[18], NQKV_SWA, 64 * kb, 32 * nb, 32, a.in[17], (bf16*)(ws + WS_WSWA), D, 32 * nb, scr, lane); continue; }
;         r -= I_SWA;
.LBB0_20:
	s_or_b64 exec, exec, s[4:5]
	s_load_dwordx2 s[6:7], s[0:1], 0xe0
	s_waitcnt lgkmcnt(0)
	s_setprio 0
	s_cmp_lt_i32 s6, 1
	s_cselect_b64 s[4:5], -1, 0
	s_cmp_gt_i32 s7, 0
	s_cselect_b64 s[8:9], -1, 0
	s_and_b64 s[4:5], s[4:5], s[8:9]
	s_andn2_b64 vcc, exec, s[4:5]
	s_cbranch_vccnz .LBB0_222
	s_load_dwordx2 s[8:9], s[0:1], 0xd8
	v_readfirstlane_b32 s3, v242
	s_lshr_b32 s6, s3, 6
	s_lshl_b32 s3, s2, 3
	s_add_i32 s3, s6, s3
	s_cmpk_gt_i32 s3, 0x4e8f
	v_and_b32_e32 v39, 63, v242
	s_cbranch_scc1 .LBB0_142
	v_and_b32_e32 v2, 7, v242
	v_mov_b32_e32 v37, 0
	v_lshlrev_b32_e32 v36, 4, v2
	s_waitcnt lgkmcnt(0)
	v_lshl_add_u64 v[0:1], s[8:9], 0, v[36:37]
	s_mov_b64 s[12:13], 0x400000
	v_lshl_add_u64 v[46:47], v[0:1], 0, s[12:13]
	s_mov_b64 s[12:13], 0x4c00000
	v_lshl_add_u64 v[48:49], v[0:1], 0, s[12:13]
	s_load_dwordx2 s[20:21], s[0:1], 0xa0
	s_load_dwordx4 s[12:15], s[0:1], 0x88
	s_lshl_b32 s4, s6, 14
	s_lshl_b32 s42, s61, 3
	s_add_i32 s7, s4, 0
	s_load_dwordx4 s[16:19], s[0:1], 0x28
	s_load_dwordx2 s[22:23], s[0:1], 0x40
	s_add_u32 s43, s8, 0x800000
	s_addc_u32 s44, s9, 0
	v_lshrrev_b32_e32 v34, 3, v39
	s_waitcnt lgkmcnt(0)
	s_cmp_lg_u64 s[12:13], 0
	v_mul_u32_u24_e32 v4, 0x420, v2
	v_lshlrev_b32_e32 v6, 2, v34
	s_cselect_b64 s[36:37], -1, 0
	s_cmp_lg_u64 s[16:17], 0
	v_lshl_add_u64 v[56:57], s[18:19], 0, v[36:37]
	s_mov_b64 s[18:19], 0x3000
	v_add_u32_e32 v3, s7, v36
	s_mov_b64 s[4:5], 0x5700000
	v_add3_u32 v79, s7, v4, v6
	v_lshl_add_u64 v[52:53], s[14:15], 0, v[36:37]
	s_cselect_b64 s[14:15], -1, 0
	v_lshl_add_u64 v[58:59], v[56:57], 0, s[18:19]
	s_lshl_b32 s7, s2, 8
	s_lshl_b32 s18, s6, 5
	v_lshl_add_u64 v[40:41], v[0:1], 0, s[4:5]
	s_mov_b64 s[4:5], 0x5400000
	s_add_i32 s45, s7, s18
	s_lshl_b32 s7, s2, 4
	s_lshl_b32 s18, s6, 1
	v_or_b32_e32 v33, 8, v34
	v_mul_u32_u24_e32 v5, 0x84, v34
	v_lshl_add_u64 v[42:43], v[0:1], 0, s[4:5]
	s_mov_b64 s[4:5], 0x5200000
	s_add_i32 s47, s7, s18
	s_lshl_b32 s7, s2, 9
	s_lshl_b32 s6, s6, 6
	v_lshlrev_b32_e32 v32, 2, v2
	v_lshlrev_b32_e32 v38, 3, v2
	v_lshl_add_u64 v[44:45], v[0:1], 0, s[4:5]
	v_cmp_gt_u32_e64 s[4:5], 4, v2
	v_lshlrev_b32_e32 v2, 10, v34
	v_lshlrev_b32_e32 v4, 10, v33
	s_add_i32 s6, s7, s6
	v_add_u32_e32 v80, v3, v5
	s_mov_b32 s35, 0
	v_or_b32_e32 v67, 16, v34
	v_or_b32_e32 v69, 24, v34
	v_or_b32_e32 v71, 32, v34
	v_or_b32_e32 v73, 40, v34
	v_or_b32_e32 v75, 48, v34
	v_or_b32_e32 v77, 56, v34
	v_lshl_add_u64 v[50:51], s[20:21], 0, v[36:37]
	v_lshl_add_u64 v[54:55], s[22:23], 0, v[36:37]
	v_mov_b32_e32 v35, v37
	s_lshl_b32 s46, s61, 8
	s_lshl_b32 s48, s61, 4
	s_add_i32 s34, s6, 0xffee0000
	s_lshl_b32 s49, s61, 9
	v_add_u32_e32 v81, 0x420, v80
	v_add_u32_e32 v82, 0x428, v80
	v_add_u32_e32 v83, 0x840, v80
	v_add_u32_e32 v84, 0x848, v80
	v_add_u32_e32 v85, 0xc60, v80
	v_add_u32_e32 v86, 0xc68, v80
	v_add_u32_e32 v87, 0x1080, v80
	s_movk_i32 s50, 0x3040
	v_lshlrev_b32_e32 v60, 1, v2
	v_lshlrev_b32_e32 v62, 1, v4
	s_mov_b64 s[18:19], 0xb00000
	s_movk_i32 s51, 0xb00
	s_movk_i32 s52, 0x2c00
	v_add_u32_e32 v88, 0x1088, v80
	v_add_u32_e32 v89, 0x14a0, v80
	v_add_u32_e32 v90, 0x14a8, v80
	v_add_u32_e32 v91, 0x18c0, v80
	v_add_u32_e32 v92, 0x18c8, v80
	v_add_u32_e32 v93, 0x1ce0, v80
	v_add_u32_e32 v94, 0x1ce8, v80
	s_mov_b32 s53, s3
	s_branch .LBB0_26

; template <class Epi, class Sched, bool ALIGN_EPI = false, bool SP2 = false>
; __device__ __forceinline__ void gemm_phase(PG8_LAS unsigned char* lds, const Gemm g, const Sched& S, const Epi& E) {
;     const int tid = threadIdx.x, wid = __builtin_amdgcn_readfirstlane(tid >> 6), lane = tid & 63, wr = wid >> 2, wc = wid & 3, fr = lane & 15, fq = lane >> 4;
;     const int K = g.K, nt = K / BK;
;     unsigned voffA[2], voffB[2];
; #pragma unroll
;     for (int i = 0; i < 2; ++i) { int R, C; stage_rc(tid * 16 + i * 8192, R, C); const int Rb = Epi::PERM ? ((R & ~31) + perm32(R & 31)) : R;
;         voffA[i] = (unsigned)(R * K + C) * 2u; voffB[i] = (unsigned)(Rb * K + C) * 2u; }
;     const size_t kstep = (size_t)(BK * 2);
;     const size_t hstep = (size_t)HALF * K * 2;
;     const size_t tstep = 2 * hstep;
;     const unsigned ldsw = (unsigned)wid * 1024u;
;     const int aoff = lds_byte(wr * 64 + fr, fq * 8), boff = lds_byte(wc * 32 + fr, fq * 8);
;     ...
;     Unit cur, nxt; int ui = 0;
;     if (!S.next(0, cur)) return;
;     f32x4 acc[2][2][4][2];
; #pragma unroll
;     for (int a = 0; a < 2; ++a)
; #pragma unroll
;         for (int b = 0; b < 2; ++b)
; #pragma unroll
;             for (int m = 0; m < 4; ++m)
; #pragma unroll
;                 for (int n = 0; n < 2; ++n) acc[a][b][m][n] = (f32x4){0.f, 0.f, 0.f, 0.f};
;     bf16x8 At[4][2], B0[2][2], B1[2][2];
;     const char* cA = (const char*)g.A + (size_t)cur.pm * tstep; const char* cB = (const char*)g.Bt + (size_t)cur.pn * tstep;
;     S.a_ready(cur);
;     if constexpr (SP2) {
;         PG8_STAGE(PG8_SB(0, 0), cB, voffB); PG8_STAGE(PG8_SB(0, 1), cB + hstep, voffB); PG8_STAGE(PG8_SA(0, 0), cA, voffA); PG8_STAGE(PG8_SA(0, 1), cA + hstep, voffA);
;         if (wr == 1) PG8_BAR;
;         PG8_WAIT_V(2); PG8_BAR;
;         PG8_STAGE(PG8_SB(1, 0), cB + kstep, voffB); PG8_STAGE(PG8_SA(1, 0), cA + kstep, voffA); PG8_STAGE(PG8_SB(1, 1), cB + hstep + kstep, voffB);
;         PG8_WAIT_V(6); PG8_BAR;
;     } else {
;         PG8_STAGE(PG8_SB(0, 0), cB, voffB); PG8_STAGE(PG8_SA(0, 0), cA, voffA); PG8_STAGE(PG8_SB(0, 1), cB + hstep, voffB); PG8_STAGE(PG8_SA(0, 1), cA + hstep, voffA);
;         if (wr == 1) PG8_BAR;
;         PG8_WAIT_V(4); PG8_BAR;
;         PG8_STAGE(PG8_SB(1, 0), cB + kstep, voffB); PG8_STAGE(PG8_SA(1, 0), cA + kstep, voffA); PG8_STAGE(PG8_SB(1, 1), cB + hstep + kstep, voffB);
.LBB0_222:
	s_load_dword s6, s[0:1], 0xe0
	s_and_b64 s[4:5], s[30:31], exec
	s_cselect_b32 s3, 3, 0
	s_lshr_b32 s62, s61, s3
	s_waitcnt lgkmcnt(0)
	s_setprio 0
	s_cmp_lt_i32 s6, 2
	s_cselect_b64 s[4:5], -1, 0
	s_cmp_gt_i32 s7, 1
	s_cselect_b64 s[8:9], -1, 0
	s_and_b64 s[4:5], s[4:5], s[8:9]
	s_andn2_b64 vcc, exec, s[4:5]
	s_cbranch_vccnz .LBB0_385
	s_and_b64 s[4:5], s[30:31], exec
	s_cselect_b32 s8, 8, 1
	v_cvt_f32_ubyte0_e32 v0, s8
	v_rcp_iflag_f32_e32 v0, v0
	v_readfirstlane_b32 s5, v242
	s_cmpk_gt_i32 s2, 0xaff
	v_mul_f32_e32 v0, 0x4f7ffffe, v0
	v_cvt_u32_f32_e32 v0, v0
	s_nop 0
	v_readfirstlane_b32 s4, v0
	s_cbranch_scc1 .LBB0_239
	v_lshrrev_b32_e32 v0, 5, v242
	v_lshrrev_b32_e32 v2, 1, v242
	s_sub_i32 s6, 0, s8
	s_load_dwordx2 s[12:13], s[0:1], 0xd8
	v_and_b32_e32 v0, 4, v0
	v_bfe_u32 v1, v242, 2, 2
	v_and_b32_e32 v11, 24, v2
	s_mul_i32 s6, s6, s4
	v_or3_b32 v0, v0, v1, v11
	v_lshlrev_b32_e32 v1, 4, v242
	s_mul_hi_u32 s6, s4, s6
	v_add_u32_e32 v8, 0x2000, v1
	s_add_i32 s15, s4, s6
	v_lshrrev_b32_e32 v2, 7, v8
	s_movk_i32 s4, 0xe0
	v_and_b32_e32 v4, 32, v242
	s_ashr_i32 s3, s2, 31
	s_abs_i32 s9, s2
	s_lshr_b32 s14, s5, 6
	v_and_or_b32 v3, v2, s4, v0
	v_bitop3_b32 v9, v1, v4, 48 bitop3:0x6c
	v_and_b32_e32 v10, 64, v242
	v_bfe_u32 v12, v242, 2, 4
	s_movk_i32 s4, 0xf0
	s_waitcnt lgkmcnt(0)
	s_add_u32 s44, s12, 0x6000000
	v_or_b32_e32 v1, v9, v10
	v_and_or_b32 v2, v2, s4, v12
	s_addc_u32 s45, s13, 0
	v_lshl_or_b32 v130, v2, 11, v1
	v_lshrrev_b32_e32 v2, 3, v242
	s_movk_i32 s4, 0x60
	s_add_u32 s46, s12, 0x800000
	v_and_or_b32 v0, v2, s4, v0
	s_movk_i32 s4, 0x70
	s_addc_u32 s47, s13, 0
	v_lshl_or_b32 v132, v0, 11, v1
	v_and_or_b32 v0, v2, s4, v12
	s_lshr_b32 s4, s3, 29
	s_add_i32 s4, s2, s4
	s_ashr_i32 s6, s4, 3
	s_and_b32 s4, s4, -8
	s_lshr_b32 s16, s5, 8
	s_lshl_b32 s48, s14, 10
	s_sub_i32 s4, s2, s4
	s_cmp_lt_i32 s4, 0
	s_movk_i32 s49, 0x161
	s_cselect_b32 s7, s49, 0x160
	s_mul_i32 s4, s7, s4
	s_add_i32 s4, s4, s6
	s_mul_hi_i32 s6, s4, 0x2e8ba2e9
	s_lshr_b32 s7, s6, 31
	s_ashr_i32 s6, s6, 5
	s_add_i32 s6, s6, s7
	s_lshl_b32 s7, s6, 3
	s_mulk_i32 s6, 0xb0
	s_sub_i32 s6, s4, s6
	s_sext_i32_i16 s4, s6
	s_bfe_u32 s4, s4, 0x3001c
	s_add_i32 s17, s6, s4
	s_sext_i32_i16 s4, s17
	s_and_b32 s17, s17, 0xfff8
	s_sub_i32 s6, s6, s17
	s_sext_i32_i16 s6, s6
	s_lshr_b32 s4, s4, 3
	s_add_i32 s36, s7, s6
	s_ashr_i32 s37, s36, 31
	s_bfe_i64 s[18:19], s[4:5], 0x100000
	s_lshl_b64 s[6:7], s[36:37], 19
	s_lshl_b64 s[18:19], s[18:19], 19
	s_add_u32 s40, s46, s18
	s_addc_u32 s41, s47, s19
	s_add_i32 s37, s48, 0
	s_add_i32 m0, s37, 0x10000
	v_lshl_or_b32 v128, v3, 11, v1
	global_load_lds_dwordx4 v132, s[40:41]
	s_add_i32 m0, s37, 0x12000
	s_add_u32 s18, s40, 0x40000
	global_load_lds_dwordx4 v128, s[40:41]
	s_addc_u32 s19, s41, 0
	s_add_i32 m0, s37, 0x14000
	v_lshl_or_b32 v134, v0, 11, v1
	global_load_lds_dwordx4 v132, s[18:19]
	s_add_i32 m0, s37, 0x16000
	s_add_u32 s38, s44, s6
	s_addc_u32 s39, s45, s7
	s_add_i32 s50, s37, 0x2000
	global_load_lds_dwordx4 v128, s[18:19]
	s_mov_b32 m0, s37
	s_add_u32 s6, s38, 0x40000
	global_load_lds_dwordx4 v134, s[38:39]
	s_mov_b32 m0, s50
	s_addc_u32 s7, s39, 0
	s_add_i32 s51, s37, 0x4000
	global_load_lds_dwordx4 v130, s[38:39]
	s_mov_b32 m0, s51
	s_add_i32 s52, s37, 0x6000
	global_load_lds_dwordx4 v134, s[6:7]
	s_mov_b32 m0, s52
	v_mov_b32_e32 v133, 0
	global_load_lds_dwordx4 v130, s[6:7]
	v_mov_b32_e32 v129, v133
	v_mov_b32_e32 v135, v133
	v_mov_b32_e32 v131, v133
	s_cmp_eq_u32 s16, 1
	s_mul_hi_u32 s15, s9, s15
	s_mov_b32 s53, 0
	v_lshl_add_u64 v[6:7], s[40:41], 0, v[132:133]
	v_lshl_add_u64 v[4:5], s[40:41], 0, v[128:129]
	v_lshl_add_u64 v[0:1], s[38:39], 0, v[134:135]
	s_cselect_b64 s[6:7], -1, 0
	s_cmp_lg_u32 s16, 1
	v_lshl_add_u64 v[2:3], s[38:39], 0, v[130:131]
	s_cbranch_scc1 .LBB0_226
	s_barrier
.LBB0_226:
	s_mul_i32 s15, s15, s8
	s_sub_i32 s9, s9, s15
	s_sub_i32 s15, s9, s8
	s_cmp_ge_u32 s9, s8
	s_cselect_b32 s9, s15, s9
	s_sub_i32 s15, s9, s8
	s_cmp_ge_u32 s9, s8
	s_cselect_b32 s8, s15, s9
	s_xor_b32 s8, s8, s3
	s_sub_i32 s18, s8, s3
	s_add_u32 s8, s12, 0x500000
	s_addc_u32 s9, s13, 0
	s_ashr_i32 s19, s18, 31
	s_and_b64 s[20:21], s[30:31], exec
	s_cselect_b32 s15, 25, 28
	s_lshl_b64 s[20:21], s[18:19], s15
	s_add_u32 s15, s12, s20
	s_addc_u32 s17, s13, s21
	s_and_b64 s[12:13], s[30:31], exec
	s_cselect_b32 s12, 12, 15
	s_lshl_b64 s[12:13], s[18:19], s12
	s_mul_hi_u32 s18, s12, 0xffffea00
	s_sub_i32 s18, s18, s12
	s_mulk_i32 s13, 0xea00
	s_add_i32 s18, s18, s13
	s_mulk_i32 s12, 0xea00
	s_add_u32 s12, s15, s12
	s_addc_u32 s13, s17, s18
	s_add_u32 s12, s12, 0xa000000
	s_addc_u32 s13, s13, 0
	s_lshl_b32 s14, s14, 5
	s_and_b32 s20, s14, 0x60
	s_mov_b64 s[14:15], 0x80
	s_add_i32 m0, s37, 0x18000
	v_lshl_add_u64 v[6:7], v[6:7], 0, s[14:15]
	s_lshl_b32 s17, s16, 13
	s_lshl_b32 s21, s20, 7
	s_waitcnt vmcnt(2)
	s_barrier
	global_load_lds_dwordx4 v[6:7], off
	v_lshl_add_u64 v[4:5], v[4:5], 0, s[14:15]
	s_add_i32 m0, s37, 0x1a000
	s_add_i32 s54, s37, 0x8000
	s_add_i32 s55, s37, 0xa000
	global_load_lds_dwordx4 v[4:5], off
	v_lshl_add_u64 v[0:1], v[0:1], 0, s[14:15]
	s_mov_b32 m0, s54
	s_add_u32 s18, s40, 0x40080
	global_load_lds_dwordx4 v[0:1], off
	v_lshl_add_u64 v[0:1], v[2:3], 0, s[14:15]
	s_mov_b32 m0, s55
	s_addc_u32 s19, s41, 0
	global_load_lds_dwordx4 v[0:1], off
	s_add_i32 m0, s37, 0x1c000
	v_lshl_add_u64 v[0:1], s[18:19], 0, v[132:133]
	global_load_lds_dwordx4 v[0:1], off
	v_lshl_add_u64 v[0:1], s[18:19], 0, v[128:129]
	s_add_i32 m0, s37, 0x1e000
	s_sext_i32_i16 s63, s4
	global_load_lds_dwordx4 v[0:1], off
	v_and_b32_e32 v0, 15, v242
	v_lshlrev_b32_e32 v1, 1, v11
	v_lshlrev_b32_e32 v2, 2, v242
	v_lshlrev_b32_e32 v3, 6, v242
	s_movk_i32 s4, 0x3c0
	v_lshl_or_b32 v146, s16, 6, v0
	v_lshl_or_b32 v0, v0, 6, v1
	v_and_b32_e32 v2, 32, v2
	v_and_or_b32 v1, v3, s4, v1
	v_bitop3_b32 v147, s21, v1, v2 bitop3:0xf6
	v_lshlrev_b32_e32 v1, 8, v242
	v_bitop3_b32 v0, v0, s17, v2 bitop3:0xde
	v_and_b32_e32 v1, 0x38000, v1
	v_lshlrev_b32_e32 v2, 11, v12
	v_or3_b32 v1, v9, v1, v2
	v_add_u32_e32 v136, v1, v10
	v_lshlrev_b32_e32 v1, 4, v8
	s_waitcnt vmcnt(6)
	s_cmpk_lt_u32 s5, 0x100
	v_and_b32_e32 v1, 0x78000, v1
	s_cselect_b64 s[16:17], -1, 0
	v_or3_b32 v1, v9, v1, v2
	s_add_i32 s57, 0, 0x10000
	s_add_i32 s58, 0, 0x14000
	s_ashr_i32 s56, s61, 31
	v_or_b32_e32 v148, s20, v11
	v_mov_b32_e32 v137, v133
	v_add_u32_e32 v138, v1, v10
	v_mov_b32_e32 v139, v133
	v_mov_b64_e32 v[140:141], 0xb00
	v_mov_b64_e32 v[142:143], 0xaff
	v_add_u32_e32 v149, s57, v147
	v_add_u32_e32 v150, s58, v147
	v_add_u32_e32 v151, 0, v0
	v_mov_b32_e32 v152, 0x358637bd
	s_movk_i32 s59, 0x1600
	s_barrier
	v_readfirstlane_b32 s99, v242
	s_nop 3
	s_cmp_ge_u32 s99, 0x100
	s_cbranch_scc1 .Lprio_skip_0
	s_setprio 1
.Lprio_skip_0:
	s_branch .LBB0_229
.LBB0_227:
	s_mov_b64 s[4:5], 0

; #define PG8_STAGE(bufoff, gbase, voff) do { _Pragma("unroll") for (int _i = 0; _i < 2; ++_i) \
;         __builtin_amdgcn_global_load_lds((const unsigned*)((const char*)(gbase) + (voff)[_i]), (PG8_LAS unsigned*)(lds + (bufoff) + ldsw + _i * 8192), 16, 0, 0); } while (0)
; #define PG8_LDA(dst, b, h) do { _Pragma("unroll") for (int m = 0; m < 4; ++m) _Pragma("unroll") for (int k = 0; k < 2; ++k) dst[m][k] = *(const PG8_LAS bf16x8*)(lds + PG8_SA(b, h) + aoff + m * 2048 + k * 1024); } while (0)
; #define PG8_LDB(dst, b, h) do { _Pragma("unroll") for (int n = 0; n < 2; ++n) _Pragma("unroll") for (int k = 0; k < 2; ++k) dst[n][k] = *(const PG8_LAS bf16x8*)(lds + PG8_SB(b, h) + boff + n * 2048 + k * 1024); } while (0)
; #define PG8_WAIT_V(n) asm volatile("s_waitcnt vmcnt(" #n ")" ::: "memory")
; #define PG8_WAIT_L(n) asm volatile("s_waitcnt lgkmcnt(" #n ")" ::: "memory")
; template <class Epi, class Sched, bool ALIGN_EPI = false, bool SP2 = false>
; __device__ __forceinline__ void gemm_phase(PG8_LAS unsigned char* lds, const Gemm g, const Sched& S, const Epi& E) {
;     ...
;         const bool has_next = S.next(ui + 1, nxt);
;         const char* nA = has_next ? (const char*)g.A + (size_t)nxt.pm * tstep : cA; const char* nB = has_next ? (const char*)g.Bt + (size_t)nxt.pn * tstep : cB;
;         for (int t = 0; t < nt; t += 2) {
;             const bool last = (t == nt - 2);
;             if constexpr (Epi::PREFETCH) { if (t == nt - 4) E.prefetch(cur, lds + STAGE_BYTES + 1024, tid); }
;             const char* a1 = cA + (size_t)(t + 1) * kstep;
;             const char* a2 = last ? nA : cA + (size_t)(t + 2) * kstep; const char* b2 = last ? nB : cB + (size_t)(t + 2) * kstep;
;             const char* a3 = a2 + kstep; const char* b3 = b2 + kstep;
;             if (last && has_next) S.a_ready(nxt);
;             if constexpr (SP2) {
;             PG8_LDB(B0, 0, 0); PG8_LDB(B1, 0, 1); PG8_SCHED; PG8_LDA(At, 0, 0); PG8_STAGE(PG8_SA(1, 1), a1 + hstep, voffA);
;             PG8_WAIT_V(8); PG8_WAIT_L(0); PG8_BAR; PG8_MMA(0, 0, At, B0); PG8_MMA(0, 1, At, B1); PG8_BAR; PG8_SCHED;
;             PG8_LDA(At, 0, 1); PG8_STAGE(PG8_SB(0, 0), b2, voffB); PG8_STAGE(PG8_SB(0, 1), b2 + hstep, voffB); PG8_STAGE(PG8_SA(0, 0), a2, voffA);
;             PG8_WAIT_V(8); PG8_WAIT_L(0); PG8_BAR; PG8_MMA(1, 0, At, B0); PG8_MMA(1, 1, At, B1); PG8_BAR; PG8_SCHED;
.LBB0_231:
	s_ashr_i32 s21, s20, 31
	s_lshl_b64 s[22:23], s[20:21], 19
	s_add_u32 s22, s44, s22
	s_addc_u32 s23, s45, s23
	s_and_b64 s[34:35], s[4:5], exec
	s_cselect_b32 s21, s23, s39
	s_cselect_b32 s64, s22, s38
	s_ashr_i32 s19, s18, 31
	s_lshl_b64 s[34:35], s[18:19], 19
	s_add_u32 s34, s46, s34
	s_addc_u32 s35, s47, s35
	s_and_b64 s[42:43], s[4:5], exec
	s_cselect_b32 s19, s35, s41
	s_cselect_b32 s65, s34, s40
	s_add_u32 s38, s38, 0x40080
	s_addc_u32 s39, s39, 0
	s_add_u32 s66, s40, 0x100
	s_addc_u32 s67, s41, 0
	s_mov_b32 s68, -2
	ds_read_b128 v[154:157], v149
	ds_read_b128 v[158:161], v149 offset:1024
	ds_read_b128 v[162:165], v149 offset:2048
	ds_read_b128 v[166:169], v149 offset:3072
	ds_read_b128 v[170:173], v150
	ds_read_b128 v[174:177], v150 offset:1024
	ds_read_b128 v[178:181], v150 offset:2048
	ds_read_b128 v[182:185], v150 offset:3072
	s_add_u32 s40, s38, 0xfffc0080
	s_addc_u32 s41, s39, -1
	s_cmp_eq_u32 s68, 12
	s_cselect_b32 s43, s21, s41
	s_cselect_b32 s42, s64, s40
	s_cselect_b32 s41, s19, s67
	s_cselect_b32 s40, s65, s66
	v_lshl_add_u64 v[144:145], s[38:39], 0, v[136:137]
	s_add_i32 m0, s37, 0xc000
	ds_read_b128 v[186:189], v151
	ds_read_b128 v[190:193], v151 offset:1024
	ds_read_b128 v[194:197], v151 offset:2048
	ds_read_b128 v[198:201], v151 offset:3072
	ds_read_b128 v[202:205], v151 offset:4096
	ds_read_b128 v[206:209], v151 offset:5120
	ds_read_b128 v[210:213], v151 offset:6144
	ds_read_b128 v[214:217], v151 offset:7168
	global_load_lds_dwordx4 v[144:145], off
	v_lshl_add_u64 v[144:145], s[38:39], 0, v[138:139]
	s_add_i32 m0, s37, 0xe000
	s_nop 0
	global_load_lds_dwordx4 v[144:145], off
	s_waitcnt vmcnt(8)
	s_waitcnt lgkmcnt(0)
	s_barrier
	v_mfma_f32_16x16x32_bf16 v[120:123], v[154:157], v[186:189], 0
	v_mfma_f32_16x16x32_bf16 v[116:119], v[162:165], v[186:189], 0
	v_mfma_f32_16x16x32_bf16 v[108:111], v[154:157], v[194:197], 0
	v_mfma_f32_16x16x32_bf16 v[100:103], v[162:165], v[194:197], 0
	v_mfma_f32_16x16x32_bf16 v[92:95], v[154:157], v[202:205], 0
	v_mfma_f32_16x16x32_bf16 v[84:87], v[162:165], v[202:205], 0
	v_mfma_f32_16x16x32_bf16 v[76:79], v[154:157], v[210:213], 0
	v_mfma_f32_16x16x32_bf16 v[68:71], v[162:165], v[210:213], 0
	v_mfma_f32_16x16x32_bf16 v[120:123], v[158:161], v[190:193], v[120:123]
	v_mfma_f32_16x16x32_bf16 v[116:119], v[166:169], v[190:193], v[116:119]
	v_mfma_f32_16x16x32_bf16 v[108:111], v[158:161], v[198:201], v[108:111]
	v_mfma_f32_16x16x32_bf16 v[100:103], v[166:169], v[198:201], v[100:103]
	v_mfma_f32_16x16x32_bf16 v[92:95], v[158:161], v[206:209], v[92:95]
	v_mfma_f32_16x16x32_bf16 v[84:87], v[166:169], v[206:209], v[84:87]
	v_mfma_f32_16x16x32_bf16 v[76:79], v[158:161], v[214:217], v[76:79]
	v_mfma_f32_16x16x32_bf16 v[68:71], v[166:169], v[214:217], v[68:71]
	v_mfma_f32_16x16x32_bf16 v[124:127], v[170:173], v[186:189], 0
	v_mfma_f32_16x16x32_bf16 v[112:115], v[178:181], v[186:189], 0
	v_mfma_f32_16x16x32_bf16 v[104:107], v[170:173], v[194:197], 0
	v_mfma_f32_16x16x32_bf16 v[96:99], v[178:181], v[194:197], 0
	v_mfma_f32_16x16x32_bf16 v[88:91], v[170:173], v[202:205], 0
	v_mfma_f32_16x16x32_bf16 v[80:83], v[178:181], v[202:205], 0
	v_mfma_f32_16x16x32_bf16 v[72:75], v[170:173], v[210:213], 0
	v_mfma_f32_16x16x32_bf16 v[64:67], v[178:181], v[210:213], 0
	v_mfma_f32_16x16x32_bf16 v[124:127], v[174:177], v[190:193], v[124:127]
	v_mfma_f32_16x16x32_bf16 v[112:115], v[182:185], v[190:193], v[112:115]
	v_mfma_f32_16x16x32_bf16 v[104:107], v[174:177], v[198:201], v[104:107]
	v_mfma_f32_16x16x32_bf16 v[96:99], v[182:185], v[198:201], v[96:99]
	v_mfma_f32_16x16x32_bf16 v[88:91], v[174:177], v[206:209], v[88:91]
	v_mfma_f32_16x16x32_bf16 v[80:83], v[182:185], v[206:209], v[80:83]
	v_mfma_f32_16x16x32_bf16 v[72:75], v[174:177], v[214:217], v[72:75]
	v_mfma_f32_16x16x32_bf16 v[64:67], v[182:185], v[214:217], v[64:67]
	s_barrier
	s_add_i32 s69, s57, s48
	v_lshl_add_u64 v[144:145], s[40:41], 0, v[132:133]
	s_mov_b32 m0, s69
	ds_read_b128 v[186:189], v151 offset:16384
	ds_read_b128 v[190:193], v151 offset:17408
	ds_read_b128 v[194:197], v151 offset:18432
	ds_read_b128 v[198:201], v151 offset:19456
	ds_read_b128 v[202:205], v151 offset:20480
	ds_read_b128 v[206:209], v151 offset:21504
	ds_read_b128 v[210:213], v151 offset:22528
	ds_read_b128 v[214:217], v151 offset:23552
	global_load_lds_dwordx4 v[144:145], off
	s_add_i32 m0, s69, 0x2000
	s_add_u32 s70, s40, 0x40000
	v_lshl_add_u64 v[218:219], s[40:41], 0, v[128:129]
	s_addc_u32 s71, s41, 0
	s_add_i32 s69, s58, s48
	global_load_lds_dwordx4 v[218:219], off
	v_lshl_add_u64 v[220:221], s[70:71], 0, v[132:133]
	s_mov_b32 m0, s69
	v_lshl_add_u64 v[222:223], s[42:43], 0, v[130:131]
	global_load_lds_dwordx4 v[220:221], off
	v_lshl_add_u64 v[220:221], s[70:71], 0, v[128:129]
	s_add_i32 m0, s69, 0x2000
	s_nop 0
	global_load_lds_dwordx4 v[220:221], off
	v_lshl_add_u64 v[220:221], s[42:43], 0, v[134:135]
	s_mov_b32 m0, s37
	s_nop 0
	global_load_lds_dwordx4 v[220:221], off
	s_mov_b32 m0, s50
	s_nop 0
	global_load_lds_dwordx4 v[222:223], off
	s_waitcnt vmcnt(8)
	s_waitcnt lgkmcnt(0)
	s_barrier
; #define PG8_STAGE(bufoff, gbase, voff) do { _Pragma("unroll") for (int _i = 0; _i < 2; ++_i) \
;         __builtin_amdgcn_global_load_lds((const unsigned*)((const char*)(gbase) + (voff)[_i]), (PG8_LAS unsigned*)(lds + (bufoff) + ldsw + _i * 8192), 16, 0, 0); } while (0)
; #define PG8_LDA(dst, b, h) do { _Pragma("unroll") for (int m = 0; m < 4; ++m) _Pragma("unroll") for (int k = 0; k < 2; ++k) dst[m][k] = *(const PG8_LAS bf16x8*)(lds + PG8_SA(b, h) + aoff + m * 2048 + k * 1024); } while (0)
; #define PG8_LDB(dst, b, h) do { _Pragma("unroll") for (int n = 0; n < 2; ++n) _Pragma("unroll") for (int k = 0; k < 2; ++k) dst[n][k] = *(const PG8_LAS bf16x8*)(lds + PG8_SB(b, h) + boff + n * 2048 + k * 1024); } while (0)
; #define PG8_MMA(ai, bj, At, Bt) do { __builtin_amdgcn_s_setprio(1); _Pragma("unroll") for (int m = 0; m < 4; ++m) _Pragma("unroll") for (int n = 0; n < 2; ++n) _Pragma("unroll") for (int k = 0; k < 2; ++k) \
;         acc[ai][bj][m][n] = __builtin_amdgcn_mfma_f32_16x16x32_bf16(Bt[n][k], At[m][k], acc[ai][bj][m][n], 0, 0, 0); __builtin_amdgcn_s_setprio(0); } while (0)
; #define PG8_WAIT_V(n) asm volatile("s_waitcnt vmcnt(" #n ")" ::: "memory")
; #define PG8_WAIT_L(n) asm volatile("s_waitcnt lgkmcnt(" #n ")" ::: "memory")
; #define PG8_BAR __builtin_amdgcn_s_barrier()
; #define PG8_SCHED __builtin_amdgcn_sched_barrier(0)
; template <class Epi, class Sched, bool ALIGN_EPI = false, bool SP2 = false>
; __device__ __forceinline__ void gemm_phase(PG8_LAS unsigned char* lds, const Gemm g, const Sched& S, const Epi& E) {
;     ...
;             PG8_WAIT_V(8); PG8_WAIT_L(0); PG8_BAR; PG8_MMA(1, 0, At, B0); PG8_MMA(1, 1, At, B1); PG8_BAR; PG8_SCHED;
;             PG8_LDB(B0, 1, 0); PG8_LDB(B1, 1, 1); PG8_SCHED; PG8_LDA(At, 1, 0); PG8_STAGE(PG8_SA(0, 1), a2 + hstep, voffA);
;             PG8_WAIT_V(8); PG8_WAIT_L(0); PG8_BAR; PG8_MMA(0, 0, At, B0); PG8_MMA(0, 1, At, B1); PG8_BAR; PG8_SCHED;
	v_mfma_f32_16x16x32_bf16 v[60:63], v[154:157], v[186:189], 0
	v_mfma_f32_16x16x32_bf16 v[52:55], v[162:165], v[186:189], 0
	v_mfma_f32_16x16x32_bf16 v[44:47], v[154:157], v[194:197], 0
	v_mfma_f32_16x16x32_bf16 v[36:39], v[162:165], v[194:197], 0
	v_mfma_f32_16x16x32_bf16 v[28:31], v[154:157], v[202:205], 0
	v_mfma_f32_16x16x32_bf16 v[20:23], v[162:165], v[202:205], 0
	v_mfma_f32_16x16x32_bf16 v[12:15], v[154:157], v[210:213], 0
	v_mfma_f32_16x16x32_bf16 v[4:7], v[162:165], v[210:213], 0
	v_mfma_f32_16x16x32_bf16 v[60:63], v[158:161], v[190:193], v[60:63]
	v_mfma_f32_16x16x32_bf16 v[52:55], v[166:169], v[190:193], v[52:55]
	v_mfma_f32_16x16x32_bf16 v[44:47], v[158:161], v[198:201], v[44:47]
	v_mfma_f32_16x16x32_bf16 v[36:39], v[166:169], v[198:201], v[36:39]
	v_mfma_f32_16x16x32_bf16 v[28:31], v[158:161], v[206:209], v[28:31]
	v_mfma_f32_16x16x32_bf16 v[20:23], v[166:169], v[206:209], v[20:23]
	v_mfma_f32_16x16x32_bf16 v[12:15], v[158:161], v[214:217], v[12:15]
	v_mfma_f32_16x16x32_bf16 v[4:7], v[166:169], v[214:217], v[4:7]
	v_mfma_f32_16x16x32_bf16 v[56:59], v[170:173], v[186:189], 0
	v_mfma_f32_16x16x32_bf16 v[48:51], v[178:181], v[186:189], 0
	v_mfma_f32_16x16x32_bf16 v[40:43], v[170:173], v[194:197], 0
	v_mfma_f32_16x16x32_bf16 v[32:35], v[178:181], v[194:197], 0
	v_mfma_f32_16x16x32_bf16 v[24:27], v[170:173], v[202:205], 0
	v_mfma_f32_16x16x32_bf16 v[16:19], v[178:181], v[202:205], 0
	v_mfma_f32_16x16x32_bf16 v[8:11], v[170:173], v[210:213], 0
	v_mfma_f32_16x16x32_bf16 v[0:3], v[178:181], v[210:213], 0
	v_mfma_f32_16x16x32_bf16 v[56:59], v[174:177], v[190:193], v[56:59]
	v_mfma_f32_16x16x32_bf16 v[48:51], v[182:185], v[190:193], v[48:51]
	v_mfma_f32_16x16x32_bf16 v[40:43], v[174:177], v[198:201], v[40:43]
	v_mfma_f32_16x16x32_bf16 v[32:35], v[182:185], v[198:201], v[32:35]
	v_mfma_f32_16x16x32_bf16 v[24:27], v[174:177], v[206:209], v[24:27]
	v_mfma_f32_16x16x32_bf16 v[16:19], v[182:185], v[206:209], v[16:19]
	v_mfma_f32_16x16x32_bf16 v[8:11], v[174:177], v[214:217], v[8:11]
	v_mfma_f32_16x16x32_bf16 v[0:3], v[182:185], v[214:217], v[0:3]
	s_barrier
	s_add_i32 s69, 0, 0x18000
	v_add_u32_e32 v153, s69, v147
	s_add_i32 s70, 0, 0x1c000
	ds_read_b128 v[154:157], v153
	ds_read_b128 v[158:161], v153 offset:1024
	ds_read_b128 v[162:165], v153 offset:2048
	ds_read_b128 v[166:169], v153 offset:3072
	v_add_u32_e32 v153, s70, v147
	ds_read_b128 v[170:173], v153
	ds_read_b128 v[174:177], v153 offset:1024
	ds_read_b128 v[178:181], v153 offset:2048
	ds_read_b128 v[182:185], v153 offset:3072
	s_add_u32 s42, s42, 0x40000
	s_addc_u32 s43, s43, 0
	s_mov_b32 m0, s51
	v_lshl_add_u64 v[224:225], s[42:43], 0, v[134:135]
	ds_read_b128 v[186:189], v151 offset:32768
	ds_read_b128 v[190:193], v151 offset:33792
	ds_read_b128 v[194:197], v151 offset:34816
	ds_read_b128 v[198:201], v151 offset:35840
	ds_read_b128 v[202:205], v151 offset:36864
	ds_read_b128 v[206:209], v151 offset:37888
	ds_read_b128 v[210:213], v151 offset:38912
	ds_read_b128 v[214:217], v151 offset:39936
	global_load_lds_dwordx4 v[224:225], off
	v_lshl_add_u64 v[224:225], s[42:43], 0, v[130:131]
	s_mov_b32 m0, s52
	s_nop 0
	global_load_lds_dwordx4 v[224:225], off
	s_waitcnt vmcnt(8)
	s_waitcnt lgkmcnt(0)
	s_barrier
	v_mfma_f32_16x16x32_bf16 v[120:123], v[154:157], v[186:189], v[120:123]
	v_mfma_f32_16x16x32_bf16 v[116:119], v[162:165], v[186:189], v[116:119]
	v_mfma_f32_16x16x32_bf16 v[108:111], v[154:157], v[194:197], v[108:111]
	v_mfma_f32_16x16x32_bf16 v[100:103], v[162:165], v[194:197], v[100:103]
	v_mfma_f32_16x16x32_bf16 v[92:95], v[154:157], v[202:205], v[92:95]
	v_mfma_f32_16x16x32_bf16 v[84:87], v[162:165], v[202:205], v[84:87]
	v_mfma_f32_16x16x32_bf16 v[76:79], v[154:157], v[210:213], v[76:79]
	v_mfma_f32_16x16x32_bf16 v[68:71], v[162:165], v[210:213], v[68:71]
	v_mfma_f32_16x16x32_bf16 v[120:123], v[158:161], v[190:193], v[120:123]
	v_mfma_f32_16x16x32_bf16 v[116:119], v[166:169], v[190:193], v[116:119]
	v_mfma_f32_16x16x32_bf16 v[108:111], v[158:161], v[198:201], v[108:111]
	v_mfma_f32_16x16x32_bf16 v[100:103], v[166:169], v[198:201], v[100:103]
	v_mfma_f32_16x16x32_bf16 v[92:95], v[158:161], v[206:209], v[92:95]
	v_mfma_f32_16x16x32_bf16 v[84:87], v[166:169], v[206:209], v[84:87]
	v_mfma_f32_16x16x32_bf16 v[76:79], v[158:161], v[214:217], v[76:79]
	v_mfma_f32_16x16x32_bf16 v[68:71], v[166:169], v[214:217], v[68:71]
	v_mfma_f32_16x16x32_bf16 v[124:127], v[170:173], v[186:189], v[124:127]
	v_mfma_f32_16x16x32_bf16 v[112:115], v[178:181], v[186:189], v[112:115]
	v_mfma_f32_16x16x32_bf16 v[104:107], v[170:173], v[194:197], v[104:107]
	v_mfma_f32_16x16x32_bf16 v[96:99], v[178:181], v[194:197], v[96:99]
	v_mfma_f32_16x16x32_bf16 v[88:91], v[170:173], v[202:205], v[88:91]
	v_mfma_f32_16x16x32_bf16 v[80:83], v[178:181], v[202:205], v[80:83]
	v_mfma_f32_16x16x32_bf16 v[72:75], v[170:173], v[210:213], v[72:75]
	v_mfma_f32_16x16x32_bf16 v[64:67], v[178:181], v[210:213], v[64:67]
	v_mfma_f32_16x16x32_bf16 v[124:127], v[174:177], v[190:193], v[124:127]
	v_mfma_f32_16x16x32_bf16 v[112:115], v[182:185], v[190:193], v[112:115]
	v_mfma_f32_16x16x32_bf16 v[104:107], v[174:177], v[198:201], v[104:107]
	v_mfma_f32_16x16x32_bf16 v[96:99], v[182:185], v[198:201], v[96:99]
	v_mfma_f32_16x16x32_bf16 v[88:91], v[174:177], v[206:209], v[88:91]
	v_mfma_f32_16x16x32_bf16 v[80:83], v[182:185], v[206:209], v[80:83]
	v_mfma_f32_16x16x32_bf16 v[72:75], v[174:177], v[214:217], v[72:75]
	v_mfma_f32_16x16x32_bf16 v[64:67], v[182:185], v[214:217], v[64:67]
	s_barrier
; #define PG8_STAGE(bufoff, gbase, voff) do { _Pragma("unroll") for (int _i = 0; _i < 2; ++_i) \
;         __builtin_amdgcn_global_load_lds((const unsigned*)((const char*)(gbase) + (voff)[_i]), (PG8_LAS unsigned*)(lds + (bufoff) + ldsw + _i * 8192), 16, 0, 0); } while (0)
; #define PG8_LDA(dst, b, h) do { _Pragma("unroll") for (int m = 0; m < 4; ++m) _Pragma("unroll") for (int k = 0; k < 2; ++k) dst[m][k] = *(const PG8_LAS bf16x8*)(lds + PG8_SA(b, h) + aoff + m * 2048 + k * 1024); } while (0)
; #define PG8_MMA(ai, bj, At, Bt) do { __builtin_amdgcn_s_setprio(1); _Pragma("unroll") for (int m = 0; m < 4; ++m) _Pragma("unroll") for (int n = 0; n < 2; ++n) _Pragma("unroll") for (int k = 0; k < 2; ++k) \
;         acc[ai][bj][m][n] = __builtin_amdgcn_mfma_f32_16x16x32_bf16(Bt[n][k], At[m][k], acc[ai][bj][m][n], 0, 0, 0); __builtin_amdgcn_s_setprio(0); } while (0)
; #define PG8_WAIT_V(n) asm volatile("s_waitcnt vmcnt(" #n ")" ::: "memory")
; #define PG8_WAIT_L(n) asm volatile("s_waitcnt lgkmcnt(" #n ")" ::: "memory")
; #define PG8_BAR __builtin_amdgcn_s_barrier()
; #define PG8_SCHED __builtin_amdgcn_sched_barrier(0)
; template <class Epi, class Sched, bool ALIGN_EPI = false, bool SP2 = false>
; __device__ __forceinline__ void gemm_phase(PG8_LAS unsigned char* lds, const Gemm g, const Sched& S, const Epi& E) {
;     ...
;             PG8_LDA(At, 1, 1); PG8_STAGE(PG8_SB(1, 0), b3, voffB); PG8_STAGE(PG8_SB(1, 1), b3 + hstep, voffB); PG8_STAGE(PG8_SA(1, 0), a3, voffA);
;             PG8_WAIT_V(8); PG8_WAIT_L(0); PG8_BAR; PG8_MMA(1, 0, At, B0); PG8_MMA(1, 1, At, B1); PG8_BAR; PG8_SCHED;
	s_add_i32 s42, s69, s48
	v_lshl_add_u64 v[144:145], v[144:145], 0, s[14:15]
	s_mov_b32 m0, s42
	ds_read_b128 v[186:189], v151 offset:49152
	ds_read_b128 v[190:193], v151 offset:50176
	ds_read_b128 v[194:197], v151 offset:51200
	ds_read_b128 v[198:201], v151 offset:52224
	ds_read_b128 v[202:205], v151 offset:53248
	ds_read_b128 v[206:209], v151 offset:54272
	ds_read_b128 v[210:213], v151 offset:55296
	ds_read_b128 v[214:217], v151 offset:56320
	global_load_lds_dwordx4 v[144:145], off
	s_add_i32 m0, s42, 0x2000
	s_add_u32 s40, s40, 0x40080
	v_lshl_add_u64 v[144:145], v[218:219], 0, s[14:15]
	s_addc_u32 s41, s41, 0
	s_add_i32 s42, s70, s48
	global_load_lds_dwordx4 v[144:145], off
	v_lshl_add_u64 v[144:145], s[40:41], 0, v[132:133]
	s_mov_b32 m0, s42
	s_nop 0
	global_load_lds_dwordx4 v[144:145], off
	v_lshl_add_u64 v[144:145], s[40:41], 0, v[128:129]
	s_add_i32 m0, s42, 0x2000
	s_nop 0
	global_load_lds_dwordx4 v[144:145], off
	v_lshl_add_u64 v[144:145], v[220:221], 0, s[14:15]
	s_mov_b32 m0, s54
	s_nop 0
	global_load_lds_dwordx4 v[144:145], off
	v_lshl_add_u64 v[144:145], v[222:223], 0, s[14:15]
	s_mov_b32 m0, s55
	s_nop 0
	global_load_lds_dwordx4 v[144:145], off
	s_waitcnt vmcnt(8)
	s_waitcnt lgkmcnt(0)
	s_barrier
	v_mfma_f32_16x16x32_bf16 v[60:63], v[154:157], v[186:189], v[60:63]
	v_mfma_f32_16x16x32_bf16 v[52:55], v[162:165], v[186:189], v[52:55]
	v_mfma_f32_16x16x32_bf16 v[44:47], v[154:157], v[194:197], v[44:47]
	v_mfma_f32_16x16x32_bf16 v[36:39], v[162:165], v[194:197], v[36:39]
	v_mfma_f32_16x16x32_bf16 v[28:31], v[154:157], v[202:205], v[28:31]
	v_mfma_f32_16x16x32_bf16 v[20:23], v[162:165], v[202:205], v[20:23]
	v_mfma_f32_16x16x32_bf16 v[12:15], v[154:157], v[210:213], v[12:15]
	v_mfma_f32_16x16x32_bf16 v[4:7], v[162:165], v[210:213], v[4:7]
	v_mfma_f32_16x16x32_bf16 v[60:63], v[158:161], v[190:193], v[60:63]
	v_mfma_f32_16x16x32_bf16 v[52:55], v[166:169], v[190:193], v[52:55]
	v_mfma_f32_16x16x32_bf16 v[44:47], v[158:161], v[198:201], v[44:47]
	v_mfma_f32_16x16x32_bf16 v[36:39], v[166:169], v[198:201], v[36:39]
	v_mfma_f32_16x16x32_bf16 v[28:31], v[158:161], v[206:209], v[28:31]
	v_mfma_f32_16x16x32_bf16 v[20:23], v[166:169], v[206:209], v[20:23]
	v_mfma_f32_16x16x32_bf16 v[12:15], v[158:161], v[214:217], v[12:15]
	v_mfma_f32_16x16x32_bf16 v[4:7], v[166:169], v[214:217], v[4:7]
	v_mfma_f32_16x16x32_bf16 v[56:59], v[170:173], v[186:189], v[56:59]
	v_mfma_f32_16x16x32_bf16 v[48:51], v[178:181], v[186:189], v[48:51]
	v_mfma_f32_16x16x32_bf16 v[40:43], v[170:173], v[194:197], v[40:43]
	v_mfma_f32_16x16x32_bf16 v[32:35], v[178:181], v[194:197], v[32:35]
	v_mfma_f32_16x16x32_bf16 v[24:27], v[170:173], v[202:205], v[24:27]
	v_mfma_f32_16x16x32_bf16 v[16:19], v[178:181], v[202:205], v[16:19]
	v_mfma_f32_16x16x32_bf16 v[8:11], v[170:173], v[210:213], v[8:11]
	v_mfma_f32_16x16x32_bf16 v[0:3], v[178:181], v[210:213], v[0:3]
	v_mfma_f32_16x16x32_bf16 v[56:59], v[174:177], v[190:193], v[56:59]
	v_mfma_f32_16x16x32_bf16 v[48:51], v[182:185], v[190:193], v[48:51]
	v_mfma_f32_16x16x32_bf16 v[40:43], v[174:177], v[198:201], v[40:43]
	v_mfma_f32_16x16x32_bf16 v[32:35], v[182:185], v[198:201], v[32:35]
	v_mfma_f32_16x16x32_bf16 v[24:27], v[174:177], v[206:209], v[24:27]
	v_mfma_f32_16x16x32_bf16 v[16:19], v[182:185], v[206:209], v[16:19]
	v_mfma_f32_16x16x32_bf16 v[8:11], v[174:177], v[214:217], v[8:11]
	v_mfma_f32_16x16x32_bf16 v[0:3], v[182:185], v[214:217], v[0:3]
	s_barrier
	s_add_i32 s68, s68, 2
	s_add_u32 s38, s38, 0x100
	s_addc_u32 s39, s39, 0
	s_add_u32 s66, s66, 0x100
	s_addc_u32 s67, s67, 0

; #define LAS __attribute__((address_space(3)))
; __device__ __forceinline__ void run_phase(const int ph, const Args& a, LAS unsigned char* lds, unsigned char* ldsg, const bool dummy = false) {
;     const int tid = threadIdx.x, lane = tid & 63, wave = __builtin_amdgcn_readfirstlane(tid >> 6);
;     const int G = gridDim.x, bx = blockIdx.x;
;     const int gw = bx * 8 + wave, NGW = G * 8;
;     const int ngrp = (G == 256) ? 8 : 1, gsize = G / ngrp, gx = bx % ngrp, gj = bx / ngrp;
;     unsigned char* ws = a.ws;
;     pg8::rss_t* RS = (pg8::rss_t*)(ws + WS_ROWSS);
;     bf16* HB = (bf16*)(ws + WS_HB);
;     const size_t rpg = (size_t)(M / ngrp), RPG = (256 * MiB) / ngrp;
;     unsigned char* reg = ws + WS_ACT + (size_t)gx * RPG;
;     bf16* ACT = (bf16*)(reg - (size_t)gx * rpg * FF * 2);
;     bf16* QX = (bf16*)(reg - (size_t)gx * rpg * D * 2); bf16* KX = QX + rpg * D; bf16* VX = QX + 2 * rpg * D; bf16* OB = QX + 3 * rpg * D;
.LBB0_385:
	s_waitcnt lgkmcnt(0)
	s_setprio 0
	s_cmp_lt_i32 s6, 3
	s_cselect_b64 s[4:5], -1, 0
	s_cmp_gt_i32 s7, 2
	s_cselect_b64 s[8:9], -1, 0
	s_and_b64 s[4:5], s[4:5], s[8:9]
	s_andn2_b64 vcc, exec, s[4:5]
	s_cbranch_vccnz .LBB0_578
	s_and_b64 s[4:5], s[30:31], exec
	s_cselect_b32 s14, 8, 1
	v_cvt_f32_ubyte0_e32 v0, s14
	v_rcp_iflag_f32_e32 v0, v0
	s_sub_i32 s8, 0, s14
	s_load_dwordx2 s[4:5], s[0:1], 0xd8
	s_ashr_i32 s3, s2, 31
	v_mul_f32_e32 v0, 0x4f7ffffe, v0
	v_cvt_u32_f32_e32 v0, v0
	s_abs_i32 s15, s2
	v_readfirstlane_b32 s20, v242
	v_readfirstlane_b32 s9, v0
	s_mul_i32 s8, s8, s9
	s_mul_hi_u32 s8, s9, s8
	s_add_i32 s12, s9, s8
	s_cmpk_lt_i32 s2, 0x200
	s_cselect_b64 s[8:9], -1, 0
	s_cmpk_gt_i32 s2, 0x1ff
	s_mul_hi_u32 s16, s15, s12
	s_cbranch_scc1 .LBB0_389
	s_lshr_b32 s12, s3, 29
	s_add_i32 s17, s2, s12
	s_and_b32 s12, s17, -8
	s_sub_i32 s18, s2, s12
	s_cmp_gt_i32 s18, -1
	s_cbranch_scc0 .LBB0_429
	s_lshl_b32 s19, s18, 6
	s_cbranch_execz .LBB0_430
	s_branch .LBB0_431

; #define PG8_STAGE(bufoff, gbase, voff) do { _Pragma("unroll") for (int _i = 0; _i < 2; ++_i) \
;         __builtin_amdgcn_global_load_lds((const unsigned*)((const char*)(gbase) + (voff)[_i]), (PG8_LAS unsigned*)(lds + (bufoff) + ldsw + _i * 8192), 16, 0, 0); } while (0)
; #define PG8_WAIT_V(n) asm volatile("s_waitcnt vmcnt(" #n ")" ::: "memory")
; #define PG8_BAR __builtin_amdgcn_s_barrier()
; template <class Epi, class Sched, bool ALIGN_EPI = false, bool SP2 = false>
; __device__ __forceinline__ void gemm_phase(PG8_LAS unsigned char* lds, const Gemm g, const Sched& S, const Epi& E) {
;     ...
;         if (wr == 1) PG8_BAR;
;         PG8_WAIT_V(4); PG8_BAR;
;         PG8_STAGE(PG8_SB(1, 0), cB + kstep, voffB); PG8_STAGE(PG8_SA(1, 0), cA + kstep, voffA); PG8_STAGE(PG8_SB(1, 1), cB + hstep + kstep, voffB);
;         PG8_WAIT_V(6); PG8_BAR;
;     }
.LBB0_392:
	s_add_u32 s14, s4, 0x6000000
	s_addc_u32 s15, s5, 0
	s_add_u32 s16, s4, 0x540000
	s_addc_u32 s17, s5, 0
	s_lshl_b32 s4, s7, 5
	s_mov_b64 s[18:19], 0x80
	s_and_b32 s7, s4, 0x60
	s_add_i32 m0, s45, 0x18000
	v_lshl_add_u64 v[6:7], v[6:7], 0, s[18:19]
	s_lshl_b32 s8, s6, 13
	s_lshl_b32 s9, s7, 7
	s_waitcnt vmcnt(2)
	s_barrier
	global_load_lds_dwordx4 v[6:7], off
	v_lshl_add_u64 v[4:5], v[4:5], 0, s[18:19]
	s_add_i32 m0, s45, 0x1a000
	s_add_i32 s50, s45, 0x8000
	s_add_i32 s51, s45, 0xa000
	global_load_lds_dwordx4 v[4:5], off
	v_lshl_add_u64 v[0:1], v[0:1], 0, s[18:19]
	s_mov_b32 m0, s50
	s_add_u32 s4, s36, 0xb0080
	global_load_lds_dwordx4 v[0:1], off
	v_lshl_add_u64 v[0:1], v[2:3], 0, s[18:19]
	s_mov_b32 m0, s51
	s_addc_u32 s5, s37, 0
	global_load_lds_dwordx4 v[0:1], off
	s_add_i32 m0, s45, 0x1c000
	v_lshl_add_u64 v[0:1], s[4:5], 0, v[194:195]
	global_load_lds_dwordx4 v[0:1], off
	v_lshl_add_u64 v[0:1], s[4:5], 0, v[198:199]
	s_add_i32 m0, s45, 0x1e000
	v_lshlrev_b32_e32 v4, 6, v242
	global_load_lds_dwordx4 v[0:1], off
	v_bfe_u32 v0, v242, 4, 2
	v_and_b32_e32 v1, 15, v242
	v_lshlrev_b32_e32 v2, 4, v0
	s_movk_i32 s4, 0x3c0
	v_lshl_or_b32 v243, s6, 6, v1
	v_lshl_or_b32 v1, v1, 6, v2
	v_lshlrev_b32_e32 v3, 2, v242
	v_and_or_b32 v2, v4, s4, v2
	v_cmp_eq_u32_e64 s[4:5], 0, v0
	v_lshl_or_b32 v245, v0, 3, s7
	v_add_u16_e32 v0, v8, v9
	v_and_b32_e32 v3, 32, v3
	s_waitcnt vmcnt(6)
	s_cmpk_lt_u32 s20, 0x100
	v_lshrrev_b16_e32 v0, 1, v0
	v_bitop3_b32 v1, v1, s8, v3 bitop3:0xde
	v_bitop3_b32 v244, s9, v2, v3 bitop3:0xf6
	s_cselect_b64 s[20:21], -1, 0
	v_add_lshl_u32 v200, v10, v0, 1
	v_add_lshl_u32 v202, v11, v0, 1
	s_add_i32 s53, 0, 0x10000
	s_add_i32 s54, 0, 0x14000
	v_mbcnt_lo_u32_b32 v0, -1, 0
	s_ashr_i32 s52, s61, 31
	v_mov_b32_e32 v201, v195
	v_mov_b32_e32 v203, v195
	v_mov_b64_e32 v[204:205], 0x1ff
	v_add_u32_e32 v246, s53, v244
	v_add_u32_e32 v247, s54, v244
	v_add_u32_e32 v248, 0, v1
	v_mbcnt_hi_u32_b32 v249, -1, v0
	s_barrier
	v_readfirstlane_b32 s99, v242
	s_nop 3
	s_cmp_ge_u32 s99, 0x100
	s_cbranch_scc1 .Lprio_skip_1
	s_setprio 1
.Lprio_skip_1:
	s_branch .LBB0_395
.LBB0_393:
	s_mov_b64 s[6:7], 0

; #define PG8_STAGE(bufoff, gbase, voff) do { _Pragma("unroll") for (int _i = 0; _i < 2; ++_i) \
;         __builtin_amdgcn_global_load_lds((const unsigned*)((const char*)(gbase) + (voff)[_i]), (PG8_LAS unsigned*)(lds + (bufoff) + ldsw + _i * 8192), 16, 0, 0); } while (0)
; #define PG8_LDA(dst, b, h) do { _Pragma("unroll") for (int m = 0; m < 4; ++m) _Pragma("unroll") for (int k = 0; k < 2; ++k) dst[m][k] = *(const PG8_LAS bf16x8*)(lds + PG8_SA(b, h) + aoff + m * 2048 + k * 1024); } while (0)
; #define PG8_LDB(dst, b, h) do { _Pragma("unroll") for (int n = 0; n < 2; ++n) _Pragma("unroll") for (int k = 0; k < 2; ++k) dst[n][k] = *(const PG8_LAS bf16x8*)(lds + PG8_SB(b, h) + boff + n * 2048 + k * 1024); } while (0)
; #define PG8_WAIT_V(n) asm volatile("s_waitcnt vmcnt(" #n ")" ::: "memory")
; #define PG8_WAIT_L(n) asm volatile("s_waitcnt lgkmcnt(" #n ")" ::: "memory")
; template <class Epi, class Sched, bool ALIGN_EPI = false, bool SP2 = false>
; __device__ __forceinline__ void gemm_phase(PG8_LAS unsigned char* lds, const Gemm g, const Sched& S, const Epi& E) {
;     ...
;         const bool has_next = S.next(ui + 1, nxt);
;         const char* nA = has_next ? (const char*)g.A + (size_t)nxt.pm * tstep : cA; const char* nB = has_next ? (const char*)g.Bt + (size_t)nxt.pn * tstep : cB;
;         for (int t = 0; t < nt; t += 2) {
;             const bool last = (t == nt - 2);
;             if constexpr (Epi::PREFETCH) { if (t == nt - 4) E.prefetch(cur, lds + STAGE_BYTES + 1024, tid); }
;             const char* a1 = cA + (size_t)(t + 1) * kstep;
;             const char* a2 = last ? nA : cA + (size_t)(t + 2) * kstep; const char* b2 = last ? nB : cB + (size_t)(t + 2) * kstep;
;             const char* a3 = a2 + kstep; const char* b3 = b2 + kstep;
;             if (last && has_next) S.a_ready(nxt);
;             if constexpr (SP2) {
;             PG8_LDB(B0, 0, 0); PG8_LDB(B1, 0, 1); PG8_SCHED; PG8_LDA(At, 0, 0); PG8_STAGE(PG8_SA(1, 1), a1 + hstep, voffA);
;             PG8_WAIT_V(8); PG8_WAIT_L(0); PG8_BAR; PG8_MMA(0, 0, At, B0); PG8_MMA(0, 1, At, B1); PG8_BAR; PG8_SCHED;
;             PG8_LDA(At, 0, 1); PG8_STAGE(PG8_SB(0, 0), b2, voffB); PG8_STAGE(PG8_SB(0, 1), b2 + hstep, voffB); PG8_STAGE(PG8_SA(0, 0), a2, voffA);
;             PG8_WAIT_V(8); PG8_WAIT_L(0); PG8_BAR; PG8_MMA(1, 0, At, B0); PG8_MMA(1, 1, At, B1); PG8_BAR; PG8_SCHED;
.LBB0_405:
	s_add_u32 s34, s34, 0xb0080
	s_addc_u32 s35, s35, 0
	s_add_u32 s59, s36, 0x100
	s_addc_u32 s63, s37, 0
	s_mov_b32 s64, -2
	ds_read_b128 v[112:115], v246
	ds_read_b128 v[116:119], v246 offset:1024
	ds_read_b128 v[120:123], v246 offset:2048
	ds_read_b128 v[124:127], v246 offset:3072
	ds_read_b128 v[136:139], v247
	ds_read_b128 v[140:143], v247 offset:1024
	ds_read_b128 v[152:155], v247 offset:2048
	ds_read_b128 v[156:159], v247 offset:3072
	s_add_u32 s36, s34, 0xfff50080
	s_addc_u32 s37, s35, -1
	s_cmp_eq_u32 s64, 40
	s_cselect_b32 s39, s9, s37
	s_cselect_b32 s38, s8, s36
	s_cselect_b32 s37, s23, s63
	s_cselect_b32 s36, s22, s59
	v_lshl_add_u64 v[206:207], s[34:35], 0, v[200:201]
	s_add_i32 m0, s45, 0xc000
	ds_read_b128 v[160:163], v248
	ds_read_b128 v[164:167], v248 offset:1024
	ds_read_b128 v[168:171], v248 offset:2048
	ds_read_b128 v[172:175], v248 offset:3072
	ds_read_b128 v[176:179], v248 offset:4096
	ds_read_b128 v[180:183], v248 offset:5120
	ds_read_b128 v[184:187], v248 offset:6144
	ds_read_b128 v[188:191], v248 offset:7168
	global_load_lds_dwordx4 v[206:207], off
	v_lshl_add_u64 v[206:207], s[34:35], 0, v[202:203]
	s_add_i32 m0, s45, 0xe000
	s_nop 0
	global_load_lds_dwordx4 v[206:207], off
	s_waitcnt vmcnt(8)
	s_waitcnt lgkmcnt(0)
	s_barrier
	v_mfma_f32_16x16x32_bf16 v[148:151], v[112:115], v[160:163], 0
	v_mfma_f32_16x16x32_bf16 v[144:147], v[120:123], v[160:163], 0
	v_mfma_f32_16x16x32_bf16 v[108:111], v[112:115], v[168:171], 0
	v_mfma_f32_16x16x32_bf16 v[104:107], v[120:123], v[168:171], 0
	v_mfma_f32_16x16x32_bf16 v[92:95], v[112:115], v[176:179], 0
	v_mfma_f32_16x16x32_bf16 v[88:91], v[120:123], v[176:179], 0
	v_mfma_f32_16x16x32_bf16 v[76:79], v[112:115], v[184:187], 0
	v_mfma_f32_16x16x32_bf16 v[72:75], v[120:123], v[184:187], 0
	v_mfma_f32_16x16x32_bf16 v[148:151], v[116:119], v[164:167], v[148:151]
	v_mfma_f32_16x16x32_bf16 v[144:147], v[124:127], v[164:167], v[144:147]
	v_mfma_f32_16x16x32_bf16 v[108:111], v[116:119], v[172:175], v[108:111]
	v_mfma_f32_16x16x32_bf16 v[104:107], v[124:127], v[172:175], v[104:107]
	v_mfma_f32_16x16x32_bf16 v[92:95], v[116:119], v[180:183], v[92:95]
	v_mfma_f32_16x16x32_bf16 v[88:91], v[124:127], v[180:183], v[88:91]
	v_mfma_f32_16x16x32_bf16 v[76:79], v[116:119], v[188:191], v[76:79]
	v_mfma_f32_16x16x32_bf16 v[72:75], v[124:127], v[188:191], v[72:75]
	v_mfma_f32_16x16x32_bf16 v[132:135], v[136:139], v[160:163], 0
	v_mfma_f32_16x16x32_bf16 v[128:131], v[152:155], v[160:163], 0
	v_mfma_f32_16x16x32_bf16 v[100:103], v[136:139], v[168:171], 0
	v_mfma_f32_16x16x32_bf16 v[96:99], v[152:155], v[168:171], 0
	v_mfma_f32_16x16x32_bf16 v[84:87], v[136:139], v[176:179], 0
	v_mfma_f32_16x16x32_bf16 v[80:83], v[152:155], v[176:179], 0
	v_mfma_f32_16x16x32_bf16 v[68:71], v[136:139], v[184:187], 0
	v_mfma_f32_16x16x32_bf16 v[64:67], v[152:155], v[184:187], 0
	v_mfma_f32_16x16x32_bf16 v[132:135], v[140:143], v[164:167], v[132:135]
	v_mfma_f32_16x16x32_bf16 v[128:131], v[156:159], v[164:167], v[128:131]
	v_mfma_f32_16x16x32_bf16 v[100:103], v[140:143], v[172:175], v[100:103]
	v_mfma_f32_16x16x32_bf16 v[96:99], v[156:159], v[172:175], v[96:99]
	v_mfma_f32_16x16x32_bf16 v[84:87], v[140:143], v[180:183], v[84:87]
	v_mfma_f32_16x16x32_bf16 v[80:83], v[156:159], v[180:183], v[80:83]
	v_mfma_f32_16x16x32_bf16 v[68:71], v[140:143], v[188:191], v[68:71]
	v_mfma_f32_16x16x32_bf16 v[64:67], v[156:159], v[188:191], v[64:67]
	s_barrier
	s_add_i32 s65, s53, s44
	v_lshl_add_u64 v[206:207], s[36:37], 0, v[194:195]
	s_mov_b32 m0, s65
	ds_read_b128 v[160:163], v248 offset:16384
	ds_read_b128 v[164:167], v248 offset:17408
	ds_read_b128 v[168:171], v248 offset:18432
	ds_read_b128 v[172:175], v248 offset:19456
	ds_read_b128 v[176:179], v248 offset:20480
	ds_read_b128 v[180:183], v248 offset:21504
	ds_read_b128 v[184:187], v248 offset:22528
	ds_read_b128 v[188:191], v248 offset:23552
	global_load_lds_dwordx4 v[206:207], off
	s_add_i32 m0, s65, 0x2000
	s_add_u32 s66, s36, 0xb0000
	v_lshl_add_u64 v[208:209], s[36:37], 0, v[198:199]
	s_addc_u32 s67, s37, 0
	s_add_i32 s65, s54, s44
	global_load_lds_dwordx4 v[208:209], off
	v_lshl_add_u64 v[210:211], s[66:67], 0, v[194:195]
	s_mov_b32 m0, s65
	v_lshl_add_u64 v[212:213], s[38:39], 0, v[196:197]
	global_load_lds_dwordx4 v[210:211], off
	v_lshl_add_u64 v[210:211], s[66:67], 0, v[198:199]
	s_add_i32 m0, s65, 0x2000
	s_nop 0
	global_load_lds_dwordx4 v[210:211], off
	v_lshl_add_u64 v[210:211], s[38:39], 0, v[192:193]
	s_mov_b32 m0, s45
	s_nop 0
	global_load_lds_dwordx4 v[210:211], off
	s_mov_b32 m0, s46
	s_nop 0
	global_load_lds_dwordx4 v[212:213], off
	s_waitcnt vmcnt(8)
	s_waitcnt lgkmcnt(0)
	s_barrier
; #define PG8_STAGE(bufoff, gbase, voff) do { _Pragma("unroll") for (int _i = 0; _i < 2; ++_i) \
;         __builtin_amdgcn_global_load_lds((const unsigned*)((const char*)(gbase) + (voff)[_i]), (PG8_LAS unsigned*)(lds + (bufoff) + ldsw + _i * 8192), 16, 0, 0); } while (0)
; #define PG8_LDA(dst, b, h) do { _Pragma("unroll") for (int m = 0; m < 4; ++m) _Pragma("unroll") for (int k = 0; k < 2; ++k) dst[m][k] = *(const PG8_LAS bf16x8*)(lds + PG8_SA(b, h) + aoff + m * 2048 + k * 1024); } while (0)
; #define PG8_LDB(dst, b, h) do { _Pragma("unroll") for (int n = 0; n < 2; ++n) _Pragma("unroll") for (int k = 0; k < 2; ++k) dst[n][k] = *(const PG8_LAS bf16x8*)(lds + PG8_SB(b, h) + boff + n * 2048 + k * 1024); } while (0)
; #define PG8_MMA(ai, bj, At, Bt) do { __builtin_amdgcn_s_setprio(1); _Pragma("unroll") for (int m = 0; m < 4; ++m) _Pragma("unroll") for (int n = 0; n < 2; ++n) _Pragma("unroll") for (int k = 0; k < 2; ++k) \
;         acc[ai][bj][m][n] = __builtin_amdgcn_mfma_f32_16x16x32_bf16(Bt[n][k], At[m][k], acc[ai][bj][m][n], 0, 0, 0); __builtin_amdgcn_s_setprio(0); } while (0)
; #define PG8_WAIT_V(n) asm volatile("s_waitcnt vmcnt(" #n ")" ::: "memory")
; #define PG8_WAIT_L(n) asm volatile("s_waitcnt lgkmcnt(" #n ")" ::: "memory")
; #define PG8_BAR __builtin_amdgcn_s_barrier()
; #define PG8_SCHED __builtin_amdgcn_sched_barrier(0)
; template <class Epi, class Sched, bool ALIGN_EPI = false, bool SP2 = false>
; __device__ __forceinline__ void gemm_phase(PG8_LAS unsigned char* lds, const Gemm g, const Sched& S, const Epi& E) {
;     ...
;             PG8_WAIT_V(8); PG8_WAIT_L(0); PG8_BAR; PG8_MMA(1, 0, At, B0); PG8_MMA(1, 1, At, B1); PG8_BAR; PG8_SCHED;
;             PG8_LDB(B0, 1, 0); PG8_LDB(B1, 1, 1); PG8_SCHED; PG8_LDA(At, 1, 0); PG8_STAGE(PG8_SA(0, 1), a2 + hstep, voffA);
;             PG8_WAIT_V(8); PG8_WAIT_L(0); PG8_BAR; PG8_MMA(0, 0, At, B0); PG8_MMA(0, 1, At, B1); PG8_BAR; PG8_SCHED;
	v_mfma_f32_16x16x32_bf16 v[60:63], v[112:115], v[160:163], 0
	v_mfma_f32_16x16x32_bf16 v[56:59], v[120:123], v[160:163], 0
	v_mfma_f32_16x16x32_bf16 v[44:47], v[112:115], v[168:171], 0
	v_mfma_f32_16x16x32_bf16 v[40:43], v[120:123], v[168:171], 0
	v_mfma_f32_16x16x32_bf16 v[28:31], v[112:115], v[176:179], 0
	v_mfma_f32_16x16x32_bf16 v[24:27], v[120:123], v[176:179], 0
	v_mfma_f32_16x16x32_bf16 v[12:15], v[112:115], v[184:187], 0
	v_mfma_f32_16x16x32_bf16 v[8:11], v[120:123], v[184:187], 0
	v_mfma_f32_16x16x32_bf16 v[60:63], v[116:119], v[164:167], v[60:63]
	v_mfma_f32_16x16x32_bf16 v[56:59], v[124:127], v[164:167], v[56:59]
	v_mfma_f32_16x16x32_bf16 v[44:47], v[116:119], v[172:175], v[44:47]
	v_mfma_f32_16x16x32_bf16 v[40:43], v[124:127], v[172:175], v[40:43]
	v_mfma_f32_16x16x32_bf16 v[28:31], v[116:119], v[180:183], v[28:31]
	v_mfma_f32_16x16x32_bf16 v[24:27], v[124:127], v[180:183], v[24:27]
	v_mfma_f32_16x16x32_bf16 v[12:15], v[116:119], v[188:191], v[12:15]
	v_mfma_f32_16x16x32_bf16 v[8:11], v[124:127], v[188:191], v[8:11]
	v_mfma_f32_16x16x32_bf16 v[52:55], v[136:139], v[160:163], 0
	v_mfma_f32_16x16x32_bf16 v[48:51], v[152:155], v[160:163], 0
	v_mfma_f32_16x16x32_bf16 v[36:39], v[136:139], v[168:171], 0
	v_mfma_f32_16x16x32_bf16 v[32:35], v[152:155], v[168:171], 0
	v_mfma_f32_16x16x32_bf16 v[20:23], v[136:139], v[176:179], 0
	v_mfma_f32_16x16x32_bf16 v[16:19], v[152:155], v[176:179], 0
	v_mfma_f32_16x16x32_bf16 v[4:7], v[136:139], v[184:187], 0
	v_mfma_f32_16x16x32_bf16 v[0:3], v[152:155], v[184:187], 0
	v_mfma_f32_16x16x32_bf16 v[52:55], v[140:143], v[164:167], v[52:55]
	v_mfma_f32_16x16x32_bf16 v[48:51], v[156:159], v[164:167], v[48:51]
	v_mfma_f32_16x16x32_bf16 v[36:39], v[140:143], v[172:175], v[36:39]
	v_mfma_f32_16x16x32_bf16 v[32:35], v[156:159], v[172:175], v[32:35]
	v_mfma_f32_16x16x32_bf16 v[20:23], v[140:143], v[180:183], v[20:23]
	v_mfma_f32_16x16x32_bf16 v[16:19], v[156:159], v[180:183], v[16:19]
	v_mfma_f32_16x16x32_bf16 v[4:7], v[140:143], v[188:191], v[4:7]
	v_mfma_f32_16x16x32_bf16 v[0:3], v[156:159], v[188:191], v[0:3]
	s_barrier
	s_add_i32 s65, 0, 0x18000
	s_add_i32 s66, 0, 0x1c000
	v_add_u32_e32 v124, s65, v244
	v_add_u32_e32 v156, s66, v244
	ds_read_b128 v[112:115], v124
	ds_read_b128 v[116:119], v124 offset:1024
	ds_read_b128 v[120:123], v124 offset:2048
	ds_read_b128 v[124:127], v124 offset:3072
	ds_read_b128 v[136:139], v156
	ds_read_b128 v[140:143], v156 offset:1024
	ds_read_b128 v[152:155], v156 offset:2048
	ds_read_b128 v[156:159], v156 offset:3072
	s_add_u32 s38, s38, 0xb0000
	s_addc_u32 s39, s39, 0
	s_mov_b32 m0, s47
	v_lshl_add_u64 v[214:215], s[38:39], 0, v[192:193]
	ds_read_b128 v[160:163], v248 offset:32768
	ds_read_b128 v[164:167], v248 offset:33792
	ds_read_b128 v[168:171], v248 offset:34816
	ds_read_b128 v[172:175], v248 offset:35840
	ds_read_b128 v[176:179], v248 offset:36864
	ds_read_b128 v[180:183], v248 offset:37888
	ds_read_b128 v[184:187], v248 offset:38912
	ds_read_b128 v[188:191], v248 offset:39936
	global_load_lds_dwordx4 v[214:215], off
	v_lshl_add_u64 v[214:215], s[38:39], 0, v[196:197]
	s_mov_b32 m0, s48
	s_nop 0
	global_load_lds_dwordx4 v[214:215], off
	s_waitcnt vmcnt(8)
	s_waitcnt lgkmcnt(0)
	s_barrier
	v_mfma_f32_16x16x32_bf16 v[148:151], v[112:115], v[160:163], v[148:151]
	v_mfma_f32_16x16x32_bf16 v[144:147], v[120:123], v[160:163], v[144:147]
	v_mfma_f32_16x16x32_bf16 v[108:111], v[112:115], v[168:171], v[108:111]
	v_mfma_f32_16x16x32_bf16 v[104:107], v[120:123], v[168:171], v[104:107]
	v_mfma_f32_16x16x32_bf16 v[92:95], v[112:115], v[176:179], v[92:95]
	v_mfma_f32_16x16x32_bf16 v[88:91], v[120:123], v[176:179], v[88:91]
	v_mfma_f32_16x16x32_bf16 v[76:79], v[112:115], v[184:187], v[76:79]
	v_mfma_f32_16x16x32_bf16 v[72:75], v[120:123], v[184:187], v[72:75]
	v_mfma_f32_16x16x32_bf16 v[148:151], v[116:119], v[164:167], v[148:151]
	v_mfma_f32_16x16x32_bf16 v[144:147], v[124:127], v[164:167], v[144:147]
	v_mfma_f32_16x16x32_bf16 v[108:111], v[116:119], v[172:175], v[108:111]
	v_mfma_f32_16x16x32_bf16 v[104:107], v[124:127], v[172:175], v[104:107]
	v_mfma_f32_16x16x32_bf16 v[92:95], v[116:119], v[180:183], v[92:95]
	v_mfma_f32_16x16x32_bf16 v[88:91], v[124:127], v[180:183], v[88:91]
	v_mfma_f32_16x16x32_bf16 v[76:79], v[116:119], v[188:191], v[76:79]
	v_mfma_f32_16x16x32_bf16 v[72:75], v[124:127], v[188:191], v[72:75]
	v_mfma_f32_16x16x32_bf16 v[132:135], v[136:139], v[160:163], v[132:135]
	v_mfma_f32_16x16x32_bf16 v[128:131], v[152:155], v[160:163], v[128:131]
	v_mfma_f32_16x16x32_bf16 v[100:103], v[136:139], v[168:171], v[100:103]
	v_mfma_f32_16x16x32_bf16 v[96:99], v[152:155], v[168:171], v[96:99]
	v_mfma_f32_16x16x32_bf16 v[84:87], v[136:139], v[176:179], v[84:87]
	v_mfma_f32_16x16x32_bf16 v[80:83], v[152:155], v[176:179], v[80:83]
	v_mfma_f32_16x16x32_bf16 v[68:71], v[136:139], v[184:187], v[68:71]
	v_mfma_f32_16x16x32_bf16 v[64:67], v[152:155], v[184:187], v[64:67]
	v_mfma_f32_16x16x32_bf16 v[132:135], v[140:143], v[164:167], v[132:135]
	v_mfma_f32_16x16x32_bf16 v[128:131], v[156:159], v[164:167], v[128:131]
	v_mfma_f32_16x16x32_bf16 v[100:103], v[140:143], v[172:175], v[100:103]
	v_mfma_f32_16x16x32_bf16 v[96:99], v[156:159], v[172:175], v[96:99]
	v_mfma_f32_16x16x32_bf16 v[84:87], v[140:143], v[180:183], v[84:87]
	v_mfma_f32_16x16x32_bf16 v[80:83], v[156:159], v[180:183], v[80:83]
	v_mfma_f32_16x16x32_bf16 v[68:71], v[140:143], v[188:191], v[68:71]
	v_mfma_f32_16x16x32_bf16 v[64:67], v[156:159], v[188:191], v[64:67]
	s_barrier
; #define PG8_STAGE(bufoff, gbase, voff) do { _Pragma("unroll") for (int _i = 0; _i < 2; ++_i) \
;         __builtin_amdgcn_global_load_lds((const unsigned*)((const char*)(gbase) + (voff)[_i]), (PG8_LAS unsigned*)(lds + (bufoff) + ldsw + _i * 8192), 16, 0, 0); } while (0)
; #define PG8_LDA(dst, b, h) do { _Pragma("unroll") for (int m = 0; m < 4; ++m) _Pragma("unroll") for (int k = 0; k < 2; ++k) dst[m][k] = *(const PG8_LAS bf16x8*)(lds + PG8_SA(b, h) + aoff + m * 2048 + k * 1024); } while (0)
; #define PG8_MMA(ai, bj, At, Bt) do { __builtin_amdgcn_s_setprio(1); _Pragma("unroll") for (int m = 0; m < 4; ++m) _Pragma("unroll") for (int n = 0; n < 2; ++n) _Pragma("unroll") for (int k = 0; k < 2; ++k) \
;         acc[ai][bj][m][n] = __builtin_amdgcn_mfma_f32_16x16x32_bf16(Bt[n][k], At[m][k], acc[ai][bj][m][n], 0, 0, 0); __builtin_amdgcn_s_setprio(0); } while (0)
; #define PG8_WAIT_V(n) asm volatile("s_waitcnt vmcnt(" #n ")" ::: "memory")
; #define PG8_WAIT_L(n) asm volatile("s_waitcnt lgkmcnt(" #n ")" ::: "memory")
; #define PG8_BAR __builtin_amdgcn_s_barrier()
; #define PG8_SCHED __builtin_amdgcn_sched_barrier(0)
; template <class Epi, class Sched, bool ALIGN_EPI = false, bool SP2 = false>
; __device__ __forceinline__ void gemm_phase(PG8_LAS unsigned char* lds, const Gemm g, const Sched& S, const Epi& E) {
;     ...
;             PG8_LDA(At, 1, 1); PG8_STAGE(PG8_SB(1, 0), b3, voffB); PG8_STAGE(PG8_SB(1, 1), b3 + hstep, voffB); PG8_STAGE(PG8_SA(1, 0), a3, voffA);
;             PG8_WAIT_V(8); PG8_WAIT_L(0); PG8_BAR; PG8_MMA(1, 0, At, B0); PG8_MMA(1, 1, At, B1); PG8_BAR; PG8_SCHED;
	s_add_i32 s38, s65, s44
	v_lshl_add_u64 v[206:207], v[206:207], 0, s[18:19]
	s_mov_b32 m0, s38
	ds_read_b128 v[160:163], v248 offset:49152
	ds_read_b128 v[164:167], v248 offset:50176
	ds_read_b128 v[168:171], v248 offset:51200
	ds_read_b128 v[172:175], v248 offset:52224
	ds_read_b128 v[176:179], v248 offset:53248
	ds_read_b128 v[180:183], v248 offset:54272
	ds_read_b128 v[184:187], v248 offset:55296
	ds_read_b128 v[188:191], v248 offset:56320
	global_load_lds_dwordx4 v[206:207], off
	s_add_i32 m0, s38, 0x2000
	s_add_u32 s36, s36, 0xb0080
	v_lshl_add_u64 v[206:207], v[208:209], 0, s[18:19]
	s_addc_u32 s37, s37, 0
	s_add_i32 s38, s66, s44
	global_load_lds_dwordx4 v[206:207], off
	v_lshl_add_u64 v[206:207], s[36:37], 0, v[194:195]
	s_mov_b32 m0, s38
	s_nop 0
	global_load_lds_dwordx4 v[206:207], off
	v_lshl_add_u64 v[206:207], s[36:37], 0, v[198:199]
	s_add_i32 m0, s38, 0x2000
	s_nop 0
	global_load_lds_dwordx4 v[206:207], off
	v_lshl_add_u64 v[206:207], v[210:211], 0, s[18:19]
	s_mov_b32 m0, s50
	s_nop 0
	global_load_lds_dwordx4 v[206:207], off
	v_lshl_add_u64 v[206:207], v[212:213], 0, s[18:19]
	s_mov_b32 m0, s51
	s_nop 0
	global_load_lds_dwordx4 v[206:207], off
	s_waitcnt vmcnt(8)
	s_waitcnt lgkmcnt(0)
	s_barrier
	v_mfma_f32_16x16x32_bf16 v[60:63], v[112:115], v[160:163], v[60:63]
	v_mfma_f32_16x16x32_bf16 v[56:59], v[120:123], v[160:163], v[56:59]
	v_mfma_f32_16x16x32_bf16 v[44:47], v[112:115], v[168:171], v[44:47]
	v_mfma_f32_16x16x32_bf16 v[40:43], v[120:123], v[168:171], v[40:43]
	v_mfma_f32_16x16x32_bf16 v[28:31], v[112:115], v[176:179], v[28:31]
	v_mfma_f32_16x16x32_bf16 v[24:27], v[120:123], v[176:179], v[24:27]
	v_mfma_f32_16x16x32_bf16 v[12:15], v[112:115], v[184:187], v[12:15]
	v_mfma_f32_16x16x32_bf16 v[8:11], v[120:123], v[184:187], v[8:11]
	v_mfma_f32_16x16x32_bf16 v[60:63], v[116:119], v[164:167], v[60:63]
	v_mfma_f32_16x16x32_bf16 v[56:59], v[124:127], v[164:167], v[56:59]
	v_mfma_f32_16x16x32_bf16 v[44:47], v[116:119], v[172:175], v[44:47]
	v_mfma_f32_16x16x32_bf16 v[40:43], v[124:127], v[172:175], v[40:43]
	v_mfma_f32_16x16x32_bf16 v[28:31], v[116:119], v[180:183], v[28:31]
	v_mfma_f32_16x16x32_bf16 v[24:27], v[124:127], v[180:183], v[24:27]
	v_mfma_f32_16x16x32_bf16 v[12:15], v[116:119], v[188:191], v[12:15]
	v_mfma_f32_16x16x32_bf16 v[8:11], v[124:127], v[188:191], v[8:11]
	v_mfma_f32_16x16x32_bf16 v[52:55], v[136:139], v[160:163], v[52:55]
	v_mfma_f32_16x16x32_bf16 v[48:51], v[152:155], v[160:163], v[48:51]
	v_mfma_f32_16x16x32_bf16 v[36:39], v[136:139], v[168:171], v[36:39]
	v_mfma_f32_16x16x32_bf16 v[32:35], v[152:155], v[168:171], v[32:35]
	v_mfma_f32_16x16x32_bf16 v[20:23], v[136:139], v[176:179], v[20:23]
	v_mfma_f32_16x16x32_bf16 v[16:19], v[152:155], v[176:179], v[16:19]
	v_mfma_f32_16x16x32_bf16 v[4:7], v[136:139], v[184:187], v[4:7]
	v_mfma_f32_16x16x32_bf16 v[0:3], v[152:155], v[184:187], v[0:3]
	v_mfma_f32_16x16x32_bf16 v[52:55], v[140:143], v[164:167], v[52:55]
	v_mfma_f32_16x16x32_bf16 v[48:51], v[156:159], v[164:167], v[48:51]
	v_mfma_f32_16x16x32_bf16 v[36:39], v[140:143], v[172:175], v[36:39]
	v_mfma_f32_16x16x32_bf16 v[32:35], v[156:159], v[172:175], v[32:35]
	v_mfma_f32_16x16x32_bf16 v[20:23], v[140:143], v[180:183], v[20:23]
	v_mfma_f32_16x16x32_bf16 v[16:19], v[156:159], v[180:183], v[16:19]
	v_mfma_f32_16x16x32_bf16 v[4:7], v[140:143], v[188:191], v[4:7]
	v_mfma_f32_16x16x32_bf16 v[0:3], v[156:159], v[188:191], v[0:3]
	s_barrier
	s_add_i32 s64, s64, 2
	s_add_u32 s34, s34, 0x100
	s_addc_u32 s35, s35, 0
	s_add_u32 s59, s59, 0x100
	s_addc_u32 s63, s63, 0

; __device__ __forceinline__ float rstd_of(const rss_t* rowss, int row) { return __builtin_amdgcn_rsqf(ld_agent(rowss + row) * (1.0f / 1024.0f) + 1e-6f); }
; __device__ __forceinline__ void fgate(const bf16* HB, const bf16* WF, const pg8::rss_t* rowss, const float* bfg, float* LFT, int gx, int ngrp, int gwl, int NGWL, int lane) {
;     const int fr = lane & 15, fq = lane >> 4;
;     const int per = (M / 16) / ngrp;
;     for (int gi = gwl; gi < per; gi += NGWL) { const int grp = gx * per + gi;
;         const int row = grp * 16 + fr;
;         const bf16* ap = HB + (size_t)row * D + 8 * fq; const bf16* wp = WF + (size_t)fr * D + 8 * fq;
;         f32x4 acc = {0.f, 0.f, 0.f, 0.f};
; #pragma unroll 8
;         for (int k = 0; k < D; k += 32) { const bf16x8 av = *(const bf16x8*)(ap + k); const bf16x8 wv = *(const bf16x8*)(wp + k); acc = __builtin_amdgcn_mfma_f32_16x16x32_bf16(wv, av, acc, 0, 0, 0); }
;         const float rs = pg8::rstd_of(rowss, row); const int b = row / SEQ, s = row % SEQ;
.LBB0_578:
	s_waitcnt lgkmcnt(0)
	s_setprio 0
	s_cmp_lt_i32 s6, 4
	s_cselect_b64 s[4:5], -1, 0
	s_cmp_gt_i32 s7, 3
	s_cselect_b64 s[8:9], -1, 0
	s_and_b64 s[4:5], s[4:5], s[8:9]
	s_andn2_b64 vcc, exec, s[4:5]
	s_cbranch_vccnz .LBB0_746
	v_readfirstlane_b32 s3, v242
	s_lshr_b32 s12, s3, 6
	s_and_b64 s[4:5], s[30:31], exec
	s_cselect_b32 s8, 8, 1
	v_cvt_f32_ubyte0_e32 v0, s8
	v_rcp_iflag_f32_e32 v0, v0
	s_sub_i32 s7, 0, s8
	s_abs_i32 s6, s2
	s_ashr_i32 s3, s2, 31
	v_mul_f32_e32 v0, 0x4f7ffffe, v0
	v_cvt_u32_f32_e32 v0, v0
	s_load_dwordx2 s[4:5], s[0:1], 0xd8
	s_movk_i32 s18, 0x100
	v_and_b32_e32 v16, 15, v242
	v_readfirstlane_b32 s9, v0
	s_mul_i32 s7, s7, s9
	s_mul_hi_u32 s7, s9, s7
	s_add_i32 s9, s9, s7
	s_mul_hi_u32 s7, s6, s9
	s_mul_i32 s13, s7, s8
	s_sub_i32 s6, s6, s13
	s_add_i32 s14, s7, 1
	s_sub_i32 s13, s6, s8
	s_cmp_ge_u32 s6, s8
	s_cselect_b32 s7, s14, s7
	s_cselect_b32 s6, s13, s6
	s_add_i32 s13, s7, 1
	s_cmp_ge_u32 s6, s8
	s_cselect_b32 s6, s13, s7
	s_xor_b32 s13, s6, s3
	s_sub_i32 s15, s13, s3
	s_mul_i32 s6, s15, s8
	s_sub_i32 s14, s2, s6
	s_waitcnt lgkmcnt(0)
	s_add_u32 s6, s4, 0x540000
	s_addc_u32 s7, s5, 0
	s_lshl_b32 s15, s15, 3
	s_add_i32 s15, s15, s12
	s_and_b64 s[16:17], s[30:31], exec
	s_cselect_b32 s16, s18, 0x800
	s_cmp_ge_i32 s15, s16
	s_cbranch_scc1 .LBB0_584
	s_abs_i32 s17, s61
	s_mul_hi_u32 s9, s17, s9
	s_mul_i32 s18, s9, s8
	s_sub_i32 s17, s17, s18
	s_ashr_i32 s22, s61, 31
	s_add_i32 s18, s9, 1
	s_sub_i32 s19, s17, s8
	s_cmp_ge_u32 s17, s8
	s_cselect_b32 s9, s18, s9
	s_cselect_b32 s17, s19, s17
	s_add_i32 s18, s9, 1
	s_cmp_ge_u32 s17, s8
	s_cselect_b32 s8, s18, s9
	s_xor_b32 s23, s8, s22
	s_sub_i32 s17, s23, s22
	s_add_u32 s8, s4, 0x200000
	s_addc_u32 s9, s5, 0
	s_lshl_b32 s17, s17, 3
	s_and_b64 s[18:19], s[30:31], exec
	s_cselect_b32 s18, 8, 11
	s_load_dwordx2 s[20:21], s[0:1], 0x38
	s_lshl_b32 s18, s14, s18
	s_add_i32 s12, s18, s12
	s_lshl_b32 s13, s13, 3
	s_add_i32 s12, s12, s13
	s_lshl_b32 s13, s3, 3
	v_bfe_u32 v0, v242, 4, 2
	v_mov_b32_e32 v5, 0
	s_sub_i32 s12, s12, s13
	v_lshlrev_b32_e32 v17, 2, v0
	v_lshlrev_b32_e32 v4, 4, v0
	v_lshl_or_b32 v8, s12, 4, v16
	s_lshl_b32 s12, s23, 7
	s_lshl_b32 s13, s22, 7
	v_lshlrev_b32_e32 v0, 11, v16
	v_mov_b32_e32 v1, v5
	s_waitcnt lgkmcnt(0)
	v_lshl_add_u64 v[6:7], s[20:21], 0, v[4:5]
	v_or_b32_e32 v18, 1, v17
	v_or_b32_e32 v19, 2, v17
	v_or_b32_e32 v20, 3, v17
	s_sub_i32 s19, s12, s13
	v_lshl_add_u64 v[10:11], s[4:5], 0, v[0:1]
	s_mov_b64 s[12:13], 0x200
	s_mov_b32 s20, 0x33800000
	v_mov_b32_e32 v21, 0x358637bd
	s_mov_b32 s21, 0xbfb8aa3b
	s_mov_b32 s22, 0xb2a5705f
	s_mov_b32 s23, 0x42ce8ed0
	s_mov_b32 s34, 0xc2b17218
	s_mov_b32 s35, 0x7f800000
	v_mov_b32_e32 v22, 0x7f800000
	s_mov_b32 s36, 0x3f2aaaab
	v_mov_b32_e32 v23, 0x3ecc95a3
	s_mov_b32 s37, 0x3f317218

; #define PG8_STAGE(bufoff, gbase, voff) do { _Pragma("unroll") for (int _i = 0; _i < 2; ++_i) \
;         __builtin_amdgcn_global_load_lds((const unsigned*)((const char*)(gbase) + (voff)[_i]), (PG8_LAS unsigned*)(lds + (bufoff) + ldsw + _i * 8192), 16, 0, 0); } while (0)
; #define PG8_WAIT_V(n) asm volatile("s_waitcnt vmcnt(" #n ")" ::: "memory")
; #define PG8_BAR __builtin_amdgcn_s_barrier()
; template <class Epi, class Sched, bool ALIGN_EPI = false, bool SP2 = false>
; __device__ __forceinline__ void gemm_phase(PG8_LAS unsigned char* lds, const Gemm g, const Sched& S, const Epi& E) {
;     ...
;         if (wr == 1) PG8_BAR;
;         PG8_WAIT_V(4); PG8_BAR;
;         PG8_STAGE(PG8_SB(1, 0), cB + kstep, voffB); PG8_STAGE(PG8_SA(1, 0), cA + kstep, voffA); PG8_STAGE(PG8_SB(1, 1), cB + hstep + kstep, voffB);
;         PG8_WAIT_V(6); PG8_BAR;
;     }
; __device__ __forceinline__ void run_phase(const int ph, const Args& a, LAS unsigned char* lds, unsigned char* ldsg, const bool dummy = false) {
;     ...
;             pg8::EpiScale E{lay == 0 ? QX : SQKV, lay == 0 ? D : NQKV_SWA, RS + (size_t)rsi * M, lay == 0 ? D : 0, rpg * D, 4, C2};
.LBB0_587:
	s_lshl_b32 s15, s15, 5
	s_and_b32 s22, s15, 0x60
	s_lshl_b32 s19, s18, 13
	s_lshl_b32 s23, s22, 7
	s_ashr_i32 s15, s14, 31
	s_and_b64 s[20:21], s[30:31], exec
	s_cselect_b32 s20, 25, 28
	s_lshl_b64 s[20:21], s[14:15], s20
	s_add_u32 s20, s4, s20
	s_addc_u32 s21, s5, s21
	s_and_b64 s[4:5], s[30:31], exec
	s_cselect_b32 s4, 12, 15
	s_lshl_b64 s[4:5], s[14:15], s4
	s_lshl_b64 s[4:5], s[4:5], 11
	s_sub_u32 s4, 0, s4
	s_subb_u32 s5, 0, s5
	s_add_u32 s4, s20, s4
	s_addc_u32 s5, s21, s5
	s_add_u32 s63, s4, 0xa000000
	s_mov_b64 s[14:15], 0x80
	s_addc_u32 s64, s5, 0
	s_add_i32 m0, s43, 0x18000
	v_lshl_add_u64 v[6:7], v[6:7], 0, s[14:15]
	s_waitcnt vmcnt(2)
	s_barrier
	global_load_lds_dwordx4 v[6:7], off
	v_lshl_add_u64 v[2:3], v[2:3], 0, s[14:15]
	s_add_i32 m0, s43, 0x1a000
	s_add_i32 s65, s43, 0x8000
	s_add_i32 s66, s43, 0xa000
	global_load_lds_dwordx4 v[2:3], off
	v_lshl_add_u64 v[0:1], v[0:1], 0, s[14:15]
	s_mov_b32 m0, s65
	s_add_u32 s4, s46, 0x40080
	global_load_lds_dwordx4 v[0:1], off
	v_lshl_add_u64 v[0:1], v[4:5], 0, s[14:15]
	s_mov_b32 m0, s66
	s_addc_u32 s5, s47, 0
	global_load_lds_dwordx4 v[0:1], off
	s_add_i32 m0, s43, 0x1c000
	v_lshl_add_u64 v[0:1], s[4:5], 0, v[132:133]
	global_load_lds_dwordx4 v[0:1], off
	v_lshl_add_u64 v[0:1], s[4:5], 0, v[128:129]
	s_add_i32 m0, s43, 0x1e000
	v_lshlrev_b32_e32 v2, 2, v16
	global_load_lds_dwordx4 v[0:1], off
	v_lshlrev_b32_e32 v0, 1, v11
	v_lshl_or_b32 v1, v16, 6, v0
	v_and_b32_e32 v2, 32, v2
	v_bitop3_b32 v1, v1, s19, v2 bitop3:0xde
	v_lshlrev_b32_e32 v2, 6, v242
	s_movk_i32 s4, 0x3c0
	v_and_or_b32 v0, v2, s4, v0
	v_lshlrev_b32_e32 v2, 2, v242
	v_and_b32_e32 v2, 32, v2
	v_bitop3_b32 v149, s23, v0, v2 bitop3:0xf6
	v_lshlrev_b32_e32 v0, 8, v242
	v_and_b32_e32 v0, 0x38000, v0
	v_lshlrev_b32_e32 v2, 11, v12
	s_cmpk_lt_u32 s17, 0x100
	v_or3_b32 v0, v9, v0, v2
	s_sext_i32_i8 s75, s16
	s_cselect_b64 s[16:17], -1, 0
	s_ashr_i32 s67, s61, 31
	v_add_u32_e32 v136, v0, v10
	v_lshlrev_b32_e32 v0, 4, v8
	s_waitcnt vmcnt(6)
	s_and_b64 s[4:5], s[30:31], exec
	v_and_b32_e32 v0, 0x78000, v0
	s_cselect_b32 s68, 22, 25
	v_or3_b32 v0, v9, v0, v2
	s_add_i32 s69, 0, 0x10000
	s_add_i32 s70, 0, 0x14000
	v_lshl_or_b32 v148, s18, 6, v16
	v_or_b32_e32 v150, s22, v11
	v_mov_b32_e32 v137, v133
	v_add_u32_e32 v138, v0, v10
	v_mov_b32_e32 v139, v133
	v_mov_b64_e32 v[140:141], 0x600
	v_mov_b64_e32 v[142:143], 0x5ff
	v_add_u32_e32 v151, s69, v149
	v_add_u32_e32 v152, s70, v149
	v_add_u32_e32 v153, 0, v1
	v_mov_b32_e32 v154, 0x358637bd
	s_mov_b32 s71, 0x40000
	s_mov_b64 s[18:19], 0x48000
	s_mov_b32 s72, 0x48000
	s_mov_b64 s[20:21], 0x50000
	s_mov_b32 s73, 0x50000
	s_mov_b64 s[22:23], 0x58000
	s_mov_b32 s74, 0x58000
	v_mov_b32_e32 v155, 0x3e38aa3b
	s_barrier
	v_readfirstlane_b32 s99, v242
	s_nop 3
	s_cmp_ge_u32 s99, 0x100
	s_cbranch_scc1 .Lprio_skip_2
	s_setprio 1
.Lprio_skip_2:
	s_branch .LBB0_590
.LBB0_588:
	s_mov_b64 s[4:5], 0

; #define PG8_STAGE(bufoff, gbase, voff) do { _Pragma("unroll") for (int _i = 0; _i < 2; ++_i) \
;         __builtin_amdgcn_global_load_lds((const unsigned*)((const char*)(gbase) + (voff)[_i]), (PG8_LAS unsigned*)(lds + (bufoff) + ldsw + _i * 8192), 16, 0, 0); } while (0)
; #define PG8_LDA(dst, b, h) do { _Pragma("unroll") for (int m = 0; m < 4; ++m) _Pragma("unroll") for (int k = 0; k < 2; ++k) dst[m][k] = *(const PG8_LAS bf16x8*)(lds + PG8_SA(b, h) + aoff + m * 2048 + k * 1024); } while (0)
; #define PG8_LDB(dst, b, h) do { _Pragma("unroll") for (int n = 0; n < 2; ++n) _Pragma("unroll") for (int k = 0; k < 2; ++k) dst[n][k] = *(const PG8_LAS bf16x8*)(lds + PG8_SB(b, h) + boff + n * 2048 + k * 1024); } while (0)
; #define PG8_WAIT_V(n) asm volatile("s_waitcnt vmcnt(" #n ")" ::: "memory")
; #define PG8_WAIT_L(n) asm volatile("s_waitcnt lgkmcnt(" #n ")" ::: "memory")
; template <class Epi, class Sched, bool ALIGN_EPI = false, bool SP2 = false>
; __device__ __forceinline__ void gemm_phase(PG8_LAS unsigned char* lds, const Gemm g, const Sched& S, const Epi& E) {
;     ...
;         const bool has_next = S.next(ui + 1, nxt);
;         const char* nA = has_next ? (const char*)g.A + (size_t)nxt.pm * tstep : cA; const char* nB = has_next ? (const char*)g.Bt + (size_t)nxt.pn * tstep : cB;
;         for (int t = 0; t < nt; t += 2) {
;             const bool last = (t == nt - 2);
;             if constexpr (Epi::PREFETCH) { if (t == nt - 4) E.prefetch(cur, lds + STAGE_BYTES + 1024, tid); }
;             const char* a1 = cA + (size_t)(t + 1) * kstep;
;             const char* a2 = last ? nA : cA + (size_t)(t + 2) * kstep; const char* b2 = last ? nB : cB + (size_t)(t + 2) * kstep;
;             const char* a3 = a2 + kstep; const char* b3 = b2 + kstep;
;             if (last && has_next) S.a_ready(nxt);
;             if constexpr (SP2) {
;             PG8_LDB(B0, 0, 0); PG8_LDB(B1, 0, 1); PG8_SCHED; PG8_LDA(At, 0, 0); PG8_STAGE(PG8_SA(1, 1), a1 + hstep, voffA);
;             PG8_WAIT_V(8); PG8_WAIT_L(0); PG8_BAR; PG8_MMA(0, 0, At, B0); PG8_MMA(0, 1, At, B1); PG8_BAR; PG8_SCHED;
;             PG8_LDA(At, 0, 1); PG8_STAGE(PG8_SB(0, 0), b2, voffB); PG8_STAGE(PG8_SB(0, 1), b2 + hstep, voffB); PG8_STAGE(PG8_SA(0, 0), a2, voffA);
;             PG8_WAIT_V(8); PG8_WAIT_L(0); PG8_BAR; PG8_MMA(1, 0, At, B0); PG8_MMA(1, 1, At, B1); PG8_BAR; PG8_SCHED;
.LBB0_592:
	s_ashr_i32 s37, s36, 31
	s_lshl_b64 s[38:39], s[36:37], 19
	s_add_u32 s38, s53, s38
	s_addc_u32 s39, s54, s39
	s_and_b64 s[40:41], s[4:5], exec
	s_cselect_b32 s37, s39, s45
	s_cselect_b32 s76, s38, s44
	s_ashr_i32 s35, s34, 31
	s_lshl_b64 s[40:41], s[34:35], 19
	s_add_u32 s40, s50, s40
	s_addc_u32 s41, s51, s41
	s_and_b64 s[48:49], s[4:5], exec
	s_cselect_b32 s35, s41, s47
	s_cselect_b32 s77, s40, s46
	s_add_u32 s44, s44, 0x40080
	s_addc_u32 s45, s45, 0
	s_add_u32 s78, s46, 0x100
	s_addc_u32 s79, s47, 0
	s_mov_b32 s80, -2
	ds_read_b128 v[144:147], v151
	ds_read_b128 v[156:159], v151 offset:1024
	ds_read_b128 v[160:163], v151 offset:2048
	ds_read_b128 v[164:167], v151 offset:3072
	ds_read_b128 v[168:171], v152
	ds_read_b128 v[172:175], v152 offset:1024
	ds_read_b128 v[176:179], v152 offset:2048
	ds_read_b128 v[180:183], v152 offset:3072
	s_add_u32 s46, s44, 0xfffc0080
	s_addc_u32 s47, s45, -1
	s_cmp_eq_u32 s80, 12
	s_cselect_b32 s49, s37, s47
	s_cselect_b32 s48, s76, s46
	s_cselect_b32 s47, s35, s79
	s_cselect_b32 s46, s77, s78
	v_lshl_add_u64 v[216:217], s[44:45], 0, v[136:137]
	s_add_i32 m0, s43, 0xc000
	ds_read_b128 v[184:187], v153
	ds_read_b128 v[188:191], v153 offset:1024
	ds_read_b128 v[192:195], v153 offset:2048
	ds_read_b128 v[196:199], v153 offset:3072
	ds_read_b128 v[200:203], v153 offset:4096
	ds_read_b128 v[204:207], v153 offset:5120
	ds_read_b128 v[208:211], v153 offset:6144
	ds_read_b128 v[212:215], v153 offset:7168
	global_load_lds_dwordx4 v[216:217], off
	v_lshl_add_u64 v[216:217], s[44:45], 0, v[138:139]
	s_add_i32 m0, s43, 0xe000
	s_nop 0
	global_load_lds_dwordx4 v[216:217], off
	s_waitcnt vmcnt(8)
	s_waitcnt lgkmcnt(0)
	s_barrier
	v_mfma_f32_16x16x32_bf16 v[124:127], v[144:147], v[184:187], 0
	v_mfma_f32_16x16x32_bf16 v[120:123], v[160:163], v[184:187], 0
	v_mfma_f32_16x16x32_bf16 v[108:111], v[144:147], v[192:195], 0
	v_mfma_f32_16x16x32_bf16 v[104:107], v[160:163], v[192:195], 0
	v_mfma_f32_16x16x32_bf16 v[92:95], v[144:147], v[200:203], 0
	v_mfma_f32_16x16x32_bf16 v[88:91], v[160:163], v[200:203], 0
	v_mfma_f32_16x16x32_bf16 v[76:79], v[144:147], v[208:211], 0
	v_mfma_f32_16x16x32_bf16 v[72:75], v[160:163], v[208:211], 0
	v_mfma_f32_16x16x32_bf16 v[124:127], v[156:159], v[188:191], v[124:127]
	v_mfma_f32_16x16x32_bf16 v[120:123], v[164:167], v[188:191], v[120:123]
	v_mfma_f32_16x16x32_bf16 v[108:111], v[156:159], v[196:199], v[108:111]
	v_mfma_f32_16x16x32_bf16 v[104:107], v[164:167], v[196:199], v[104:107]
	v_mfma_f32_16x16x32_bf16 v[92:95], v[156:159], v[204:207], v[92:95]
	v_mfma_f32_16x16x32_bf16 v[88:91], v[164:167], v[204:207], v[88:91]
	v_mfma_f32_16x16x32_bf16 v[76:79], v[156:159], v[212:215], v[76:79]
	v_mfma_f32_16x16x32_bf16 v[72:75], v[164:167], v[212:215], v[72:75]
	v_mfma_f32_16x16x32_bf16 v[116:119], v[168:171], v[184:187], 0
	v_mfma_f32_16x16x32_bf16 v[112:115], v[176:179], v[184:187], 0
	v_mfma_f32_16x16x32_bf16 v[100:103], v[168:171], v[192:195], 0
	v_mfma_f32_16x16x32_bf16 v[96:99], v[176:179], v[192:195], 0
	v_mfma_f32_16x16x32_bf16 v[84:87], v[168:171], v[200:203], 0
	v_mfma_f32_16x16x32_bf16 v[80:83], v[176:179], v[200:203], 0
	v_mfma_f32_16x16x32_bf16 v[68:71], v[168:171], v[208:211], 0
	v_mfma_f32_16x16x32_bf16 v[64:67], v[176:179], v[208:211], 0
	v_mfma_f32_16x16x32_bf16 v[116:119], v[172:175], v[188:191], v[116:119]
	v_mfma_f32_16x16x32_bf16 v[112:115], v[180:183], v[188:191], v[112:115]
	v_mfma_f32_16x16x32_bf16 v[100:103], v[172:175], v[196:199], v[100:103]
	v_mfma_f32_16x16x32_bf16 v[96:99], v[180:183], v[196:199], v[96:99]
	v_mfma_f32_16x16x32_bf16 v[84:87], v[172:175], v[204:207], v[84:87]
	v_mfma_f32_16x16x32_bf16 v[80:83], v[180:183], v[204:207], v[80:83]
	v_mfma_f32_16x16x32_bf16 v[68:71], v[172:175], v[212:215], v[68:71]
	v_mfma_f32_16x16x32_bf16 v[64:67], v[180:183], v[212:215], v[64:67]
	s_barrier
	s_add_i32 s81, s69, s52
	v_lshl_add_u64 v[216:217], s[46:47], 0, v[132:133]
	s_mov_b32 m0, s81
	ds_read_b128 v[184:187], v153 offset:16384
	ds_read_b128 v[188:191], v153 offset:17408
	ds_read_b128 v[192:195], v153 offset:18432
	ds_read_b128 v[196:199], v153 offset:19456
	ds_read_b128 v[200:203], v153 offset:20480
	ds_read_b128 v[204:207], v153 offset:21504
	ds_read_b128 v[208:211], v153 offset:22528
	ds_read_b128 v[212:215], v153 offset:23552
	global_load_lds_dwordx4 v[216:217], off
	s_add_i32 m0, s81, 0x2000
	s_add_u32 s82, s46, 0x40000
	v_lshl_add_u64 v[218:219], s[46:47], 0, v[128:129]
	s_addc_u32 s83, s47, 0
	s_add_i32 s81, s70, s52
	global_load_lds_dwordx4 v[218:219], off
	v_lshl_add_u64 v[220:221], s[82:83], 0, v[132:133]
	s_mov_b32 m0, s81
	v_lshl_add_u64 v[222:223], s[48:49], 0, v[130:131]
	global_load_lds_dwordx4 v[220:221], off
	v_lshl_add_u64 v[220:221], s[82:83], 0, v[128:129]
	s_add_i32 m0, s81, 0x2000
	s_nop 0
	global_load_lds_dwordx4 v[220:221], off
	v_lshl_add_u64 v[220:221], s[48:49], 0, v[134:135]
	s_mov_b32 m0, s43
	s_nop 0
	global_load_lds_dwordx4 v[220:221], off
	s_mov_b32 m0, s56
	s_nop 0
	global_load_lds_dwordx4 v[222:223], off
	s_waitcnt vmcnt(8)
	s_waitcnt lgkmcnt(0)
	s_barrier
; #define PG8_STAGE(bufoff, gbase, voff) do { _Pragma("unroll") for (int _i = 0; _i < 2; ++_i) \
;         __builtin_amdgcn_global_load_lds((const unsigned*)((const char*)(gbase) + (voff)[_i]), (PG8_LAS unsigned*)(lds + (bufoff) + ldsw + _i * 8192), 16, 0, 0); } while (0)
; #define PG8_LDA(dst, b, h) do { _Pragma("unroll") for (int m = 0; m < 4; ++m) _Pragma("unroll") for (int k = 0; k < 2; ++k) dst[m][k] = *(const PG8_LAS bf16x8*)(lds + PG8_SA(b, h) + aoff + m * 2048 + k * 1024); } while (0)
; #define PG8_LDB(dst, b, h) do { _Pragma("unroll") for (int n = 0; n < 2; ++n) _Pragma("unroll") for (int k = 0; k < 2; ++k) dst[n][k] = *(const PG8_LAS bf16x8*)(lds + PG8_SB(b, h) + boff + n * 2048 + k * 1024); } while (0)
; #define PG8_MMA(ai, bj, At, Bt) do { __builtin_amdgcn_s_setprio(1); _Pragma("unroll") for (int m = 0; m < 4; ++m) _Pragma("unroll") for (int n = 0; n < 2; ++n) _Pragma("unroll") for (int k = 0; k < 2; ++k) \
;         acc[ai][bj][m][n] = __builtin_amdgcn_mfma_f32_16x16x32_bf16(Bt[n][k], At[m][k], acc[ai][bj][m][n], 0, 0, 0); __builtin_amdgcn_s_setprio(0); } while (0)
; #define PG8_WAIT_V(n) asm volatile("s_waitcnt vmcnt(" #n ")" ::: "memory")
; #define PG8_WAIT_L(n) asm volatile("s_waitcnt lgkmcnt(" #n ")" ::: "memory")
; #define PG8_BAR __builtin_amdgcn_s_barrier()
; #define PG8_SCHED __builtin_amdgcn_sched_barrier(0)
; template <class Epi, class Sched, bool ALIGN_EPI = false, bool SP2 = false>
; __device__ __forceinline__ void gemm_phase(PG8_LAS unsigned char* lds, const Gemm g, const Sched& S, const Epi& E) {
;     ...
;             PG8_WAIT_V(8); PG8_WAIT_L(0); PG8_BAR; PG8_MMA(1, 0, At, B0); PG8_MMA(1, 1, At, B1); PG8_BAR; PG8_SCHED;
;             PG8_LDB(B0, 1, 0); PG8_LDB(B1, 1, 1); PG8_SCHED; PG8_LDA(At, 1, 0); PG8_STAGE(PG8_SA(0, 1), a2 + hstep, voffA);
;             PG8_WAIT_V(8); PG8_WAIT_L(0); PG8_BAR; PG8_MMA(0, 0, At, B0); PG8_MMA(0, 1, At, B1); PG8_BAR; PG8_SCHED;
	v_mfma_f32_16x16x32_bf16 v[60:63], v[144:147], v[184:187], 0
	v_mfma_f32_16x16x32_bf16 v[56:59], v[160:163], v[184:187], 0
	v_mfma_f32_16x16x32_bf16 v[44:47], v[144:147], v[192:195], 0
	v_mfma_f32_16x16x32_bf16 v[40:43], v[160:163], v[192:195], 0
	v_mfma_f32_16x16x32_bf16 v[28:31], v[144:147], v[200:203], 0
	v_mfma_f32_16x16x32_bf16 v[24:27], v[160:163], v[200:203], 0
	v_mfma_f32_16x16x32_bf16 v[12:15], v[144:147], v[208:211], 0
	v_mfma_f32_16x16x32_bf16 v[8:11], v[160:163], v[208:211], 0
	v_mfma_f32_16x16x32_bf16 v[60:63], v[156:159], v[188:191], v[60:63]
	v_mfma_f32_16x16x32_bf16 v[56:59], v[164:167], v[188:191], v[56:59]
	v_mfma_f32_16x16x32_bf16 v[44:47], v[156:159], v[196:199], v[44:47]
	v_mfma_f32_16x16x32_bf16 v[40:43], v[164:167], v[196:199], v[40:43]
	v_mfma_f32_16x16x32_bf16 v[28:31], v[156:159], v[204:207], v[28:31]
	v_mfma_f32_16x16x32_bf16 v[24:27], v[164:167], v[204:207], v[24:27]
	v_mfma_f32_16x16x32_bf16 v[12:15], v[156:159], v[212:215], v[12:15]
	v_mfma_f32_16x16x32_bf16 v[8:11], v[164:167], v[212:215], v[8:11]
	v_mfma_f32_16x16x32_bf16 v[52:55], v[168:171], v[184:187], 0
	v_mfma_f32_16x16x32_bf16 v[48:51], v[176:179], v[184:187], 0
	v_mfma_f32_16x16x32_bf16 v[36:39], v[168:171], v[192:195], 0
	v_mfma_f32_16x16x32_bf16 v[32:35], v[176:179], v[192:195], 0
	v_mfma_f32_16x16x32_bf16 v[20:23], v[168:171], v[200:203], 0
	v_mfma_f32_16x16x32_bf16 v[16:19], v[176:179], v[200:203], 0
	v_mfma_f32_16x16x32_bf16 v[4:7], v[168:171], v[208:211], 0
	v_mfma_f32_16x16x32_bf16 v[0:3], v[176:179], v[208:211], 0
	v_mfma_f32_16x16x32_bf16 v[52:55], v[172:175], v[188:191], v[52:55]
	v_mfma_f32_16x16x32_bf16 v[48:51], v[180:183], v[188:191], v[48:51]
	v_mfma_f32_16x16x32_bf16 v[36:39], v[172:175], v[196:199], v[36:39]
	v_mfma_f32_16x16x32_bf16 v[32:35], v[180:183], v[196:199], v[32:35]
	v_mfma_f32_16x16x32_bf16 v[20:23], v[172:175], v[204:207], v[20:23]
	v_mfma_f32_16x16x32_bf16 v[16:19], v[180:183], v[204:207], v[16:19]
	v_mfma_f32_16x16x32_bf16 v[4:7], v[172:175], v[212:215], v[4:7]
	v_mfma_f32_16x16x32_bf16 v[0:3], v[180:183], v[212:215], v[0:3]
	s_barrier
	s_add_i32 s81, 0, 0x18000
	s_add_i32 s82, 0, 0x1c000
	v_add_u32_e32 v164, s81, v149
	v_add_u32_e32 v180, s82, v149
	ds_read_b128 v[144:147], v164
	ds_read_b128 v[156:159], v164 offset:1024
	ds_read_b128 v[160:163], v164 offset:2048
	ds_read_b128 v[164:167], v164 offset:3072
	ds_read_b128 v[168:171], v180
	ds_read_b128 v[172:175], v180 offset:1024
	ds_read_b128 v[176:179], v180 offset:2048
	ds_read_b128 v[180:183], v180 offset:3072
	s_add_u32 s48, s48, 0x40000
	s_addc_u32 s49, s49, 0
	s_mov_b32 m0, s57
	v_lshl_add_u64 v[224:225], s[48:49], 0, v[134:135]
	ds_read_b128 v[184:187], v153 offset:32768
	ds_read_b128 v[188:191], v153 offset:33792
	ds_read_b128 v[192:195], v153 offset:34816
	ds_read_b128 v[196:199], v153 offset:35840
	ds_read_b128 v[200:203], v153 offset:36864
	ds_read_b128 v[204:207], v153 offset:37888
	ds_read_b128 v[208:211], v153 offset:38912
	ds_read_b128 v[212:215], v153 offset:39936
	global_load_lds_dwordx4 v[224:225], off
	v_lshl_add_u64 v[224:225], s[48:49], 0, v[130:131]
	s_mov_b32 m0, s58
	s_nop 0
	global_load_lds_dwordx4 v[224:225], off
	s_waitcnt vmcnt(8)
	s_waitcnt lgkmcnt(0)
	s_barrier
	v_mfma_f32_16x16x32_bf16 v[124:127], v[144:147], v[184:187], v[124:127]
	v_mfma_f32_16x16x32_bf16 v[120:123], v[160:163], v[184:187], v[120:123]
	v_mfma_f32_16x16x32_bf16 v[108:111], v[144:147], v[192:195], v[108:111]
	v_mfma_f32_16x16x32_bf16 v[104:107], v[160:163], v[192:195], v[104:107]
	v_mfma_f32_16x16x32_bf16 v[92:95], v[144:147], v[200:203], v[92:95]
	v_mfma_f32_16x16x32_bf16 v[88:91], v[160:163], v[200:203], v[88:91]
	v_mfma_f32_16x16x32_bf16 v[76:79], v[144:147], v[208:211], v[76:79]
	v_mfma_f32_16x16x32_bf16 v[72:75], v[160:163], v[208:211], v[72:75]
	v_mfma_f32_16x16x32_bf16 v[124:127], v[156:159], v[188:191], v[124:127]
	v_mfma_f32_16x16x32_bf16 v[120:123], v[164:167], v[188:191], v[120:123]
	v_mfma_f32_16x16x32_bf16 v[108:111], v[156:159], v[196:199], v[108:111]
	v_mfma_f32_16x16x32_bf16 v[104:107], v[164:167], v[196:199], v[104:107]
	v_mfma_f32_16x16x32_bf16 v[92:95], v[156:159], v[204:207], v[92:95]
	v_mfma_f32_16x16x32_bf16 v[88:91], v[164:167], v[204:207], v[88:91]
	v_mfma_f32_16x16x32_bf16 v[76:79], v[156:159], v[212:215], v[76:79]
	v_mfma_f32_16x16x32_bf16 v[72:75], v[164:167], v[212:215], v[72:75]
	v_mfma_f32_16x16x32_bf16 v[116:119], v[168:171], v[184:187], v[116:119]
	v_mfma_f32_16x16x32_bf16 v[112:115], v[176:179], v[184:187], v[112:115]
	v_mfma_f32_16x16x32_bf16 v[100:103], v[168:171], v[192:195], v[100:103]
	v_mfma_f32_16x16x32_bf16 v[96:99], v[176:179], v[192:195], v[96:99]
	v_mfma_f32_16x16x32_bf16 v[84:87], v[168:171], v[200:203], v[84:87]
	v_mfma_f32_16x16x32_bf16 v[80:83], v[176:179], v[200:203], v[80:83]
	v_mfma_f32_16x16x32_bf16 v[68:71], v[168:171], v[208:211], v[68:71]
	v_mfma_f32_16x16x32_bf16 v[64:67], v[176:179], v[208:211], v[64:67]
	v_mfma_f32_16x16x32_bf16 v[116:119], v[172:175], v[188:191], v[116:119]
	v_mfma_f32_16x16x32_bf16 v[112:115], v[180:183], v[188:191], v[112:115]
	v_mfma_f32_16x16x32_bf16 v[100:103], v[172:175], v[196:199], v[100:103]
	v_mfma_f32_16x16x32_bf16 v[96:99], v[180:183], v[196:199], v[96:99]
	v_mfma_f32_16x16x32_bf16 v[84:87], v[172:175], v[204:207], v[84:87]
	v_mfma_f32_16x16x32_bf16 v[80:83], v[180:183], v[204:207], v[80:83]
	v_mfma_f32_16x16x32_bf16 v[68:71], v[172:175], v[212:215], v[68:71]
	v_mfma_f32_16x16x32_bf16 v[64:67], v[180:183], v[212:215], v[64:67]
	s_barrier
; #define PG8_STAGE(bufoff, gbase, voff) do { _Pragma("unroll") for (int _i = 0; _i < 2; ++_i) \
;         __builtin_amdgcn_global_load_lds((const unsigned*)((const char*)(gbase) + (voff)[_i]), (PG8_LAS unsigned*)(lds + (bufoff) + ldsw + _i * 8192), 16, 0, 0); } while (0)
; #define PG8_LDA(dst, b, h) do { _Pragma("unroll") for (int m = 0; m < 4; ++m) _Pragma("unroll") for (int k = 0; k < 2; ++k) dst[m][k] = *(const PG8_LAS bf16x8*)(lds + PG8_SA(b, h) + aoff + m * 2048 + k * 1024); } while (0)
; #define PG8_MMA(ai, bj, At, Bt) do { __builtin_amdgcn_s_setprio(1); _Pragma("unroll") for (int m = 0; m < 4; ++m) _Pragma("unroll") for (int n = 0; n < 2; ++n) _Pragma("unroll") for (int k = 0; k < 2; ++k) \
;         acc[ai][bj][m][n] = __builtin_amdgcn_mfma_f32_16x16x32_bf16(Bt[n][k], At[m][k], acc[ai][bj][m][n], 0, 0, 0); __builtin_amdgcn_s_setprio(0); } while (0)
; #define PG8_WAIT_V(n) asm volatile("s_waitcnt vmcnt(" #n ")" ::: "memory")
; #define PG8_WAIT_L(n) asm volatile("s_waitcnt lgkmcnt(" #n ")" ::: "memory")
; #define PG8_BAR __builtin_amdgcn_s_barrier()
; #define PG8_SCHED __builtin_amdgcn_sched_barrier(0)
; template <class Epi, class Sched, bool ALIGN_EPI = false, bool SP2 = false>
; __device__ __forceinline__ void gemm_phase(PG8_LAS unsigned char* lds, const Gemm g, const Sched& S, const Epi& E) {
;     ...
;             PG8_LDA(At, 1, 1); PG8_STAGE(PG8_SB(1, 0), b3, voffB); PG8_STAGE(PG8_SB(1, 1), b3 + hstep, voffB); PG8_STAGE(PG8_SA(1, 0), a3, voffA);
;             PG8_WAIT_V(8); PG8_WAIT_L(0); PG8_BAR; PG8_MMA(1, 0, At, B0); PG8_MMA(1, 1, At, B1); PG8_BAR; PG8_SCHED;
	s_add_i32 s48, s81, s52
	v_lshl_add_u64 v[216:217], v[216:217], 0, s[14:15]
	s_mov_b32 m0, s48
	ds_read_b128 v[184:187], v153 offset:49152
	ds_read_b128 v[188:191], v153 offset:50176
	ds_read_b128 v[192:195], v153 offset:51200
	ds_read_b128 v[196:199], v153 offset:52224
	ds_read_b128 v[200:203], v153 offset:53248
	ds_read_b128 v[204:207], v153 offset:54272
	ds_read_b128 v[208:211], v153 offset:55296
	ds_read_b128 v[212:215], v153 offset:56320
	global_load_lds_dwordx4 v[216:217], off
	s_add_i32 m0, s48, 0x2000
	s_add_u32 s46, s46, 0x40080
	v_lshl_add_u64 v[216:217], v[218:219], 0, s[14:15]
	s_addc_u32 s47, s47, 0
	s_add_i32 s48, s82, s52
	global_load_lds_dwordx4 v[216:217], off
	v_lshl_add_u64 v[216:217], s[46:47], 0, v[132:133]
	s_mov_b32 m0, s48
	s_nop 0
	global_load_lds_dwordx4 v[216:217], off
	v_lshl_add_u64 v[216:217], s[46:47], 0, v[128:129]
	s_add_i32 m0, s48, 0x2000
	s_nop 0
	global_load_lds_dwordx4 v[216:217], off
	v_lshl_add_u64 v[216:217], v[220:221], 0, s[14:15]
	s_mov_b32 m0, s65
	s_nop 0
	global_load_lds_dwordx4 v[216:217], off
	v_lshl_add_u64 v[216:217], v[222:223], 0, s[14:15]
	s_mov_b32 m0, s66
	s_nop 0
	global_load_lds_dwordx4 v[216:217], off
	s_waitcnt vmcnt(8)
	s_waitcnt lgkmcnt(0)
	s_barrier
	v_mfma_f32_16x16x32_bf16 v[60:63], v[144:147], v[184:187], v[60:63]
	v_mfma_f32_16x16x32_bf16 v[56:59], v[160:163], v[184:187], v[56:59]
	v_mfma_f32_16x16x32_bf16 v[44:47], v[144:147], v[192:195], v[44:47]
	v_mfma_f32_16x16x32_bf16 v[40:43], v[160:163], v[192:195], v[40:43]
	v_mfma_f32_16x16x32_bf16 v[28:31], v[144:147], v[200:203], v[28:31]
	v_mfma_f32_16x16x32_bf16 v[24:27], v[160:163], v[200:203], v[24:27]
	v_mfma_f32_16x16x32_bf16 v[12:15], v[144:147], v[208:211], v[12:15]
	v_mfma_f32_16x16x32_bf16 v[8:11], v[160:163], v[208:211], v[8:11]
	v_mfma_f32_16x16x32_bf16 v[60:63], v[156:159], v[188:191], v[60:63]
	v_mfma_f32_16x16x32_bf16 v[56:59], v[164:167], v[188:191], v[56:59]
	v_mfma_f32_16x16x32_bf16 v[44:47], v[156:159], v[196:199], v[44:47]
	v_mfma_f32_16x16x32_bf16 v[40:43], v[164:167], v[196:199], v[40:43]
	v_mfma_f32_16x16x32_bf16 v[28:31], v[156:159], v[204:207], v[28:31]
	v_mfma_f32_16x16x32_bf16 v[24:27], v[164:167], v[204:207], v[24:27]
	v_mfma_f32_16x16x32_bf16 v[12:15], v[156:159], v[212:215], v[12:15]
	v_mfma_f32_16x16x32_bf16 v[8:11], v[164:167], v[212:215], v[8:11]
	v_mfma_f32_16x16x32_bf16 v[52:55], v[168:171], v[184:187], v[52:55]
	v_mfma_f32_16x16x32_bf16 v[48:51], v[176:179], v[184:187], v[48:51]
	v_mfma_f32_16x16x32_bf16 v[36:39], v[168:171], v[192:195], v[36:39]
	v_mfma_f32_16x16x32_bf16 v[32:35], v[176:179], v[192:195], v[32:35]
	v_mfma_f32_16x16x32_bf16 v[20:23], v[168:171], v[200:203], v[20:23]
	v_mfma_f32_16x16x32_bf16 v[16:19], v[176:179], v[200:203], v[16:19]
	v_mfma_f32_16x16x32_bf16 v[4:7], v[168:171], v[208:211], v[4:7]
	v_mfma_f32_16x16x32_bf16 v[0:3], v[176:179], v[208:211], v[0:3]
	v_mfma_f32_16x16x32_bf16 v[52:55], v[172:175], v[188:191], v[52:55]
	v_mfma_f32_16x16x32_bf16 v[48:51], v[180:183], v[188:191], v[48:51]
	v_mfma_f32_16x16x32_bf16 v[36:39], v[172:175], v[196:199], v[36:39]
	v_mfma_f32_16x16x32_bf16 v[32:35], v[180:183], v[196:199], v[32:35]
	v_mfma_f32_16x16x32_bf16 v[20:23], v[172:175], v[204:207], v[20:23]
	v_mfma_f32_16x16x32_bf16 v[16:19], v[180:183], v[204:207], v[16:19]
	v_mfma_f32_16x16x32_bf16 v[4:7], v[172:175], v[212:215], v[4:7]
	v_mfma_f32_16x16x32_bf16 v[0:3], v[180:183], v[212:215], v[0:3]
	s_barrier
	s_add_i32 s80, s80, 2
	s_add_u32 s44, s44, 0x100
	s_addc_u32 s45, s45, 0
	s_add_u32 s78, s78, 0x100
	s_addc_u32 s79, s79, 0

; #define LAS __attribute__((address_space(3)))
; __device__ __forceinline__ void fox_phase(unsigned char* ldsg, const bf16* Q, const bf16* K, const bf16* V, bf16* O, const float* LFT, int gx, int ngrp, int gj, int gsize) {
;     LAS float* ctab = (LAS float*)((LAS unsigned char*)ldsg + attn_body::LDS_CT);
;     LAS float* wsum = ctab + SEQ;
;     const int per = (BATCH * NH) / ngrp;
;     for (int bi = gj; bi < per; bi += gsize) { const int bh = gx * per + bi;
;         int tid_ = threadIdx.x; asm volatile("" : "+v"(tid_));
;         const int tid = tid_, lane = tid & 63, wid = tid >> 6;
;         __syncthreads();
;         f32x4 v = *(const f32x4*)(LFT + (size_t)bh * SEQ + 4 * tid);
;         v.y += v.x; v.z += v.y; v.w += v.z;
;         const float tot = v.w; float inc = tot;
; #pragma unroll
;         for (int o = 1; o < 64; o <<= 1) { const float n = __shfl_up(inc, o); if (lane >= o) inc += n; }
;         if (lane == 63) wsum[wid] = inc;
;         __syncthreads();
;         float off = inc - tot;
;         for (int w = 0; w < 8; ++w) { const float ws_ = wsum[w]; if (w < wid) off += ws_; }
;         *(LAS f32x4*)(ctab + 4 * tid) = (f32x4){(v.x + off) * L2E, (v.y + off) * L2E, (v.z + off) * L2E, (v.w + off) * L2E};
;         __syncthreads();
;     ...
;             attn_body::attn_unit<48>(bh / NH, bh % NH, qb, (const attn_body::bf16*)Q, (const attn_body::bf16*)K, (const attn_body::bf16*)V, (attn_body::bf16*)O, (char*)ldsg);
.LBB0_746:
	s_waitcnt lgkmcnt(0)
	s_setprio 0
	s_cmp_lt_i32 s6, 5
	s_cselect_b64 s[4:5], -1, 0
	s_cmp_gt_i32 s7, 4
	s_cselect_b64 s[8:9], -1, 0
	s_and_b64 s[4:5], s[4:5], s[8:9]
	s_andn2_b64 vcc, exec, s[4:5]
	s_cbranch_vccnz .LBB0_995
	s_and_b64 s[4:5], s[30:31], exec
	s_cselect_b32 s4, 8, 1
	v_cvt_f32_ubyte0_e32 v0, s4
	v_rcp_iflag_f32_e32 v0, v0
	s_sub_i32 s5, 0, s4
	s_abs_i32 s8, s2
	s_ashr_i32 s3, s2, 31
	v_mul_f32_e32 v0, 0x4f7ffffe, v0
	v_cvt_u32_f32_e32 v0, v0
	s_nop 0
	v_readfirstlane_b32 s9, v0
	s_mul_i32 s5, s5, s9
	s_mul_hi_u32 s5, s9, s5
	s_add_i32 s5, s9, s5
	s_mul_hi_u32 s9, s8, s5
	s_mul_i32 s12, s9, s4
	s_sub_i32 s8, s8, s12
	s_add_i32 s13, s9, 1
	s_sub_i32 s12, s8, s4
	s_cmp_ge_u32 s8, s4
	s_cselect_b32 s9, s13, s9
	s_cselect_b32 s8, s12, s8
	s_add_i32 s12, s9, 1
	s_cmp_ge_u32 s8, s4
	s_cselect_b32 s8, s12, s9
	s_xor_b32 s8, s8, s3
	s_sub_i32 s3, s8, s3
	s_and_b64 s[8:9], s[30:31], exec
	s_cselect_b32 s13, 32, 0x100
	s_cmp_ge_i32 s3, s13
	s_mov_b32 s9, 0
	s_cbranch_scc1 .LBB0_849
	s_abs_i32 s7, s61
	s_mul_hi_u32 s5, s7, s5
	s_mul_i32 s8, s5, s4
	s_sub_i32 s7, s7, s8
	s_ashr_i32 s6, s61, 31
	s_add_i32 s8, s5, 1
	s_sub_i32 s12, s7, s4
	s_cmp_ge_u32 s7, s4
	s_cselect_b32 s5, s8, s5
	s_cselect_b32 s7, s12, s7
	s_add_i32 s8, s5, 1
	s_cmp_ge_u32 s7, s4
	s_cselect_b32 s5, s8, s5
	s_xor_b32 s5, s5, s6
	s_mul_i32 s4, s3, s4
	s_sub_i32 s54, s5, s6
	s_sub_i32 s4, s2, s4
	s_load_dwordx2 s[6:7], s[0:1], 0xd8
	s_ashr_i32 s5, s4, 31
	s_and_b64 s[14:15], s[30:31], exec
	s_cselect_b32 s8, 25, 28
	s_lshl_b64 s[14:15], s[4:5], s8
	s_waitcnt lgkmcnt(0)
	s_add_u32 s8, s6, s14
	s_addc_u32 s12, s7, s15
	s_and_b64 s[14:15], s[30:31], exec
	s_cselect_b32 s14, 12, 15
	s_lshl_b64 s[14:15], s[4:5], s14
	s_lshl_b64 s[14:15], s[14:15], 11
	s_sub_u32 s5, 0, s14
	s_subb_u32 s14, 0, s15
	s_add_u32 s5, s8, s5
	s_addc_u32 s8, s12, s14
	s_add_u32 s55, s5, 0xa000000
	s_addc_u32 s56, s8, 0
	s_mov_b32 s5, 0x800000
	s_and_b64 s[14:15], s[30:31], exec
	s_cselect_b32 s5, s5, 0x4000000
	s_add_u32 s57, s55, s5
	s_addc_u32 s58, s56, 0
	s_add_u32 s59, s57, s5
	s_addc_u32 s63, s58, 0
	s_mov_b32 s5, 0x1800000
	s_and_b64 s[14:15], s[30:31], exec
	s_cselect_b32 s5, s5, 0xc000000
	s_add_u32 s64, s55, s5
	s_addc_u32 s65, s56, 0
	s_add_u32 s66, s6, 0x200000
	s_addc_u32 s67, s7, 0
	s_and_b64 s[6:7], s[30:31], exec
	v_mbcnt_lo_u32_b32 v0, -1, 0
	s_cselect_b32 s5, 5, 8
	v_mbcnt_hi_u32_b32 v214, -1, v0
	s_mov_b32 s22, 0xfffe0000
	s_lshl_b32 s68, s4, s5
	v_mov_b32_e32 v209, 0
	v_and_b32_e32 v215, 64, v214
	v_add_u32_e32 v241, -1, v214
	v_add_u32_e32 v243, -2, v214
	v_add_u32_e32 v220, -16, v214
	v_subrev_u32_e32 v221, 32, v214
	s_add_i32 s69, 0, 0x16804
	s_add_i32 s70, 0, 0x16808
	s_add_i32 s71, 0, 0x1680c
	s_add_i32 s72, 0, 0x16810
	s_add_i32 s73, 0, 0x16814
	s_add_i32 s74, 0, 0x16818
	s_add_i32 s75, 0, 0x1681c
	s_mov_b32 s12, 0x3fb8aa3b
	s_mov_b64 s[14:15], 0x20000
	s_mov_b64 s[16:17], 0x40000
	s_mov_b64 s[18:19], 0x60000
	s_mov_b64 s[20:21], 0xa0000
	s_add_i32 s76, 0, 0x14900
	s_mov_b32 s23, -1
	s_mov_b32 s77, 0x42400000
	s_mov_b64 s[34:35], 0x80000
	v_mov_b32_e32 v222, 0xff800000
	s_branch .LBB0_750

; #define LAS __attribute__((address_space(3)))
; __device__ __forceinline__ void run_phase(const int ph, const Args& a, LAS unsigned char* lds, unsigned char* ldsg, const bool dummy = false) {
;     const int tid = threadIdx.x, lane = tid & 63, wave = __builtin_amdgcn_readfirstlane(tid >> 6);
;     const int G = gridDim.x, bx = blockIdx.x;
;     const int gw = bx * 8 + wave, NGW = G * 8;
;     const int ngrp = (G == 256) ? 8 : 1, gsize = G / ngrp, gx = bx % ngrp, gj = bx / ngrp;
;     unsigned char* ws = a.ws;
;     pg8::rss_t* RS = (pg8::rss_t*)(ws + WS_ROWSS);
;     bf16* HB = (bf16*)(ws + WS_HB);
;     const size_t rpg = (size_t)(M / ngrp), RPG = (256 * MiB) / ngrp;
;     unsigned char* reg = ws + WS_ACT + (size_t)gx * RPG;
;     bf16* ACT = (bf16*)(reg - (size_t)gx * rpg * FF * 2);
;     bf16* QX = (bf16*)(reg - (size_t)gx * rpg * D * 2); bf16* KX = QX + rpg * D; bf16* VX = QX + 2 * rpg * D; bf16* OB = QX + 3 * rpg * D;
.LBB0_995:
	s_waitcnt lgkmcnt(0)
	s_setprio 0
	s_cmp_lt_i32 s6, 6
	s_cselect_b64 s[4:5], -1, 0
	s_cmp_gt_i32 s7, 5
	s_cselect_b64 s[8:9], -1, 0
	s_and_b64 s[4:5], s[4:5], s[8:9]
	s_andn2_b64 vcc, exec, s[4:5]
	s_cbranch_vccnz .LBB0_1184
	s_and_b64 s[4:5], s[30:31], exec
	s_cselect_b32 s14, 8, 1
	v_cvt_f32_ubyte0_e32 v0, s14
	v_rcp_iflag_f32_e32 v0, v0
	s_sub_i32 s8, 0, s14
	s_load_dwordx2 s[4:5], s[0:1], 0xd8
	s_ashr_i32 s3, s2, 31
	v_mul_f32_e32 v0, 0x4f7ffffe, v0
	v_cvt_u32_f32_e32 v0, v0
	s_abs_i32 s15, s2
	v_readfirstlane_b32 s18, v242
	v_readfirstlane_b32 s9, v0
	s_mul_i32 s8, s8, s9
	s_mul_hi_u32 s8, s9, s8
	s_add_i32 s12, s9, s8
	s_cmpk_lt_i32 s2, 0x200
	s_cselect_b64 s[8:9], -1, 0
	s_cmpk_gt_i32 s2, 0x1ff
	s_mul_hi_u32 s16, s15, s12
	s_cbranch_scc1 .LBB0_999
	s_lshr_b32 s12, s3, 29
	s_add_i32 s17, s2, s12
	s_and_b32 s12, s17, -8
	s_sub_i32 s19, s2, s12
	s_cmp_gt_i32 s19, -1
	s_cbranch_scc0 .LBB0_1035
	s_lshl_b32 s20, s19, 6
	s_cbranch_execz .LBB0_1036
	s_branch .LBB0_1037

; #define PG8_STAGE(bufoff, gbase, voff) do { _Pragma("unroll") for (int _i = 0; _i < 2; ++_i) \
;         __builtin_amdgcn_global_load_lds((const unsigned*)((const char*)(gbase) + (voff)[_i]), (PG8_LAS unsigned*)(lds + (bufoff) + ldsw + _i * 8192), 16, 0, 0); } while (0)
; #define PG8_WAIT_V(n) asm volatile("s_waitcnt vmcnt(" #n ")" ::: "memory")
; #define PG8_BAR __builtin_amdgcn_s_barrier()
; template <class Epi, class Sched, bool ALIGN_EPI = false, bool SP2 = false>
; __device__ __forceinline__ void gemm_phase(PG8_LAS unsigned char* lds, const Gemm g, const Sched& S, const Epi& E) {
;     ...
;         if (wr == 1) PG8_BAR;
;         PG8_WAIT_V(4); PG8_BAR;
;         PG8_STAGE(PG8_SB(1, 0), cB + kstep, voffB); PG8_STAGE(PG8_SA(1, 0), cA + kstep, voffA); PG8_STAGE(PG8_SB(1, 1), cB + hstep + kstep, voffB);
;         PG8_WAIT_V(6); PG8_BAR;
;     }
.LBB0_1002:
	s_add_u32 s12, s4, 0x6000000
	s_addc_u32 s13, s5, 0
	s_add_u32 s14, s4, 0x580000
	s_addc_u32 s15, s5, 0
	s_lshl_b32 s4, s7, 5
	s_mov_b64 s[16:17], 0x80
	s_and_b32 s7, s4, 0x60
	s_add_i32 m0, s41, 0x18000
	v_lshl_add_u64 v[6:7], v[6:7], 0, s[16:17]
	s_lshl_b32 s19, s6, 13
	s_lshl_b32 s20, s7, 7
	s_waitcnt vmcnt(2)
	s_barrier
	global_load_lds_dwordx4 v[6:7], off
	v_lshl_add_u64 v[4:5], v[4:5], 0, s[16:17]
	s_add_i32 m0, s41, 0x1a000
	s_add_i32 s57, s41, 0x8000
	s_add_i32 s58, s41, 0xa000
	global_load_lds_dwordx4 v[4:5], off
	v_lshl_add_u64 v[0:1], v[0:1], 0, s[16:17]
	s_mov_b32 m0, s57
	s_add_u32 s4, s44, 0x40080
	global_load_lds_dwordx4 v[0:1], off
	v_lshl_add_u64 v[0:1], v[2:3], 0, s[16:17]
	s_mov_b32 m0, s58
	s_addc_u32 s5, s45, 0
	global_load_lds_dwordx4 v[0:1], off
	s_add_i32 m0, s41, 0x1c000
	v_lshl_add_u64 v[0:1], s[4:5], 0, v[194:195]
	global_load_lds_dwordx4 v[0:1], off
	v_lshl_add_u64 v[0:1], s[4:5], 0, v[198:199]
	s_add_i32 m0, s41, 0x1e000
	v_lshlrev_b32_e32 v3, 2, v242
	global_load_lds_dwordx4 v[0:1], off
	v_bfe_u32 v0, v242, 4, 2
	v_and_b32_e32 v1, 15, v242
	v_lshlrev_b32_e32 v2, 4, v0
	v_lshlrev_b32_e32 v4, 6, v242
	s_movk_i32 s4, 0x3c0
	v_lshl_or_b32 v243, s6, 6, v1
	v_lshl_or_b32 v1, v1, 6, v2
	v_and_b32_e32 v3, 32, v3
	v_and_or_b32 v2, v4, s4, v2
	v_cmp_eq_u32_e64 s[4:5], 0, v0
	v_lshl_or_b32 v245, v0, 3, s7
	v_lshlrev_b32_e32 v0, 8, v242
	v_bitop3_b32 v244, s20, v2, v3 bitop3:0xf6
	v_and_b32_e32 v0, 0x38000, v0
	v_lshlrev_b32_e32 v2, 11, v10
	v_or3_b32 v0, v8, v0, v2
	v_add_u32_e32 v200, v0, v9
	v_lshlrev_b32_e32 v0, 4, v11
	v_and_b32_e32 v0, 0x78000, v0
	s_waitcnt vmcnt(6)
	s_cmpk_lt_u32 s18, 0x100
	v_or3_b32 v0, v8, v0, v2
	v_bitop3_b32 v1, v1, s19, v3 bitop3:0xde
	s_cselect_b64 s[18:19], -1, 0
	v_add_u32_e32 v202, v0, v9
	s_add_i32 s63, 0, 0x10000
	s_add_i32 s64, 0, 0x14000
	v_mbcnt_lo_u32_b32 v0, -1, 0
	s_ashr_i32 s59, s61, 31
	v_mov_b32_e32 v201, v195
	v_mov_b32_e32 v203, v195
	v_mov_b64_e32 v[204:205], 0x1ff
	v_add_u32_e32 v246, s63, v244
	v_add_u32_e32 v247, s64, v244
	v_add_u32_e32 v248, 0, v1
	v_mbcnt_hi_u32_b32 v249, -1, v0
	s_barrier
	v_readfirstlane_b32 s99, v242
	s_nop 3
	s_cmp_ge_u32 s99, 0x100
	s_cbranch_scc1 .Lprio_skip_3
	s_setprio 1
.Lprio_skip_3:
	s_branch .LBB0_1005
.LBB0_1003:
	s_mov_b64 s[6:7], 0

; #define PG8_STAGE(bufoff, gbase, voff) do { _Pragma("unroll") for (int _i = 0; _i < 2; ++_i) \
;         __builtin_amdgcn_global_load_lds((const unsigned*)((const char*)(gbase) + (voff)[_i]), (PG8_LAS unsigned*)(lds + (bufoff) + ldsw + _i * 8192), 16, 0, 0); } while (0)
; #define PG8_LDA(dst, b, h) do { _Pragma("unroll") for (int m = 0; m < 4; ++m) _Pragma("unroll") for (int k = 0; k < 2; ++k) dst[m][k] = *(const PG8_LAS bf16x8*)(lds + PG8_SA(b, h) + aoff + m * 2048 + k * 1024); } while (0)
; #define PG8_LDB(dst, b, h) do { _Pragma("unroll") for (int n = 0; n < 2; ++n) _Pragma("unroll") for (int k = 0; k < 2; ++k) dst[n][k] = *(const PG8_LAS bf16x8*)(lds + PG8_SB(b, h) + boff + n * 2048 + k * 1024); } while (0)
; #define PG8_WAIT_V(n) asm volatile("s_waitcnt vmcnt(" #n ")" ::: "memory")
; #define PG8_WAIT_L(n) asm volatile("s_waitcnt lgkmcnt(" #n ")" ::: "memory")
; template <class Epi, class Sched, bool ALIGN_EPI = false, bool SP2 = false>
; __device__ __forceinline__ void gemm_phase(PG8_LAS unsigned char* lds, const Gemm g, const Sched& S, const Epi& E) {
;     ...
;         const bool has_next = S.next(ui + 1, nxt);
;         const char* nA = has_next ? (const char*)g.A + (size_t)nxt.pm * tstep : cA; const char* nB = has_next ? (const char*)g.Bt + (size_t)nxt.pn * tstep : cB;
;         for (int t = 0; t < nt; t += 2) {
;             const bool last = (t == nt - 2);
;             if constexpr (Epi::PREFETCH) { if (t == nt - 4) E.prefetch(cur, lds + STAGE_BYTES + 1024, tid); }
;             const char* a1 = cA + (size_t)(t + 1) * kstep;
;             const char* a2 = last ? nA : cA + (size_t)(t + 2) * kstep; const char* b2 = last ? nB : cB + (size_t)(t + 2) * kstep;
;             const char* a3 = a2 + kstep; const char* b3 = b2 + kstep;
;             if (last && has_next) S.a_ready(nxt);
;             if constexpr (SP2) {
;             PG8_LDB(B0, 0, 0); PG8_LDB(B1, 0, 1); PG8_SCHED; PG8_LDA(At, 0, 0); PG8_STAGE(PG8_SA(1, 1), a1 + hstep, voffA);
;             PG8_WAIT_V(8); PG8_WAIT_L(0); PG8_BAR; PG8_MMA(0, 0, At, B0); PG8_MMA(0, 1, At, B1); PG8_BAR; PG8_SCHED;
;             PG8_LDA(At, 0, 1); PG8_STAGE(PG8_SB(0, 0), b2, voffB); PG8_STAGE(PG8_SB(0, 1), b2 + hstep, voffB); PG8_STAGE(PG8_SA(0, 0), a2, voffA);
;             PG8_WAIT_V(8); PG8_WAIT_L(0); PG8_BAR; PG8_MMA(1, 0, At, B0); PG8_MMA(1, 1, At, B1); PG8_BAR; PG8_SCHED;
.LBB0_1011:
	s_ashr_i32 s23, s22, 31
	s_lshl_b64 s[34:35], s[22:23], 19
	s_add_u32 s34, s48, s34
	s_addc_u32 s35, s49, s35
	s_and_b64 s[36:37], s[6:7], exec
	s_cselect_b32 s23, s35, s43
	s_cselect_b32 s39, s34, s42
	s_ashr_i32 s21, s20, 31
	s_lshl_b64 s[36:37], s[20:21], 19
	s_add_u32 s36, s50, s36
	s_addc_u32 s37, s51, s37
	s_and_b64 s[46:47], s[6:7], exec
	s_cselect_b32 s21, s37, s45
	s_cselect_b32 s65, s36, s44
	s_add_u32 s42, s42, 0x40080
	s_addc_u32 s43, s43, 0
	s_add_u32 s66, s44, 0x100
	s_addc_u32 s67, s45, 0
	s_mov_b32 s68, -2
	ds_read_b128 v[112:115], v246
	ds_read_b128 v[116:119], v246 offset:1024
	ds_read_b128 v[120:123], v246 offset:2048
	ds_read_b128 v[124:127], v246 offset:3072
	ds_read_b128 v[136:139], v247
	ds_read_b128 v[140:143], v247 offset:1024
	ds_read_b128 v[152:155], v247 offset:2048
	ds_read_b128 v[156:159], v247 offset:3072
	s_add_u32 s44, s42, 0xfffc0080
	s_addc_u32 s45, s43, -1
	s_cmp_eq_u32 s68, 12
	s_cselect_b32 s47, s23, s45
	s_cselect_b32 s46, s39, s44
	s_cselect_b32 s45, s21, s67
	s_cselect_b32 s44, s65, s66
	v_lshl_add_u64 v[206:207], s[42:43], 0, v[200:201]
	s_add_i32 m0, s41, 0xc000
	ds_read_b128 v[160:163], v248
	ds_read_b128 v[164:167], v248 offset:1024
	ds_read_b128 v[168:171], v248 offset:2048
	ds_read_b128 v[172:175], v248 offset:3072
	ds_read_b128 v[176:179], v248 offset:4096
	ds_read_b128 v[180:183], v248 offset:5120
	ds_read_b128 v[184:187], v248 offset:6144
	ds_read_b128 v[188:191], v248 offset:7168
	global_load_lds_dwordx4 v[206:207], off
	v_lshl_add_u64 v[206:207], s[42:43], 0, v[202:203]
	s_add_i32 m0, s41, 0xe000
	s_nop 0
	global_load_lds_dwordx4 v[206:207], off
	s_waitcnt vmcnt(8)
	s_waitcnt lgkmcnt(0)
	s_barrier
	v_mfma_f32_16x16x32_bf16 v[148:151], v[112:115], v[160:163], 0
	v_mfma_f32_16x16x32_bf16 v[144:147], v[120:123], v[160:163], 0
	v_mfma_f32_16x16x32_bf16 v[108:111], v[112:115], v[168:171], 0
	v_mfma_f32_16x16x32_bf16 v[104:107], v[120:123], v[168:171], 0
	v_mfma_f32_16x16x32_bf16 v[92:95], v[112:115], v[176:179], 0
	v_mfma_f32_16x16x32_bf16 v[88:91], v[120:123], v[176:179], 0
	v_mfma_f32_16x16x32_bf16 v[76:79], v[112:115], v[184:187], 0
	v_mfma_f32_16x16x32_bf16 v[72:75], v[120:123], v[184:187], 0
	v_mfma_f32_16x16x32_bf16 v[148:151], v[116:119], v[164:167], v[148:151]
	v_mfma_f32_16x16x32_bf16 v[144:147], v[124:127], v[164:167], v[144:147]
	v_mfma_f32_16x16x32_bf16 v[108:111], v[116:119], v[172:175], v[108:111]
	v_mfma_f32_16x16x32_bf16 v[104:107], v[124:127], v[172:175], v[104:107]
	v_mfma_f32_16x16x32_bf16 v[92:95], v[116:119], v[180:183], v[92:95]
	v_mfma_f32_16x16x32_bf16 v[88:91], v[124:127], v[180:183], v[88:91]
	v_mfma_f32_16x16x32_bf16 v[76:79], v[116:119], v[188:191], v[76:79]
	v_mfma_f32_16x16x32_bf16 v[72:75], v[124:127], v[188:191], v[72:75]
	v_mfma_f32_16x16x32_bf16 v[132:135], v[136:139], v[160:163], 0
	v_mfma_f32_16x16x32_bf16 v[128:131], v[152:155], v[160:163], 0
	v_mfma_f32_16x16x32_bf16 v[100:103], v[136:139], v[168:171], 0
	v_mfma_f32_16x16x32_bf16 v[96:99], v[152:155], v[168:171], 0
	v_mfma_f32_16x16x32_bf16 v[84:87], v[136:139], v[176:179], 0
	v_mfma_f32_16x16x32_bf16 v[80:83], v[152:155], v[176:179], 0
	v_mfma_f32_16x16x32_bf16 v[68:71], v[136:139], v[184:187], 0
	v_mfma_f32_16x16x32_bf16 v[64:67], v[152:155], v[184:187], 0
	v_mfma_f32_16x16x32_bf16 v[132:135], v[140:143], v[164:167], v[132:135]
	v_mfma_f32_16x16x32_bf16 v[128:131], v[156:159], v[164:167], v[128:131]
	v_mfma_f32_16x16x32_bf16 v[100:103], v[140:143], v[172:175], v[100:103]
	v_mfma_f32_16x16x32_bf16 v[96:99], v[156:159], v[172:175], v[96:99]
	v_mfma_f32_16x16x32_bf16 v[84:87], v[140:143], v[180:183], v[84:87]
	v_mfma_f32_16x16x32_bf16 v[80:83], v[156:159], v[180:183], v[80:83]
	v_mfma_f32_16x16x32_bf16 v[68:71], v[140:143], v[188:191], v[68:71]
	v_mfma_f32_16x16x32_bf16 v[64:67], v[156:159], v[188:191], v[64:67]
	s_barrier
	s_add_i32 s69, s63, s52
	v_lshl_add_u64 v[206:207], s[44:45], 0, v[194:195]
	s_mov_b32 m0, s69
	ds_read_b128 v[160:163], v248 offset:16384
	ds_read_b128 v[164:167], v248 offset:17408
	ds_read_b128 v[168:171], v248 offset:18432
	ds_read_b128 v[172:175], v248 offset:19456
	ds_read_b128 v[176:179], v248 offset:20480
	ds_read_b128 v[180:183], v248 offset:21504
	ds_read_b128 v[184:187], v248 offset:22528
	ds_read_b128 v[188:191], v248 offset:23552
	global_load_lds_dwordx4 v[206:207], off
	s_add_i32 m0, s69, 0x2000
	s_add_u32 s70, s44, 0x40000
	v_lshl_add_u64 v[208:209], s[44:45], 0, v[198:199]
	s_addc_u32 s71, s45, 0
	s_add_i32 s69, s64, s52
	global_load_lds_dwordx4 v[208:209], off
	v_lshl_add_u64 v[210:211], s[70:71], 0, v[194:195]
	s_mov_b32 m0, s69
	v_lshl_add_u64 v[212:213], s[46:47], 0, v[196:197]
	global_load_lds_dwordx4 v[210:211], off
	v_lshl_add_u64 v[210:211], s[70:71], 0, v[198:199]
	s_add_i32 m0, s69, 0x2000
	s_nop 0
	global_load_lds_dwordx4 v[210:211], off
	v_lshl_add_u64 v[210:211], s[46:47], 0, v[192:193]
	s_mov_b32 m0, s41
	s_nop 0
	global_load_lds_dwordx4 v[210:211], off
	s_mov_b32 m0, s53
	s_nop 0
	global_load_lds_dwordx4 v[212:213], off
	s_waitcnt vmcnt(8)
	s_waitcnt lgkmcnt(0)
	s_barrier
; #define PG8_STAGE(bufoff, gbase, voff) do { _Pragma("unroll") for (int _i = 0; _i < 2; ++_i) \
;         __builtin_amdgcn_global_load_lds((const unsigned*)((const char*)(gbase) + (voff)[_i]), (PG8_LAS unsigned*)(lds + (bufoff) + ldsw + _i * 8192), 16, 0, 0); } while (0)
; #define PG8_LDA(dst, b, h) do { _Pragma("unroll") for (int m = 0; m < 4; ++m) _Pragma("unroll") for (int k = 0; k < 2; ++k) dst[m][k] = *(const PG8_LAS bf16x8*)(lds + PG8_SA(b, h) + aoff + m * 2048 + k * 1024); } while (0)
; #define PG8_LDB(dst, b, h) do { _Pragma("unroll") for (int n = 0; n < 2; ++n) _Pragma("unroll") for (int k = 0; k < 2; ++k) dst[n][k] = *(const PG8_LAS bf16x8*)(lds + PG8_SB(b, h) + boff + n * 2048 + k * 1024); } while (0)
; #define PG8_MMA(ai, bj, At, Bt) do { __builtin_amdgcn_s_setprio(1); _Pragma("unroll") for (int m = 0; m < 4; ++m) _Pragma("unroll") for (int n = 0; n < 2; ++n) _Pragma("unroll") for (int k = 0; k < 2; ++k) \
;         acc[ai][bj][m][n] = __builtin_amdgcn_mfma_f32_16x16x32_bf16(Bt[n][k], At[m][k], acc[ai][bj][m][n], 0, 0, 0); __builtin_amdgcn_s_setprio(0); } while (0)
; #define PG8_WAIT_V(n) asm volatile("s_waitcnt vmcnt(" #n ")" ::: "memory")
; #define PG8_WAIT_L(n) asm volatile("s_waitcnt lgkmcnt(" #n ")" ::: "memory")
; #define PG8_BAR __builtin_amdgcn_s_barrier()
; #define PG8_SCHED __builtin_amdgcn_sched_barrier(0)
; template <class Epi, class Sched, bool ALIGN_EPI = false, bool SP2 = false>
; __device__ __forceinline__ void gemm_phase(PG8_LAS unsigned char* lds, const Gemm g, const Sched& S, const Epi& E) {
;     ...
;             PG8_WAIT_V(8); PG8_WAIT_L(0); PG8_BAR; PG8_MMA(1, 0, At, B0); PG8_MMA(1, 1, At, B1); PG8_BAR; PG8_SCHED;
;             PG8_LDB(B0, 1, 0); PG8_LDB(B1, 1, 1); PG8_SCHED; PG8_LDA(At, 1, 0); PG8_STAGE(PG8_SA(0, 1), a2 + hstep, voffA);
;             PG8_WAIT_V(8); PG8_WAIT_L(0); PG8_BAR; PG8_MMA(0, 0, At, B0); PG8_MMA(0, 1, At, B1); PG8_BAR; PG8_SCHED;
	v_mfma_f32_16x16x32_bf16 v[60:63], v[112:115], v[160:163], 0
	v_mfma_f32_16x16x32_bf16 v[56:59], v[120:123], v[160:163], 0
	v_mfma_f32_16x16x32_bf16 v[44:47], v[112:115], v[168:171], 0
	v_mfma_f32_16x16x32_bf16 v[40:43], v[120:123], v[168:171], 0
	v_mfma_f32_16x16x32_bf16 v[28:31], v[112:115], v[176:179], 0
	v_mfma_f32_16x16x32_bf16 v[24:27], v[120:123], v[176:179], 0
	v_mfma_f32_16x16x32_bf16 v[12:15], v[112:115], v[184:187], 0
	v_mfma_f32_16x16x32_bf16 v[8:11], v[120:123], v[184:187], 0
	v_mfma_f32_16x16x32_bf16 v[60:63], v[116:119], v[164:167], v[60:63]
	v_mfma_f32_16x16x32_bf16 v[56:59], v[124:127], v[164:167], v[56:59]
	v_mfma_f32_16x16x32_bf16 v[44:47], v[116:119], v[172:175], v[44:47]
	v_mfma_f32_16x16x32_bf16 v[40:43], v[124:127], v[172:175], v[40:43]
	v_mfma_f32_16x16x32_bf16 v[28:31], v[116:119], v[180:183], v[28:31]
	v_mfma_f32_16x16x32_bf16 v[24:27], v[124:127], v[180:183], v[24:27]
	v_mfma_f32_16x16x32_bf16 v[12:15], v[116:119], v[188:191], v[12:15]
	v_mfma_f32_16x16x32_bf16 v[8:11], v[124:127], v[188:191], v[8:11]
	v_mfma_f32_16x16x32_bf16 v[52:55], v[136:139], v[160:163], 0
	v_mfma_f32_16x16x32_bf16 v[48:51], v[152:155], v[160:163], 0
	v_mfma_f32_16x16x32_bf16 v[36:39], v[136:139], v[168:171], 0
	v_mfma_f32_16x16x32_bf16 v[32:35], v[152:155], v[168:171], 0
	v_mfma_f32_16x16x32_bf16 v[20:23], v[136:139], v[176:179], 0
	v_mfma_f32_16x16x32_bf16 v[16:19], v[152:155], v[176:179], 0
	v_mfma_f32_16x16x32_bf16 v[4:7], v[136:139], v[184:187], 0
	v_mfma_f32_16x16x32_bf16 v[0:3], v[152:155], v[184:187], 0
	v_mfma_f32_16x16x32_bf16 v[52:55], v[140:143], v[164:167], v[52:55]
	v_mfma_f32_16x16x32_bf16 v[48:51], v[156:159], v[164:167], v[48:51]
	v_mfma_f32_16x16x32_bf16 v[36:39], v[140:143], v[172:175], v[36:39]
	v_mfma_f32_16x16x32_bf16 v[32:35], v[156:159], v[172:175], v[32:35]
	v_mfma_f32_16x16x32_bf16 v[20:23], v[140:143], v[180:183], v[20:23]
	v_mfma_f32_16x16x32_bf16 v[16:19], v[156:159], v[180:183], v[16:19]
	v_mfma_f32_16x16x32_bf16 v[4:7], v[140:143], v[188:191], v[4:7]
	v_mfma_f32_16x16x32_bf16 v[0:3], v[156:159], v[188:191], v[0:3]
	s_barrier
	s_add_i32 s69, 0, 0x18000
	s_add_i32 s70, 0, 0x1c000
	v_add_u32_e32 v124, s69, v244
	v_add_u32_e32 v156, s70, v244
	ds_read_b128 v[112:115], v124
	ds_read_b128 v[116:119], v124 offset:1024
	ds_read_b128 v[120:123], v124 offset:2048
	ds_read_b128 v[124:127], v124 offset:3072
	ds_read_b128 v[136:139], v156
	ds_read_b128 v[140:143], v156 offset:1024
	ds_read_b128 v[152:155], v156 offset:2048
	ds_read_b128 v[156:159], v156 offset:3072
	s_add_u32 s46, s46, 0x40000
	s_addc_u32 s47, s47, 0
	s_mov_b32 m0, s54
	v_lshl_add_u64 v[214:215], s[46:47], 0, v[192:193]
	ds_read_b128 v[160:163], v248 offset:32768
	ds_read_b128 v[164:167], v248 offset:33792
	ds_read_b128 v[168:171], v248 offset:34816
	ds_read_b128 v[172:175], v248 offset:35840
	ds_read_b128 v[176:179], v248 offset:36864
	ds_read_b128 v[180:183], v248 offset:37888
	ds_read_b128 v[184:187], v248 offset:38912
	ds_read_b128 v[188:191], v248 offset:39936
	global_load_lds_dwordx4 v[214:215], off
	v_lshl_add_u64 v[214:215], s[46:47], 0, v[196:197]
	s_mov_b32 m0, s55
	s_nop 0
	global_load_lds_dwordx4 v[214:215], off
	s_waitcnt vmcnt(8)
	s_waitcnt lgkmcnt(0)
	s_barrier
	v_mfma_f32_16x16x32_bf16 v[148:151], v[112:115], v[160:163], v[148:151]
	v_mfma_f32_16x16x32_bf16 v[144:147], v[120:123], v[160:163], v[144:147]
	v_mfma_f32_16x16x32_bf16 v[108:111], v[112:115], v[168:171], v[108:111]
	v_mfma_f32_16x16x32_bf16 v[104:107], v[120:123], v[168:171], v[104:107]
	v_mfma_f32_16x16x32_bf16 v[92:95], v[112:115], v[176:179], v[92:95]
	v_mfma_f32_16x16x32_bf16 v[88:91], v[120:123], v[176:179], v[88:91]
	v_mfma_f32_16x16x32_bf16 v[76:79], v[112:115], v[184:187], v[76:79]
	v_mfma_f32_16x16x32_bf16 v[72:75], v[120:123], v[184:187], v[72:75]
	v_mfma_f32_16x16x32_bf16 v[148:151], v[116:119], v[164:167], v[148:151]
	v_mfma_f32_16x16x32_bf16 v[144:147], v[124:127], v[164:167], v[144:147]
	v_mfma_f32_16x16x32_bf16 v[108:111], v[116:119], v[172:175], v[108:111]
	v_mfma_f32_16x16x32_bf16 v[104:107], v[124:127], v[172:175], v[104:107]
	v_mfma_f32_16x16x32_bf16 v[92:95], v[116:119], v[180:183], v[92:95]
	v_mfma_f32_16x16x32_bf16 v[88:91], v[124:127], v[180:183], v[88:91]
	v_mfma_f32_16x16x32_bf16 v[76:79], v[116:119], v[188:191], v[76:79]
	v_mfma_f32_16x16x32_bf16 v[72:75], v[124:127], v[188:191], v[72:75]
	v_mfma_f32_16x16x32_bf16 v[132:135], v[136:139], v[160:163], v[132:135]
	v_mfma_f32_16x16x32_bf16 v[128:131], v[152:155], v[160:163], v[128:131]
	v_mfma_f32_16x16x32_bf16 v[100:103], v[136:139], v[168:171], v[100:103]
	v_mfma_f32_16x16x32_bf16 v[96:99], v[152:155], v[168:171], v[96:99]
	v_mfma_f32_16x16x32_bf16 v[84:87], v[136:139], v[176:179], v[84:87]
	v_mfma_f32_16x16x32_bf16 v[80:83], v[152:155], v[176:179], v[80:83]
	v_mfma_f32_16x16x32_bf16 v[68:71], v[136:139], v[184:187], v[68:71]
	v_mfma_f32_16x16x32_bf16 v[64:67], v[152:155], v[184:187], v[64:67]
	v_mfma_f32_16x16x32_bf16 v[132:135], v[140:143], v[164:167], v[132:135]
	v_mfma_f32_16x16x32_bf16 v[128:131], v[156:159], v[164:167], v[128:131]
	v_mfma_f32_16x16x32_bf16 v[100:103], v[140:143], v[172:175], v[100:103]
	v_mfma_f32_16x16x32_bf16 v[96:99], v[156:159], v[172:175], v[96:99]
	v_mfma_f32_16x16x32_bf16 v[84:87], v[140:143], v[180:183], v[84:87]
	v_mfma_f32_16x16x32_bf16 v[80:83], v[156:159], v[180:183], v[80:83]
	v_mfma_f32_16x16x32_bf16 v[68:71], v[140:143], v[188:191], v[68:71]
	v_mfma_f32_16x16x32_bf16 v[64:67], v[156:159], v[188:191], v[64:67]
	s_barrier
; #define PG8_STAGE(bufoff, gbase, voff) do { _Pragma("unroll") for (int _i = 0; _i < 2; ++_i) \
;         __builtin_amdgcn_global_load_lds((const unsigned*)((const char*)(gbase) + (voff)[_i]), (PG8_LAS unsigned*)(lds + (bufoff) + ldsw + _i * 8192), 16, 0, 0); } while (0)
; #define PG8_LDA(dst, b, h) do { _Pragma("unroll") for (int m = 0; m < 4; ++m) _Pragma("unroll") for (int k = 0; k < 2; ++k) dst[m][k] = *(const PG8_LAS bf16x8*)(lds + PG8_SA(b, h) + aoff + m * 2048 + k * 1024); } while (0)
; #define PG8_MMA(ai, bj, At, Bt) do { __builtin_amdgcn_s_setprio(1); _Pragma("unroll") for (int m = 0; m < 4; ++m) _Pragma("unroll") for (int n = 0; n < 2; ++n) _Pragma("unroll") for (int k = 0; k < 2; ++k) \
;         acc[ai][bj][m][n] = __builtin_amdgcn_mfma_f32_16x16x32_bf16(Bt[n][k], At[m][k], acc[ai][bj][m][n], 0, 0, 0); __builtin_amdgcn_s_setprio(0); } while (0)
; #define PG8_WAIT_V(n) asm volatile("s_waitcnt vmcnt(" #n ")" ::: "memory")
; #define PG8_WAIT_L(n) asm volatile("s_waitcnt lgkmcnt(" #n ")" ::: "memory")
; #define PG8_BAR __builtin_amdgcn_s_barrier()
; #define PG8_SCHED __builtin_amdgcn_sched_barrier(0)
; template <class Epi, class Sched, bool ALIGN_EPI = false, bool SP2 = false>
; __device__ __forceinline__ void gemm_phase(PG8_LAS unsigned char* lds, const Gemm g, const Sched& S, const Epi& E) {
;     ...
;             PG8_LDA(At, 1, 1); PG8_STAGE(PG8_SB(1, 0), b3, voffB); PG8_STAGE(PG8_SB(1, 1), b3 + hstep, voffB); PG8_STAGE(PG8_SA(1, 0), a3, voffA);
;             PG8_WAIT_V(8); PG8_WAIT_L(0); PG8_BAR; PG8_MMA(1, 0, At, B0); PG8_MMA(1, 1, At, B1); PG8_BAR; PG8_SCHED;
	s_add_i32 s46, s69, s52
	v_lshl_add_u64 v[206:207], v[206:207], 0, s[16:17]
	s_mov_b32 m0, s46
	ds_read_b128 v[160:163], v248 offset:49152
	ds_read_b128 v[164:167], v248 offset:50176
	ds_read_b128 v[168:171], v248 offset:51200
	ds_read_b128 v[172:175], v248 offset:52224
	ds_read_b128 v[176:179], v248 offset:53248
	ds_read_b128 v[180:183], v248 offset:54272
	ds_read_b128 v[184:187], v248 offset:55296
	ds_read_b128 v[188:191], v248 offset:56320
	global_load_lds_dwordx4 v[206:207], off
	s_add_i32 m0, s46, 0x2000
	s_add_u32 s44, s44, 0x40080
	v_lshl_add_u64 v[206:207], v[208:209], 0, s[16:17]
	s_addc_u32 s45, s45, 0
	s_add_i32 s46, s70, s52
	global_load_lds_dwordx4 v[206:207], off
	v_lshl_add_u64 v[206:207], s[44:45], 0, v[194:195]
	s_mov_b32 m0, s46
	s_nop 0
	global_load_lds_dwordx4 v[206:207], off
	v_lshl_add_u64 v[206:207], s[44:45], 0, v[198:199]
	s_add_i32 m0, s46, 0x2000
	s_nop 0
	global_load_lds_dwordx4 v[206:207], off
	v_lshl_add_u64 v[206:207], v[210:211], 0, s[16:17]
	s_mov_b32 m0, s57
	s_nop 0
	global_load_lds_dwordx4 v[206:207], off
	v_lshl_add_u64 v[206:207], v[212:213], 0, s[16:17]
	s_mov_b32 m0, s58
	s_nop 0
	global_load_lds_dwordx4 v[206:207], off
	s_waitcnt vmcnt(8)
	s_waitcnt lgkmcnt(0)
	s_barrier
	v_mfma_f32_16x16x32_bf16 v[60:63], v[112:115], v[160:163], v[60:63]
	v_mfma_f32_16x16x32_bf16 v[56:59], v[120:123], v[160:163], v[56:59]
	v_mfma_f32_16x16x32_bf16 v[44:47], v[112:115], v[168:171], v[44:47]
	v_mfma_f32_16x16x32_bf16 v[40:43], v[120:123], v[168:171], v[40:43]
	v_mfma_f32_16x16x32_bf16 v[28:31], v[112:115], v[176:179], v[28:31]
	v_mfma_f32_16x16x32_bf16 v[24:27], v[120:123], v[176:179], v[24:27]
	v_mfma_f32_16x16x32_bf16 v[12:15], v[112:115], v[184:187], v[12:15]
	v_mfma_f32_16x16x32_bf16 v[8:11], v[120:123], v[184:187], v[8:11]
	v_mfma_f32_16x16x32_bf16 v[60:63], v[116:119], v[164:167], v[60:63]
	v_mfma_f32_16x16x32_bf16 v[56:59], v[124:127], v[164:167], v[56:59]
	v_mfma_f32_16x16x32_bf16 v[44:47], v[116:119], v[172:175], v[44:47]
	v_mfma_f32_16x16x32_bf16 v[40:43], v[124:127], v[172:175], v[40:43]
	v_mfma_f32_16x16x32_bf16 v[28:31], v[116:119], v[180:183], v[28:31]
	v_mfma_f32_16x16x32_bf16 v[24:27], v[124:127], v[180:183], v[24:27]
	v_mfma_f32_16x16x32_bf16 v[12:15], v[116:119], v[188:191], v[12:15]
	v_mfma_f32_16x16x32_bf16 v[8:11], v[124:127], v[188:191], v[8:11]
	v_mfma_f32_16x16x32_bf16 v[52:55], v[136:139], v[160:163], v[52:55]
	v_mfma_f32_16x16x32_bf16 v[48:51], v[152:155], v[160:163], v[48:51]
	v_mfma_f32_16x16x32_bf16 v[36:39], v[136:139], v[168:171], v[36:39]
	v_mfma_f32_16x16x32_bf16 v[32:35], v[152:155], v[168:171], v[32:35]
	v_mfma_f32_16x16x32_bf16 v[20:23], v[136:139], v[176:179], v[20:23]
	v_mfma_f32_16x16x32_bf16 v[16:19], v[152:155], v[176:179], v[16:19]
	v_mfma_f32_16x16x32_bf16 v[4:7], v[136:139], v[184:187], v[4:7]
	v_mfma_f32_16x16x32_bf16 v[0:3], v[152:155], v[184:187], v[0:3]
	v_mfma_f32_16x16x32_bf16 v[52:55], v[140:143], v[164:167], v[52:55]
	v_mfma_f32_16x16x32_bf16 v[48:51], v[156:159], v[164:167], v[48:51]
	v_mfma_f32_16x16x32_bf16 v[36:39], v[140:143], v[172:175], v[36:39]
	v_mfma_f32_16x16x32_bf16 v[32:35], v[156:159], v[172:175], v[32:35]
	v_mfma_f32_16x16x32_bf16 v[20:23], v[140:143], v[180:183], v[20:23]
	v_mfma_f32_16x16x32_bf16 v[16:19], v[156:159], v[180:183], v[16:19]
	v_mfma_f32_16x16x32_bf16 v[4:7], v[140:143], v[188:191], v[4:7]
	v_mfma_f32_16x16x32_bf16 v[0:3], v[156:159], v[188:191], v[0:3]
	s_barrier
	s_add_i32 s68, s68, 2
	s_add_u32 s42, s42, 0x100
	s_addc_u32 s43, s43, 0
	s_add_u32 s66, s66, 0x100
	s_addc_u32 s67, s67, 0

; #define PG8_STAGE(bufoff, gbase, voff) do { _Pragma("unroll") for (int _i = 0; _i < 2; ++_i) \
;         __builtin_amdgcn_global_load_lds((const unsigned*)((const char*)(gbase) + (voff)[_i]), (PG8_LAS unsigned*)(lds + (bufoff) + ldsw + _i * 8192), 16, 0, 0); } while (0)
; #define PG8_WAIT_V(n) asm volatile("s_waitcnt vmcnt(" #n ")" ::: "memory")
; #define PG8_BAR __builtin_amdgcn_s_barrier()
; template <class Epi, class Sched, bool ALIGN_EPI = false, bool SP2 = false>
; __device__ __forceinline__ void gemm_phase(PG8_LAS unsigned char* lds, const Gemm g, const Sched& S, const Epi& E) {
;     ...
;     const char* cA = (const char*)g.A + (size_t)cur.pm * tstep; const char* cB = (const char*)g.Bt + (size_t)cur.pn * tstep;
;     S.a_ready(cur);
;     if constexpr (SP2) {
;         PG8_STAGE(PG8_SB(0, 0), cB, voffB); PG8_STAGE(PG8_SB(0, 1), cB + hstep, voffB); PG8_STAGE(PG8_SA(0, 0), cA, voffA); PG8_STAGE(PG8_SA(0, 1), cA + hstep, voffA);
;         if (wr == 1) PG8_BAR;
;         PG8_WAIT_V(2); PG8_BAR;
;         PG8_STAGE(PG8_SB(1, 0), cB + kstep, voffB); PG8_STAGE(PG8_SA(1, 0), cA + kstep, voffA); PG8_STAGE(PG8_SB(1, 1), cB + hstep + kstep, voffB);
;         PG8_WAIT_V(6); PG8_BAR;
;     } else {
;         PG8_STAGE(PG8_SB(0, 0), cB, voffB); PG8_STAGE(PG8_SA(0, 0), cA, voffA); PG8_STAGE(PG8_SB(0, 1), cB + hstep, voffB); PG8_STAGE(PG8_SA(0, 1), cA + hstep, voffA);
;         if (wr == 1) PG8_BAR;
;         PG8_WAIT_V(4); PG8_BAR;
;         PG8_STAGE(PG8_SB(1, 0), cB + kstep, voffB); PG8_STAGE(PG8_SA(1, 0), cA + kstep, voffA); PG8_STAGE(PG8_SB(1, 1), cB + hstep + kstep, voffB);
;         PG8_WAIT_V(6); PG8_BAR;
;     }
.LBB0_1184:
	s_waitcnt lgkmcnt(0)
	s_setprio 0
	s_cmp_lt_i32 s6, 7
	s_cselect_b64 s[4:5], -1, 0
	s_cmp_gt_i32 s7, 6
	s_cselect_b64 s[8:9], -1, 0
	s_and_b64 s[4:5], s[4:5], s[8:9]
	s_andn2_b64 vcc, exec, s[4:5]
	s_cbranch_vccnz .LBB0_1347
	s_and_b64 s[4:5], s[30:31], exec
	s_cselect_b32 s8, 8, 1
	v_cvt_f32_ubyte0_e32 v0, s8
	v_rcp_iflag_f32_e32 v0, v0
	v_readfirstlane_b32 s17, v242
	s_cmpk_gt_i32 s2, 0xaff
	v_mul_f32_e32 v0, 0x4f7ffffe, v0
	v_cvt_u32_f32_e32 v0, v0
	s_nop 0
	v_readfirstlane_b32 s12, v0
	s_cbranch_scc1 .LBB0_1201
	v_lshrrev_b32_e32 v0, 5, v242
	v_lshrrev_b32_e32 v2, 1, v242
	s_sub_i32 s6, 0, s8
	s_load_dwordx2 s[4:5], s[0:1], 0xd8
	v_and_b32_e32 v0, 4, v0
	v_bfe_u32 v1, v242, 2, 2
	v_and_b32_e32 v11, 24, v2
	s_mul_i32 s6, s6, s12
	v_or3_b32 v0, v0, v1, v11
	v_lshlrev_b32_e32 v1, 4, v242
	s_mul_hi_u32 s6, s12, s6
	v_add_u32_e32 v8, 0x2000, v1
	s_add_i32 s15, s12, s6
	v_lshrrev_b32_e32 v2, 7, v8
	s_movk_i32 s6, 0xe0
	v_and_b32_e32 v4, 32, v242
	s_ashr_i32 s3, s2, 31
	s_abs_i32 s9, s2
	s_lshr_b32 s14, s17, 6
	v_and_or_b32 v3, v2, s6, v0
	v_bitop3_b32 v9, v1, v4, 48 bitop3:0x6c
	v_and_b32_e32 v10, 64, v242
	v_bfe_u32 v12, v242, 2, 4
	s_movk_i32 s6, 0xf0
	s_waitcnt lgkmcnt(0)
	s_add_u32 s44, s4, 0x6000000
	v_or_b32_e32 v1, v9, v10
	v_and_or_b32 v2, v2, s6, v12
	s_addc_u32 s45, s5, 0
	v_lshl_or_b32 v130, v2, 11, v1
	v_lshrrev_b32_e32 v2, 3, v242
	s_movk_i32 s6, 0x60
	s_add_u32 s46, s4, 0x1900000
	v_and_or_b32 v0, v2, s6, v0
	s_movk_i32 s6, 0x70
	s_addc_u32 s47, s5, 0
	v_lshl_or_b32 v132, v0, 11, v1
	v_and_or_b32 v0, v2, s6, v12
	s_lshr_b32 s6, s3, 29
	s_add_i32 s6, s2, s6
	s_ashr_i32 s7, s6, 3
	s_and_b32 s6, s6, -8
	s_lshr_b32 s18, s17, 8
	s_lshl_b32 s48, s14, 10
	s_sub_i32 s6, s2, s6
	s_cmp_lt_i32 s6, 0
	s_movk_i32 s49, 0x161
	s_cselect_b32 s12, s49, 0x160
	s_mul_i32 s6, s12, s6
	s_add_i32 s6, s6, s7
	s_mul_hi_i32 s7, s6, 0x2e8ba2e9
	s_lshr_b32 s12, s7, 31
	s_ashr_i32 s7, s7, 5
	s_add_i32 s7, s7, s12
	s_lshl_b32 s12, s7, 3
	s_mulk_i32 s7, 0xb0
	s_sub_i32 s6, s6, s7
	s_sext_i32_i16 s7, s6
	s_bfe_u32 s7, s7, 0x3001c
	s_add_i32 s7, s6, s7
	s_sext_i32_i16 s13, s7
	s_and_b32 s7, s7, 0xfff8
	s_sub_i32 s6, s6, s7
	s_sext_i32_i16 s6, s6
	s_lshr_b32 s16, s13, 3
	s_add_i32 s36, s12, s6
	s_ashr_i32 s37, s36, 31
	s_bfe_i64 s[12:13], s[16:17], 0x100000
	s_lshl_b64 s[6:7], s[36:37], 19
	s_lshl_b64 s[12:13], s[12:13], 19
	s_add_u32 s40, s46, s12
	s_addc_u32 s41, s47, s13
	s_add_i32 s37, s48, 0
	s_add_i32 m0, s37, 0x10000
	v_lshl_or_b32 v128, v3, 11, v1
	global_load_lds_dwordx4 v132, s[40:41]
	s_add_i32 m0, s37, 0x12000
	s_add_u32 s12, s40, 0x40000
	global_load_lds_dwordx4 v128, s[40:41]
	s_addc_u32 s13, s41, 0
	s_add_i32 m0, s37, 0x14000
	v_lshl_or_b32 v134, v0, 11, v1
	global_load_lds_dwordx4 v132, s[12:13]
	s_add_i32 m0, s37, 0x16000
	s_add_u32 s38, s44, s6
	s_addc_u32 s39, s45, s7
	s_add_i32 s50, s37, 0x2000
	global_load_lds_dwordx4 v128, s[12:13]
	s_mov_b32 m0, s37
	s_add_u32 s6, s38, 0x40000
	global_load_lds_dwordx4 v134, s[38:39]
	s_mov_b32 m0, s50
	s_addc_u32 s7, s39, 0
	s_add_i32 s51, s37, 0x4000
	global_load_lds_dwordx4 v130, s[38:39]
	s_mov_b32 m0, s51
	s_add_i32 s52, s37, 0x6000
	global_load_lds_dwordx4 v134, s[6:7]
	s_mov_b32 m0, s52
	v_mov_b32_e32 v133, 0
	global_load_lds_dwordx4 v130, s[6:7]
	v_mov_b32_e32 v129, v133
	v_mov_b32_e32 v135, v133
	v_mov_b32_e32 v131, v133
	s_cmp_eq_u32 s18, 1
	s_mul_hi_u32 s12, s9, s15
	v_lshl_add_u64 v[6:7], s[40:41], 0, v[132:133]
	v_lshl_add_u64 v[4:5], s[40:41], 0, v[128:129]
	v_lshl_add_u64 v[0:1], s[38:39], 0, v[134:135]
	s_cselect_b64 s[6:7], -1, 0
	s_cmp_lg_u32 s18, 1
	v_lshl_add_u64 v[2:3], s[38:39], 0, v[130:131]
	s_cbranch_scc1 .LBB0_1188
	s_barrier
.LBB0_1188:
	s_mul_i32 s12, s12, s8
	s_sub_i32 s9, s9, s12
	s_sub_i32 s12, s9, s8
	s_cmp_ge_u32 s9, s8
	s_cselect_b32 s9, s12, s9
	s_sub_i32 s12, s9, s8
	s_cmp_ge_u32 s9, s8
	s_cselect_b32 s8, s12, s9
	s_xor_b32 s8, s8, s3
	s_sub_i32 s8, s8, s3
	s_ashr_i32 s9, s8, 31
	s_and_b64 s[12:13], s[30:31], exec
	s_cselect_b32 s12, 25, 28
	s_lshl_b64 s[12:13], s[8:9], s12
	s_add_u32 s15, s4, s12
	s_addc_u32 s19, s5, s13
	s_and_b64 s[12:13], s[30:31], exec
	s_cselect_b32 s12, 12, 15
	s_lshl_b64 s[8:9], s[8:9], s12
	s_mul_hi_u32 s12, s8, 0xffffea00
	s_sub_i32 s12, s12, s8
	s_mulk_i32 s9, 0xea00
	s_add_i32 s12, s12, s9
	s_mulk_i32 s8, 0xea00
	s_add_u32 s8, s15, s8
	s_addc_u32 s9, s19, s12
	s_add_u32 s8, s8, 0xa000000
	s_addc_u32 s9, s9, 0
	s_add_u32 s12, s4, 0x580000
	s_addc_u32 s13, s5, 0
	s_lshl_b32 s4, s14, 5
	s_mov_b64 s[14:15], 0x80
	s_and_b32 s20, s4, 0x60
	s_add_i32 m0, s37, 0x18000
	v_lshl_add_u64 v[6:7], v[6:7], 0, s[14:15]
	s_lshl_b32 s19, s18, 13
	s_lshl_b32 s21, s20, 7
	s_waitcnt vmcnt(2)
	s_barrier
	global_load_lds_dwordx4 v[6:7], off
	v_lshl_add_u64 v[4:5], v[4:5], 0, s[14:15]
	s_add_i32 m0, s37, 0x1a000
	s_add_i32 s53, s37, 0x8000
	s_add_i32 s54, s37, 0xa000
	global_load_lds_dwordx4 v[4:5], off
	v_lshl_add_u64 v[0:1], v[0:1], 0, s[14:15]
	s_mov_b32 m0, s53
	s_add_u32 s4, s40, 0x40080
	global_load_lds_dwordx4 v[0:1], off
	v_lshl_add_u64 v[0:1], v[2:3], 0, s[14:15]
	s_mov_b32 m0, s54
	s_addc_u32 s5, s41, 0
	global_load_lds_dwordx4 v[0:1], off
	s_add_i32 m0, s37, 0x1c000
	v_lshl_add_u64 v[0:1], s[4:5], 0, v[132:133]
	global_load_lds_dwordx4 v[0:1], off
	v_lshl_add_u64 v[0:1], s[4:5], 0, v[128:129]
	s_add_i32 m0, s37, 0x1e000
	v_lshlrev_b32_e32 v2, 2, v242
	global_load_lds_dwordx4 v[0:1], off
	v_and_b32_e32 v0, 15, v242
	v_lshlrev_b32_e32 v1, 1, v11
	v_lshlrev_b32_e32 v3, 6, v242
	s_movk_i32 s4, 0x3c0
	v_lshl_or_b32 v146, s18, 6, v0
	v_lshl_or_b32 v0, v0, 6, v1
	v_and_b32_e32 v2, 32, v2
	v_and_or_b32 v1, v3, s4, v1
	v_bitop3_b32 v147, s21, v1, v2 bitop3:0xf6
	v_lshlrev_b32_e32 v1, 8, v242
	v_bitop3_b32 v0, v0, s19, v2 bitop3:0xde
	v_and_b32_e32 v1, 0x38000, v1
	v_lshlrev_b32_e32 v2, 11, v12
	v_or3_b32 v1, v9, v1, v2
	v_add_u32_e32 v136, v1, v10
	v_lshlrev_b32_e32 v1, 4, v8
	s_waitcnt vmcnt(6)
	s_cmpk_lt_u32 s17, 0x100
	v_and_b32_e32 v1, 0x78000, v1
	s_sext_i32_i16 s63, s16
	s_cselect_b64 s[16:17], -1, 0
	v_or3_b32 v1, v9, v1, v2
	s_add_i32 s57, 0, 0x10000
	s_add_i32 s58, 0, 0x14000
	s_mov_b32 s55, 0
	s_ashr_i32 s56, s61, 31
	v_or_b32_e32 v148, s20, v11
	v_mov_b32_e32 v137, v133
	v_add_u32_e32 v138, v1, v10
	v_mov_b32_e32 v139, v133
	v_mov_b64_e32 v[140:141], 0xb00
	v_mov_b64_e32 v[142:143], 0xaff
	v_add_u32_e32 v149, s57, v147
	v_add_u32_e32 v150, s58, v147
	v_add_u32_e32 v151, 0, v0
	v_mov_b32_e32 v152, 0x358637bd
	s_movk_i32 s59, 0x1600
	s_barrier
	v_readfirstlane_b32 s99, v242
	s_nop 3
	s_cmp_ge_u32 s99, 0x100
	s_cbranch_scc1 .Lprio_skip_4
	s_setprio 1
.Lprio_skip_4:
	s_branch .LBB0_1191
.LBB0_1189:
	s_mov_b64 s[4:5], 0

; #define PG8_STAGE(bufoff, gbase, voff) do { _Pragma("unroll") for (int _i = 0; _i < 2; ++_i) \
;         __builtin_amdgcn_global_load_lds((const unsigned*)((const char*)(gbase) + (voff)[_i]), (PG8_LAS unsigned*)(lds + (bufoff) + ldsw + _i * 8192), 16, 0, 0); } while (0)
; #define PG8_LDA(dst, b, h) do { _Pragma("unroll") for (int m = 0; m < 4; ++m) _Pragma("unroll") for (int k = 0; k < 2; ++k) dst[m][k] = *(const PG8_LAS bf16x8*)(lds + PG8_SA(b, h) + aoff + m * 2048 + k * 1024); } while (0)
; #define PG8_LDB(dst, b, h) do { _Pragma("unroll") for (int n = 0; n < 2; ++n) _Pragma("unroll") for (int k = 0; k < 2; ++k) dst[n][k] = *(const PG8_LAS bf16x8*)(lds + PG8_SB(b, h) + boff + n * 2048 + k * 1024); } while (0)
; #define PG8_WAIT_V(n) asm volatile("s_waitcnt vmcnt(" #n ")" ::: "memory")
; #define PG8_WAIT_L(n) asm volatile("s_waitcnt lgkmcnt(" #n ")" ::: "memory")
; template <class Epi, class Sched, bool ALIGN_EPI = false, bool SP2 = false>
; __device__ __forceinline__ void gemm_phase(PG8_LAS unsigned char* lds, const Gemm g, const Sched& S, const Epi& E) {
;     ...
;         const bool has_next = S.next(ui + 1, nxt);
;         const char* nA = has_next ? (const char*)g.A + (size_t)nxt.pm * tstep : cA; const char* nB = has_next ? (const char*)g.Bt + (size_t)nxt.pn * tstep : cB;
;         for (int t = 0; t < nt; t += 2) {
;             const bool last = (t == nt - 2);
;             if constexpr (Epi::PREFETCH) { if (t == nt - 4) E.prefetch(cur, lds + STAGE_BYTES + 1024, tid); }
;             const char* a1 = cA + (size_t)(t + 1) * kstep;
;             const char* a2 = last ? nA : cA + (size_t)(t + 2) * kstep; const char* b2 = last ? nB : cB + (size_t)(t + 2) * kstep;
;             const char* a3 = a2 + kstep; const char* b3 = b2 + kstep;
;             if (last && has_next) S.a_ready(nxt);
;             if constexpr (SP2) {
;             PG8_LDB(B0, 0, 0); PG8_LDB(B1, 0, 1); PG8_SCHED; PG8_LDA(At, 0, 0); PG8_STAGE(PG8_SA(1, 1), a1 + hstep, voffA);
;             PG8_WAIT_V(8); PG8_WAIT_L(0); PG8_BAR; PG8_MMA(0, 0, At, B0); PG8_MMA(0, 1, At, B1); PG8_BAR; PG8_SCHED;
;             PG8_LDA(At, 0, 1); PG8_STAGE(PG8_SB(0, 0), b2, voffB); PG8_STAGE(PG8_SB(0, 1), b2 + hstep, voffB); PG8_STAGE(PG8_SA(0, 0), a2, voffA);
;             PG8_WAIT_V(8); PG8_WAIT_L(0); PG8_BAR; PG8_MMA(1, 0, At, B0); PG8_MMA(1, 1, At, B1); PG8_BAR; PG8_SCHED;
.LBB0_1193:
	s_ashr_i32 s21, s20, 31
	s_lshl_b64 s[22:23], s[20:21], 19
	s_add_u32 s22, s44, s22
	s_addc_u32 s23, s45, s23
	s_and_b64 s[34:35], s[4:5], exec
	s_cselect_b32 s21, s23, s39
	s_cselect_b32 s64, s22, s38
	s_ashr_i32 s19, s18, 31
	s_lshl_b64 s[34:35], s[18:19], 19
	s_add_u32 s34, s46, s34
	s_addc_u32 s35, s47, s35
	s_and_b64 s[42:43], s[4:5], exec
	s_cselect_b32 s19, s35, s41
	s_cselect_b32 s65, s34, s40
	s_add_u32 s38, s38, 0x40080
	s_addc_u32 s39, s39, 0
	s_add_u32 s66, s40, 0x100
	s_addc_u32 s67, s41, 0
	s_mov_b32 s68, -2
	ds_read_b128 v[154:157], v149
	ds_read_b128 v[158:161], v149 offset:1024
	ds_read_b128 v[162:165], v149 offset:2048
	ds_read_b128 v[166:169], v149 offset:3072
	ds_read_b128 v[170:173], v150
	ds_read_b128 v[174:177], v150 offset:1024
	ds_read_b128 v[178:181], v150 offset:2048
	ds_read_b128 v[182:185], v150 offset:3072
	s_add_u32 s40, s38, 0xfffc0080
	s_addc_u32 s41, s39, -1
	s_cmp_eq_u32 s68, 12
	s_cselect_b32 s43, s21, s41
	s_cselect_b32 s42, s64, s40
	s_cselect_b32 s41, s19, s67
	s_cselect_b32 s40, s65, s66
	v_lshl_add_u64 v[144:145], s[38:39], 0, v[136:137]
	s_add_i32 m0, s37, 0xc000
	ds_read_b128 v[186:189], v151
	ds_read_b128 v[190:193], v151 offset:1024
	ds_read_b128 v[194:197], v151 offset:2048
	ds_read_b128 v[198:201], v151 offset:3072
	ds_read_b128 v[202:205], v151 offset:4096
	ds_read_b128 v[206:209], v151 offset:5120
	ds_read_b128 v[210:213], v151 offset:6144
	ds_read_b128 v[214:217], v151 offset:7168
	global_load_lds_dwordx4 v[144:145], off
	v_lshl_add_u64 v[144:145], s[38:39], 0, v[138:139]
	s_add_i32 m0, s37, 0xe000
	s_nop 0
	global_load_lds_dwordx4 v[144:145], off
	s_waitcnt vmcnt(8)
	s_waitcnt lgkmcnt(0)
	s_barrier
	v_mfma_f32_16x16x32_bf16 v[120:123], v[154:157], v[186:189], 0
	v_mfma_f32_16x16x32_bf16 v[116:119], v[162:165], v[186:189], 0
	v_mfma_f32_16x16x32_bf16 v[108:111], v[154:157], v[194:197], 0
	v_mfma_f32_16x16x32_bf16 v[100:103], v[162:165], v[194:197], 0
	v_mfma_f32_16x16x32_bf16 v[92:95], v[154:157], v[202:205], 0
	v_mfma_f32_16x16x32_bf16 v[84:87], v[162:165], v[202:205], 0
	v_mfma_f32_16x16x32_bf16 v[76:79], v[154:157], v[210:213], 0
	v_mfma_f32_16x16x32_bf16 v[68:71], v[162:165], v[210:213], 0
	v_mfma_f32_16x16x32_bf16 v[120:123], v[158:161], v[190:193], v[120:123]
	v_mfma_f32_16x16x32_bf16 v[116:119], v[166:169], v[190:193], v[116:119]
	v_mfma_f32_16x16x32_bf16 v[108:111], v[158:161], v[198:201], v[108:111]
	v_mfma_f32_16x16x32_bf16 v[100:103], v[166:169], v[198:201], v[100:103]
	v_mfma_f32_16x16x32_bf16 v[92:95], v[158:161], v[206:209], v[92:95]
	v_mfma_f32_16x16x32_bf16 v[84:87], v[166:169], v[206:209], v[84:87]
	v_mfma_f32_16x16x32_bf16 v[76:79], v[158:161], v[214:217], v[76:79]
	v_mfma_f32_16x16x32_bf16 v[68:71], v[166:169], v[214:217], v[68:71]
	v_mfma_f32_16x16x32_bf16 v[124:127], v[170:173], v[186:189], 0
	v_mfma_f32_16x16x32_bf16 v[112:115], v[178:181], v[186:189], 0
	v_mfma_f32_16x16x32_bf16 v[104:107], v[170:173], v[194:197], 0
	v_mfma_f32_16x16x32_bf16 v[96:99], v[178:181], v[194:197], 0
	v_mfma_f32_16x16x32_bf16 v[88:91], v[170:173], v[202:205], 0
	v_mfma_f32_16x16x32_bf16 v[80:83], v[178:181], v[202:205], 0
	v_mfma_f32_16x16x32_bf16 v[72:75], v[170:173], v[210:213], 0
	v_mfma_f32_16x16x32_bf16 v[64:67], v[178:181], v[210:213], 0
	v_mfma_f32_16x16x32_bf16 v[124:127], v[174:177], v[190:193], v[124:127]
	v_mfma_f32_16x16x32_bf16 v[112:115], v[182:185], v[190:193], v[112:115]
	v_mfma_f32_16x16x32_bf16 v[104:107], v[174:177], v[198:201], v[104:107]
	v_mfma_f32_16x16x32_bf16 v[96:99], v[182:185], v[198:201], v[96:99]
	v_mfma_f32_16x16x32_bf16 v[88:91], v[174:177], v[206:209], v[88:91]
	v_mfma_f32_16x16x32_bf16 v[80:83], v[182:185], v[206:209], v[80:83]
	v_mfma_f32_16x16x32_bf16 v[72:75], v[174:177], v[214:217], v[72:75]
	v_mfma_f32_16x16x32_bf16 v[64:67], v[182:185], v[214:217], v[64:67]
	s_barrier
	s_add_i32 s69, s57, s48
	v_lshl_add_u64 v[144:145], s[40:41], 0, v[132:133]
	s_mov_b32 m0, s69
	ds_read_b128 v[186:189], v151 offset:16384
	ds_read_b128 v[190:193], v151 offset:17408
	ds_read_b128 v[194:197], v151 offset:18432
	ds_read_b128 v[198:201], v151 offset:19456
	ds_read_b128 v[202:205], v151 offset:20480
	ds_read_b128 v[206:209], v151 offset:21504
	ds_read_b128 v[210:213], v151 offset:22528
	ds_read_b128 v[214:217], v151 offset:23552
	global_load_lds_dwordx4 v[144:145], off
	s_add_i32 m0, s69, 0x2000
	s_add_u32 s70, s40, 0x40000
	v_lshl_add_u64 v[218:219], s[40:41], 0, v[128:129]
	s_addc_u32 s71, s41, 0
	s_add_i32 s69, s58, s48
	global_load_lds_dwordx4 v[218:219], off
	v_lshl_add_u64 v[220:221], s[70:71], 0, v[132:133]
	s_mov_b32 m0, s69
	v_lshl_add_u64 v[222:223], s[42:43], 0, v[130:131]
	global_load_lds_dwordx4 v[220:221], off
	v_lshl_add_u64 v[220:221], s[70:71], 0, v[128:129]
	s_add_i32 m0, s69, 0x2000
	s_nop 0
	global_load_lds_dwordx4 v[220:221], off
	v_lshl_add_u64 v[220:221], s[42:43], 0, v[134:135]
	s_mov_b32 m0, s37
	s_nop 0
	global_load_lds_dwordx4 v[220:221], off
	s_mov_b32 m0, s50
	s_nop 0
	global_load_lds_dwordx4 v[222:223], off
	s_waitcnt vmcnt(8)
	s_waitcnt lgkmcnt(0)
	s_barrier
; #define PG8_STAGE(bufoff, gbase, voff) do { _Pragma("unroll") for (int _i = 0; _i < 2; ++_i) \
;         __builtin_amdgcn_global_load_lds((const unsigned*)((const char*)(gbase) + (voff)[_i]), (PG8_LAS unsigned*)(lds + (bufoff) + ldsw + _i * 8192), 16, 0, 0); } while (0)
; #define PG8_LDA(dst, b, h) do { _Pragma("unroll") for (int m = 0; m < 4; ++m) _Pragma("unroll") for (int k = 0; k < 2; ++k) dst[m][k] = *(const PG8_LAS bf16x8*)(lds + PG8_SA(b, h) + aoff + m * 2048 + k * 1024); } while (0)
; #define PG8_LDB(dst, b, h) do { _Pragma("unroll") for (int n = 0; n < 2; ++n) _Pragma("unroll") for (int k = 0; k < 2; ++k) dst[n][k] = *(const PG8_LAS bf16x8*)(lds + PG8_SB(b, h) + boff + n * 2048 + k * 1024); } while (0)
; #define PG8_MMA(ai, bj, At, Bt) do { __builtin_amdgcn_s_setprio(1); _Pragma("unroll") for (int m = 0; m < 4; ++m) _Pragma("unroll") for (int n = 0; n < 2; ++n) _Pragma("unroll") for (int k = 0; k < 2; ++k) \
;         acc[ai][bj][m][n] = __builtin_amdgcn_mfma_f32_16x16x32_bf16(Bt[n][k], At[m][k], acc[ai][bj][m][n], 0, 0, 0); __builtin_amdgcn_s_setprio(0); } while (0)
; #define PG8_WAIT_V(n) asm volatile("s_waitcnt vmcnt(" #n ")" ::: "memory")
; #define PG8_WAIT_L(n) asm volatile("s_waitcnt lgkmcnt(" #n ")" ::: "memory")
; #define PG8_BAR __builtin_amdgcn_s_barrier()
; #define PG8_SCHED __builtin_amdgcn_sched_barrier(0)
; template <class Epi, class Sched, bool ALIGN_EPI = false, bool SP2 = false>
; __device__ __forceinline__ void gemm_phase(PG8_LAS unsigned char* lds, const Gemm g, const Sched& S, const Epi& E) {
;     ...
;             PG8_WAIT_V(8); PG8_WAIT_L(0); PG8_BAR; PG8_MMA(1, 0, At, B0); PG8_MMA(1, 1, At, B1); PG8_BAR; PG8_SCHED;
;             PG8_LDB(B0, 1, 0); PG8_LDB(B1, 1, 1); PG8_SCHED; PG8_LDA(At, 1, 0); PG8_STAGE(PG8_SA(0, 1), a2 + hstep, voffA);
;             PG8_WAIT_V(8); PG8_WAIT_L(0); PG8_BAR; PG8_MMA(0, 0, At, B0); PG8_MMA(0, 1, At, B1); PG8_BAR; PG8_SCHED;
	v_mfma_f32_16x16x32_bf16 v[60:63], v[154:157], v[186:189], 0
	v_mfma_f32_16x16x32_bf16 v[52:55], v[162:165], v[186:189], 0
	v_mfma_f32_16x16x32_bf16 v[44:47], v[154:157], v[194:197], 0
	v_mfma_f32_16x16x32_bf16 v[36:39], v[162:165], v[194:197], 0
	v_mfma_f32_16x16x32_bf16 v[28:31], v[154:157], v[202:205], 0
	v_mfma_f32_16x16x32_bf16 v[20:23], v[162:165], v[202:205], 0
	v_mfma_f32_16x16x32_bf16 v[12:15], v[154:157], v[210:213], 0
	v_mfma_f32_16x16x32_bf16 v[4:7], v[162:165], v[210:213], 0
	v_mfma_f32_16x16x32_bf16 v[60:63], v[158:161], v[190:193], v[60:63]
	v_mfma_f32_16x16x32_bf16 v[52:55], v[166:169], v[190:193], v[52:55]
	v_mfma_f32_16x16x32_bf16 v[44:47], v[158:161], v[198:201], v[44:47]
	v_mfma_f32_16x16x32_bf16 v[36:39], v[166:169], v[198:201], v[36:39]
	v_mfma_f32_16x16x32_bf16 v[28:31], v[158:161], v[206:209], v[28:31]
	v_mfma_f32_16x16x32_bf16 v[20:23], v[166:169], v[206:209], v[20:23]
	v_mfma_f32_16x16x32_bf16 v[12:15], v[158:161], v[214:217], v[12:15]
	v_mfma_f32_16x16x32_bf16 v[4:7], v[166:169], v[214:217], v[4:7]
	v_mfma_f32_16x16x32_bf16 v[56:59], v[170:173], v[186:189], 0
	v_mfma_f32_16x16x32_bf16 v[48:51], v[178:181], v[186:189], 0
	v_mfma_f32_16x16x32_bf16 v[40:43], v[170:173], v[194:197], 0
	v_mfma_f32_16x16x32_bf16 v[32:35], v[178:181], v[194:197], 0
	v_mfma_f32_16x16x32_bf16 v[24:27], v[170:173], v[202:205], 0
	v_mfma_f32_16x16x32_bf16 v[16:19], v[178:181], v[202:205], 0
	v_mfma_f32_16x16x32_bf16 v[8:11], v[170:173], v[210:213], 0
	v_mfma_f32_16x16x32_bf16 v[0:3], v[178:181], v[210:213], 0
	v_mfma_f32_16x16x32_bf16 v[56:59], v[174:177], v[190:193], v[56:59]
	v_mfma_f32_16x16x32_bf16 v[48:51], v[182:185], v[190:193], v[48:51]
	v_mfma_f32_16x16x32_bf16 v[40:43], v[174:177], v[198:201], v[40:43]
	v_mfma_f32_16x16x32_bf16 v[32:35], v[182:185], v[198:201], v[32:35]
	v_mfma_f32_16x16x32_bf16 v[24:27], v[174:177], v[206:209], v[24:27]
	v_mfma_f32_16x16x32_bf16 v[16:19], v[182:185], v[206:209], v[16:19]
	v_mfma_f32_16x16x32_bf16 v[8:11], v[174:177], v[214:217], v[8:11]
	v_mfma_f32_16x16x32_bf16 v[0:3], v[182:185], v[214:217], v[0:3]
	s_barrier
	s_add_i32 s69, 0, 0x18000
	v_add_u32_e32 v153, s69, v147
	s_add_i32 s70, 0, 0x1c000
	ds_read_b128 v[154:157], v153
	ds_read_b128 v[158:161], v153 offset:1024
	ds_read_b128 v[162:165], v153 offset:2048
	ds_read_b128 v[166:169], v153 offset:3072
	v_add_u32_e32 v153, s70, v147
	ds_read_b128 v[170:173], v153
	ds_read_b128 v[174:177], v153 offset:1024
	ds_read_b128 v[178:181], v153 offset:2048
	ds_read_b128 v[182:185], v153 offset:3072
	s_add_u32 s42, s42, 0x40000
	s_addc_u32 s43, s43, 0
	s_mov_b32 m0, s51
	v_lshl_add_u64 v[224:225], s[42:43], 0, v[134:135]
	ds_read_b128 v[186:189], v151 offset:32768
	ds_read_b128 v[190:193], v151 offset:33792
	ds_read_b128 v[194:197], v151 offset:34816
	ds_read_b128 v[198:201], v151 offset:35840
	ds_read_b128 v[202:205], v151 offset:36864
	ds_read_b128 v[206:209], v151 offset:37888
	ds_read_b128 v[210:213], v151 offset:38912
	ds_read_b128 v[214:217], v151 offset:39936
	global_load_lds_dwordx4 v[224:225], off
	v_lshl_add_u64 v[224:225], s[42:43], 0, v[130:131]
	s_mov_b32 m0, s52
	s_nop 0
	global_load_lds_dwordx4 v[224:225], off
	s_waitcnt vmcnt(8)
	s_waitcnt lgkmcnt(0)
	s_barrier
	v_mfma_f32_16x16x32_bf16 v[120:123], v[154:157], v[186:189], v[120:123]
	v_mfma_f32_16x16x32_bf16 v[116:119], v[162:165], v[186:189], v[116:119]
	v_mfma_f32_16x16x32_bf16 v[108:111], v[154:157], v[194:197], v[108:111]
	v_mfma_f32_16x16x32_bf16 v[100:103], v[162:165], v[194:197], v[100:103]
	v_mfma_f32_16x16x32_bf16 v[92:95], v[154:157], v[202:205], v[92:95]
	v_mfma_f32_16x16x32_bf16 v[84:87], v[162:165], v[202:205], v[84:87]
	v_mfma_f32_16x16x32_bf16 v[76:79], v[154:157], v[210:213], v[76:79]
	v_mfma_f32_16x16x32_bf16 v[68:71], v[162:165], v[210:213], v[68:71]
	v_mfma_f32_16x16x32_bf16 v[120:123], v[158:161], v[190:193], v[120:123]
	v_mfma_f32_16x16x32_bf16 v[116:119], v[166:169], v[190:193], v[116:119]
	v_mfma_f32_16x16x32_bf16 v[108:111], v[158:161], v[198:201], v[108:111]
	v_mfma_f32_16x16x32_bf16 v[100:103], v[166:169], v[198:201], v[100:103]
	v_mfma_f32_16x16x32_bf16 v[92:95], v[158:161], v[206:209], v[92:95]
	v_mfma_f32_16x16x32_bf16 v[84:87], v[166:169], v[206:209], v[84:87]
	v_mfma_f32_16x16x32_bf16 v[76:79], v[158:161], v[214:217], v[76:79]
	v_mfma_f32_16x16x32_bf16 v[68:71], v[166:169], v[214:217], v[68:71]
	v_mfma_f32_16x16x32_bf16 v[124:127], v[170:173], v[186:189], v[124:127]
	v_mfma_f32_16x16x32_bf16 v[112:115], v[178:181], v[186:189], v[112:115]
	v_mfma_f32_16x16x32_bf16 v[104:107], v[170:173], v[194:197], v[104:107]
	v_mfma_f32_16x16x32_bf16 v[96:99], v[178:181], v[194:197], v[96:99]
	v_mfma_f32_16x16x32_bf16 v[88:91], v[170:173], v[202:205], v[88:91]
	v_mfma_f32_16x16x32_bf16 v[80:83], v[178:181], v[202:205], v[80:83]
	v_mfma_f32_16x16x32_bf16 v[72:75], v[170:173], v[210:213], v[72:75]
	v_mfma_f32_16x16x32_bf16 v[64:67], v[178:181], v[210:213], v[64:67]
	v_mfma_f32_16x16x32_bf16 v[124:127], v[174:177], v[190:193], v[124:127]
	v_mfma_f32_16x16x32_bf16 v[112:115], v[182:185], v[190:193], v[112:115]
	v_mfma_f32_16x16x32_bf16 v[104:107], v[174:177], v[198:201], v[104:107]
	v_mfma_f32_16x16x32_bf16 v[96:99], v[182:185], v[198:201], v[96:99]
	v_mfma_f32_16x16x32_bf16 v[88:91], v[174:177], v[206:209], v[88:91]
	v_mfma_f32_16x16x32_bf16 v[80:83], v[182:185], v[206:209], v[80:83]
	v_mfma_f32_16x16x32_bf16 v[72:75], v[174:177], v[214:217], v[72:75]
	v_mfma_f32_16x16x32_bf16 v[64:67], v[182:185], v[214:217], v[64:67]
	s_barrier
; #define PG8_STAGE(bufoff, gbase, voff) do { _Pragma("unroll") for (int _i = 0; _i < 2; ++_i) \
;         __builtin_amdgcn_global_load_lds((const unsigned*)((const char*)(gbase) + (voff)[_i]), (PG8_LAS unsigned*)(lds + (bufoff) + ldsw + _i * 8192), 16, 0, 0); } while (0)
; #define PG8_LDA(dst, b, h) do { _Pragma("unroll") for (int m = 0; m < 4; ++m) _Pragma("unroll") for (int k = 0; k < 2; ++k) dst[m][k] = *(const PG8_LAS bf16x8*)(lds + PG8_SA(b, h) + aoff + m * 2048 + k * 1024); } while (0)
; #define PG8_MMA(ai, bj, At, Bt) do { __builtin_amdgcn_s_setprio(1); _Pragma("unroll") for (int m = 0; m < 4; ++m) _Pragma("unroll") for (int n = 0; n < 2; ++n) _Pragma("unroll") for (int k = 0; k < 2; ++k) \
;         acc[ai][bj][m][n] = __builtin_amdgcn_mfma_f32_16x16x32_bf16(Bt[n][k], At[m][k], acc[ai][bj][m][n], 0, 0, 0); __builtin_amdgcn_s_setprio(0); } while (0)
; #define PG8_WAIT_V(n) asm volatile("s_waitcnt vmcnt(" #n ")" ::: "memory")
; #define PG8_WAIT_L(n) asm volatile("s_waitcnt lgkmcnt(" #n ")" ::: "memory")
; #define PG8_BAR __builtin_amdgcn_s_barrier()
; #define PG8_SCHED __builtin_amdgcn_sched_barrier(0)
; template <class Epi, class Sched, bool ALIGN_EPI = false, bool SP2 = false>
; __device__ __forceinline__ void gemm_phase(PG8_LAS unsigned char* lds, const Gemm g, const Sched& S, const Epi& E) {
;     ...
;             PG8_LDA(At, 1, 1); PG8_STAGE(PG8_SB(1, 0), b3, voffB); PG8_STAGE(PG8_SB(1, 1), b3 + hstep, voffB); PG8_STAGE(PG8_SA(1, 0), a3, voffA);
;             PG8_WAIT_V(8); PG8_WAIT_L(0); PG8_BAR; PG8_MMA(1, 0, At, B0); PG8_MMA(1, 1, At, B1); PG8_BAR; PG8_SCHED;
	s_add_i32 s42, s69, s48
	v_lshl_add_u64 v[144:145], v[144:145], 0, s[14:15]
	s_mov_b32 m0, s42
	ds_read_b128 v[186:189], v151 offset:49152
	ds_read_b128 v[190:193], v151 offset:50176
	ds_read_b128 v[194:197], v151 offset:51200
	ds_read_b128 v[198:201], v151 offset:52224
	ds_read_b128 v[202:205], v151 offset:53248
	ds_read_b128 v[206:209], v151 offset:54272
	ds_read_b128 v[210:213], v151 offset:55296
	ds_read_b128 v[214:217], v151 offset:56320
	global_load_lds_dwordx4 v[144:145], off
	s_add_i32 m0, s42, 0x2000
	s_add_u32 s40, s40, 0x40080
	v_lshl_add_u64 v[144:145], v[218:219], 0, s[14:15]
	s_addc_u32 s41, s41, 0
	s_add_i32 s42, s70, s48
	global_load_lds_dwordx4 v[144:145], off
	v_lshl_add_u64 v[144:145], s[40:41], 0, v[132:133]
	s_mov_b32 m0, s42
	s_nop 0
	global_load_lds_dwordx4 v[144:145], off
	v_lshl_add_u64 v[144:145], s[40:41], 0, v[128:129]
	s_add_i32 m0, s42, 0x2000
	s_nop 0
	global_load_lds_dwordx4 v[144:145], off
	v_lshl_add_u64 v[144:145], v[220:221], 0, s[14:15]
	s_mov_b32 m0, s53
	s_nop 0
	global_load_lds_dwordx4 v[144:145], off
	v_lshl_add_u64 v[144:145], v[222:223], 0, s[14:15]
	s_mov_b32 m0, s54
	s_nop 0
	global_load_lds_dwordx4 v[144:145], off
	s_waitcnt vmcnt(8)
	s_waitcnt lgkmcnt(0)
	s_barrier
	v_mfma_f32_16x16x32_bf16 v[60:63], v[154:157], v[186:189], v[60:63]
	v_mfma_f32_16x16x32_bf16 v[52:55], v[162:165], v[186:189], v[52:55]
	v_mfma_f32_16x16x32_bf16 v[44:47], v[154:157], v[194:197], v[44:47]
	v_mfma_f32_16x16x32_bf16 v[36:39], v[162:165], v[194:197], v[36:39]
	v_mfma_f32_16x16x32_bf16 v[28:31], v[154:157], v[202:205], v[28:31]
	v_mfma_f32_16x16x32_bf16 v[20:23], v[162:165], v[202:205], v[20:23]
	v_mfma_f32_16x16x32_bf16 v[12:15], v[154:157], v[210:213], v[12:15]
	v_mfma_f32_16x16x32_bf16 v[4:7], v[162:165], v[210:213], v[4:7]
	v_mfma_f32_16x16x32_bf16 v[60:63], v[158:161], v[190:193], v[60:63]
	v_mfma_f32_16x16x32_bf16 v[52:55], v[166:169], v[190:193], v[52:55]
	v_mfma_f32_16x16x32_bf16 v[44:47], v[158:161], v[198:201], v[44:47]
	v_mfma_f32_16x16x32_bf16 v[36:39], v[166:169], v[198:201], v[36:39]
	v_mfma_f32_16x16x32_bf16 v[28:31], v[158:161], v[206:209], v[28:31]
	v_mfma_f32_16x16x32_bf16 v[20:23], v[166:169], v[206:209], v[20:23]
	v_mfma_f32_16x16x32_bf16 v[12:15], v[158:161], v[214:217], v[12:15]
	v_mfma_f32_16x16x32_bf16 v[4:7], v[166:169], v[214:217], v[4:7]
	v_mfma_f32_16x16x32_bf16 v[56:59], v[170:173], v[186:189], v[56:59]
	v_mfma_f32_16x16x32_bf16 v[48:51], v[178:181], v[186:189], v[48:51]
	v_mfma_f32_16x16x32_bf16 v[40:43], v[170:173], v[194:197], v[40:43]
	v_mfma_f32_16x16x32_bf16 v[32:35], v[178:181], v[194:197], v[32:35]
	v_mfma_f32_16x16x32_bf16 v[24:27], v[170:173], v[202:205], v[24:27]
	v_mfma_f32_16x16x32_bf16 v[16:19], v[178:181], v[202:205], v[16:19]
	v_mfma_f32_16x16x32_bf16 v[8:11], v[170:173], v[210:213], v[8:11]
	v_mfma_f32_16x16x32_bf16 v[0:3], v[178:181], v[210:213], v[0:3]
	v_mfma_f32_16x16x32_bf16 v[56:59], v[174:177], v[190:193], v[56:59]
	v_mfma_f32_16x16x32_bf16 v[48:51], v[182:185], v[190:193], v[48:51]
	v_mfma_f32_16x16x32_bf16 v[40:43], v[174:177], v[198:201], v[40:43]
	v_mfma_f32_16x16x32_bf16 v[32:35], v[182:185], v[198:201], v[32:35]
	v_mfma_f32_16x16x32_bf16 v[24:27], v[174:177], v[206:209], v[24:27]
	v_mfma_f32_16x16x32_bf16 v[16:19], v[182:185], v[206:209], v[16:19]
	v_mfma_f32_16x16x32_bf16 v[8:11], v[174:177], v[214:217], v[8:11]
	v_mfma_f32_16x16x32_bf16 v[0:3], v[182:185], v[214:217], v[0:3]
	s_barrier
	s_add_i32 s68, s68, 2
	s_add_u32 s38, s38, 0x100
	s_addc_u32 s39, s39, 0
	s_add_u32 s66, s66, 0x100
	s_addc_u32 s67, s67, 0

; #define LAS __attribute__((address_space(3)))
; __device__ __forceinline__ void run_phase(const int ph, const Args& a, LAS unsigned char* lds, unsigned char* ldsg, const bool dummy = false) {
;     const int tid = threadIdx.x, lane = tid & 63, wave = __builtin_amdgcn_readfirstlane(tid >> 6);
;     const int G = gridDim.x, bx = blockIdx.x;
;     const int gw = bx * 8 + wave, NGW = G * 8;
;     const int ngrp = (G == 256) ? 8 : 1, gsize = G / ngrp, gx = bx % ngrp, gj = bx / ngrp;
;     unsigned char* ws = a.ws;
;     pg8::rss_t* RS = (pg8::rss_t*)(ws + WS_ROWSS);
;     bf16* HB = (bf16*)(ws + WS_HB);
;     const size_t rpg = (size_t)(M / ngrp), RPG = (256 * MiB) / ngrp;
;     unsigned char* reg = ws + WS_ACT + (size_t)gx * RPG;
;     bf16* ACT = (bf16*)(reg - (size_t)gx * rpg * FF * 2);
;     bf16* QX = (bf16*)(reg - (size_t)gx * rpg * D * 2); bf16* KX = QX + rpg * D; bf16* VX = QX + 2 * rpg * D; bf16* OB = QX + 3 * rpg * D;
.LBB0_1347:
	s_waitcnt lgkmcnt(0)
	s_setprio 0
	s_cmp_lt_i32 s6, 8
	s_cselect_b64 s[4:5], -1, 0
	s_cmp_gt_i32 s7, 7
	s_cselect_b64 s[8:9], -1, 0
	s_and_b64 s[4:5], s[4:5], s[8:9]
	s_andn2_b64 vcc, exec, s[4:5]
	s_cbranch_vccnz .LBB0_1540
	s_and_b64 s[4:5], s[30:31], exec
	s_cselect_b32 s14, 8, 1
	v_cvt_f32_ubyte0_e32 v0, s14
	v_rcp_iflag_f32_e32 v0, v0
	s_sub_i32 s8, 0, s14
	s_load_dwordx2 s[4:5], s[0:1], 0xd8
	s_ashr_i32 s3, s2, 31
	v_mul_f32_e32 v0, 0x4f7ffffe, v0
	v_cvt_u32_f32_e32 v0, v0
	s_abs_i32 s15, s2
	v_readfirstlane_b32 s20, v242
	v_readfirstlane_b32 s9, v0
	s_mul_i32 s8, s8, s9
	s_mul_hi_u32 s8, s9, s8
	s_add_i32 s12, s9, s8
	s_cmpk_lt_i32 s2, 0x200
	s_cselect_b64 s[8:9], -1, 0
	s_cmpk_gt_i32 s2, 0x1ff
	s_mul_hi_u32 s16, s15, s12
	s_cbranch_scc1 .LBB0_1351
	s_lshr_b32 s12, s3, 29
	s_add_i32 s17, s2, s12
	s_and_b32 s12, s17, -8
	s_sub_i32 s18, s2, s12
	s_cmp_gt_i32 s18, -1
	s_cbranch_scc0 .LBB0_1391
	s_lshl_b32 s19, s18, 6
	s_cbranch_execz .LBB0_1392
	s_branch .LBB0_1393

; #define PG8_STAGE(bufoff, gbase, voff) do { _Pragma("unroll") for (int _i = 0; _i < 2; ++_i) \
;         __builtin_amdgcn_global_load_lds((const unsigned*)((const char*)(gbase) + (voff)[_i]), (PG8_LAS unsigned*)(lds + (bufoff) + ldsw + _i * 8192), 16, 0, 0); } while (0)
; #define PG8_WAIT_V(n) asm volatile("s_waitcnt vmcnt(" #n ")" ::: "memory")
; #define PG8_BAR __builtin_amdgcn_s_barrier()
; template <class Epi, class Sched, bool ALIGN_EPI = false, bool SP2 = false>
; __device__ __forceinline__ void gemm_phase(PG8_LAS unsigned char* lds, const Gemm g, const Sched& S, const Epi& E) {
;     ...
;         if (wr == 1) PG8_BAR;
;         PG8_WAIT_V(4); PG8_BAR;
;         PG8_STAGE(PG8_SB(1, 0), cB + kstep, voffB); PG8_STAGE(PG8_SA(1, 0), cA + kstep, voffA); PG8_STAGE(PG8_SB(1, 1), cB + hstep + kstep, voffB);
;         PG8_WAIT_V(6); PG8_BAR;
;     }
.LBB0_1354:
	s_add_u32 s14, s4, 0x6000000
	s_addc_u32 s15, s5, 0
	s_add_u32 s16, s4, 0x5c0000
	s_addc_u32 s17, s5, 0
	s_lshl_b32 s4, s7, 5
	s_mov_b64 s[18:19], 0x80
	s_and_b32 s7, s4, 0x60
	s_add_i32 m0, s45, 0x18000
	v_lshl_add_u64 v[6:7], v[6:7], 0, s[18:19]
	s_lshl_b32 s8, s6, 13
	s_lshl_b32 s9, s7, 7
	s_waitcnt vmcnt(2)
	s_barrier
	global_load_lds_dwordx4 v[6:7], off
	v_lshl_add_u64 v[4:5], v[4:5], 0, s[18:19]
	s_add_i32 m0, s45, 0x1a000
	s_add_i32 s50, s45, 0x8000
	s_add_i32 s51, s45, 0xa000
	global_load_lds_dwordx4 v[4:5], off
	v_lshl_add_u64 v[0:1], v[0:1], 0, s[18:19]
	s_mov_b32 m0, s50
	s_add_u32 s4, s36, 0xb0080
	global_load_lds_dwordx4 v[0:1], off
	v_lshl_add_u64 v[0:1], v[2:3], 0, s[18:19]
	s_mov_b32 m0, s51
	s_addc_u32 s5, s37, 0
	global_load_lds_dwordx4 v[0:1], off
	s_add_i32 m0, s45, 0x1c000
	v_lshl_add_u64 v[0:1], s[4:5], 0, v[194:195]
	global_load_lds_dwordx4 v[0:1], off
	v_lshl_add_u64 v[0:1], s[4:5], 0, v[198:199]
	s_add_i32 m0, s45, 0x1e000
	v_lshlrev_b32_e32 v4, 6, v242
	global_load_lds_dwordx4 v[0:1], off
	v_bfe_u32 v0, v242, 4, 2
	v_and_b32_e32 v1, 15, v242
	v_lshlrev_b32_e32 v2, 4, v0
	s_movk_i32 s4, 0x3c0
	v_lshl_or_b32 v243, s6, 6, v1
	v_lshl_or_b32 v1, v1, 6, v2
	v_lshlrev_b32_e32 v3, 2, v242
	v_and_or_b32 v2, v4, s4, v2
	v_cmp_eq_u32_e64 s[4:5], 0, v0
	v_lshl_or_b32 v245, v0, 3, s7
	v_add_u16_e32 v0, v8, v9
	v_and_b32_e32 v3, 32, v3
	s_waitcnt vmcnt(6)
	s_cmpk_lt_u32 s20, 0x100
	v_lshrrev_b16_e32 v0, 1, v0
	v_bitop3_b32 v1, v1, s8, v3 bitop3:0xde
	v_bitop3_b32 v244, s9, v2, v3 bitop3:0xf6
	s_cselect_b64 s[20:21], -1, 0
	v_add_lshl_u32 v200, v10, v0, 1
	v_add_lshl_u32 v202, v11, v0, 1
	s_add_i32 s53, 0, 0x10000
	s_add_i32 s54, 0, 0x14000
	v_mbcnt_lo_u32_b32 v0, -1, 0
	s_ashr_i32 s52, s61, 31
	v_mov_b32_e32 v201, v195
	v_mov_b32_e32 v203, v195
	v_mov_b64_e32 v[204:205], 0x1ff
	v_add_u32_e32 v246, s53, v244
	v_add_u32_e32 v247, s54, v244
	v_add_u32_e32 v248, 0, v1
	v_mbcnt_hi_u32_b32 v249, -1, v0
	s_barrier
	v_readfirstlane_b32 s99, v242
	s_nop 3
	s_cmp_ge_u32 s99, 0x100
	s_cbranch_scc1 .Lprio_skip_5
	s_setprio 1
.Lprio_skip_5:
	s_branch .LBB0_1357
.LBB0_1355:
	s_mov_b64 s[6:7], 0

; #define PG8_STAGE(bufoff, gbase, voff) do { _Pragma("unroll") for (int _i = 0; _i < 2; ++_i) \
;         __builtin_amdgcn_global_load_lds((const unsigned*)((const char*)(gbase) + (voff)[_i]), (PG8_LAS unsigned*)(lds + (bufoff) + ldsw + _i * 8192), 16, 0, 0); } while (0)
; #define PG8_WAIT_V(n) asm volatile("s_waitcnt vmcnt(" #n ")" ::: "memory")
; #define PG8_BAR __builtin_amdgcn_s_barrier()
; template <class Epi, class Sched, bool ALIGN_EPI = false, bool SP2 = false>
; __device__ __forceinline__ void gemm_phase(PG8_LAS unsigned char* lds, const Gemm g, const Sched& S, const Epi& E) {
;     ...
;     const char* cA = (const char*)g.A + (size_t)cur.pm * tstep; const char* cB = (const char*)g.Bt + (size_t)cur.pn * tstep;
;     S.a_ready(cur);
;     if constexpr (SP2) {
;         PG8_STAGE(PG8_SB(0, 0), cB, voffB); PG8_STAGE(PG8_SB(0, 1), cB + hstep, voffB); PG8_STAGE(PG8_SA(0, 0), cA, voffA); PG8_STAGE(PG8_SA(0, 1), cA + hstep, voffA);
;         if (wr == 1) PG8_BAR;
;         PG8_WAIT_V(2); PG8_BAR;
;         PG8_STAGE(PG8_SB(1, 0), cB + kstep, voffB); PG8_STAGE(PG8_SA(1, 0), cA + kstep, voffA); PG8_STAGE(PG8_SB(1, 1), cB + hstep + kstep, voffB);
;         PG8_WAIT_V(6); PG8_BAR;
;     } else {
;         PG8_STAGE(PG8_SB(0, 0), cB, voffB); PG8_STAGE(PG8_SA(0, 0), cA, voffA); PG8_STAGE(PG8_SB(0, 1), cB + hstep, voffB); PG8_STAGE(PG8_SA(0, 1), cA + hstep, voffA);
;         if (wr == 1) PG8_BAR;
;         PG8_WAIT_V(4); PG8_BAR;
;         PG8_STAGE(PG8_SB(1, 0), cB + kstep, voffB); PG8_STAGE(PG8_SA(1, 0), cA + kstep, voffA); PG8_STAGE(PG8_SB(1, 1), cB + hstep + kstep, voffB);
;         PG8_WAIT_V(6); PG8_BAR;
;     }
.LBB0_1540:
	s_waitcnt lgkmcnt(0)
	s_setprio 0
	s_cmp_lt_i32 s6, 9
	s_cselect_b64 s[4:5], -1, 0
	s_cmp_gt_i32 s7, 8
	s_cselect_b64 s[8:9], -1, 0
	s_and_b64 s[4:5], s[4:5], s[8:9]
	s_andn2_b64 vcc, exec, s[4:5]
	s_cbranch_vccnz .LBB0_1703
	s_and_b64 s[4:5], s[30:31], exec
	s_cselect_b32 s8, 8, 1
	v_cvt_f32_ubyte0_e32 v0, s8
	v_rcp_iflag_f32_e32 v0, v0
	v_readfirstlane_b32 s17, v242
	s_cmpk_gt_i32 s2, 0xaff
	v_mul_f32_e32 v0, 0x4f7ffffe, v0
	v_cvt_u32_f32_e32 v0, v0
	s_nop 0
	v_readfirstlane_b32 s12, v0
	s_cbranch_scc1 .LBB0_1557
	v_lshrrev_b32_e32 v0, 5, v242
	v_lshrrev_b32_e32 v2, 1, v242
	s_sub_i32 s6, 0, s8
	s_load_dwordx2 s[4:5], s[0:1], 0xd8
	v_and_b32_e32 v0, 4, v0
	v_bfe_u32 v1, v242, 2, 2
	v_and_b32_e32 v11, 24, v2
	s_mul_i32 s6, s6, s12
	v_or3_b32 v0, v0, v1, v11
	v_lshlrev_b32_e32 v1, 4, v242
	s_mul_hi_u32 s6, s12, s6
	v_add_u32_e32 v8, 0x2000, v1
	s_add_i32 s15, s12, s6
	v_lshrrev_b32_e32 v2, 7, v8
	s_movk_i32 s6, 0xe0
	v_and_b32_e32 v4, 32, v242
	s_ashr_i32 s3, s2, 31
	s_abs_i32 s9, s2
	s_lshr_b32 s14, s17, 6
	v_and_or_b32 v3, v2, s6, v0
	v_bitop3_b32 v9, v1, v4, 48 bitop3:0x6c
	v_and_b32_e32 v10, 64, v242
	v_bfe_u32 v12, v242, 2, 4
	s_movk_i32 s6, 0xf0
	s_waitcnt lgkmcnt(0)
	s_add_u32 s44, s4, 0x6000000
	v_or_b32_e32 v1, v9, v10
	v_and_or_b32 v2, v2, s6, v12
	s_addc_u32 s45, s5, 0
	v_lshl_or_b32 v130, v2, 11, v1
	v_lshrrev_b32_e32 v2, 3, v242
	s_movk_i32 s6, 0x60
	s_add_u32 s46, s4, 0x2a00000
	v_and_or_b32 v0, v2, s6, v0
	s_movk_i32 s6, 0x70
	s_addc_u32 s47, s5, 0
	v_lshl_or_b32 v132, v0, 11, v1
	v_and_or_b32 v0, v2, s6, v12
	s_lshr_b32 s6, s3, 29
	s_add_i32 s6, s2, s6
	s_ashr_i32 s7, s6, 3
	s_and_b32 s6, s6, -8
	s_lshr_b32 s18, s17, 8
	s_lshl_b32 s48, s14, 10
	s_sub_i32 s6, s2, s6
	s_cmp_lt_i32 s6, 0
	s_movk_i32 s49, 0x161
	s_cselect_b32 s12, s49, 0x160
	s_mul_i32 s6, s12, s6
	s_add_i32 s6, s6, s7
	s_mul_hi_i32 s7, s6, 0x2e8ba2e9
	s_lshr_b32 s12, s7, 31
	s_ashr_i32 s7, s7, 5
	s_add_i32 s7, s7, s12
	s_lshl_b32 s12, s7, 3
	s_mulk_i32 s7, 0xb0
	s_sub_i32 s6, s6, s7
	s_sext_i32_i16 s7, s6
	s_bfe_u32 s7, s7, 0x3001c
	s_add_i32 s7, s6, s7
	s_sext_i32_i16 s13, s7
	s_and_b32 s7, s7, 0xfff8
	s_sub_i32 s6, s6, s7
	s_sext_i32_i16 s6, s6
	s_lshr_b32 s16, s13, 3
	s_add_i32 s36, s12, s6
	s_ashr_i32 s37, s36, 31
	s_bfe_i64 s[12:13], s[16:17], 0x100000
	s_lshl_b64 s[6:7], s[36:37], 19
	s_lshl_b64 s[12:13], s[12:13], 19
	s_add_u32 s40, s46, s12
	s_addc_u32 s41, s47, s13
	s_add_i32 s37, s48, 0
	s_add_i32 m0, s37, 0x10000
	v_lshl_or_b32 v128, v3, 11, v1
	global_load_lds_dwordx4 v132, s[40:41]
	s_add_i32 m0, s37, 0x12000
	s_add_u32 s12, s40, 0x40000
	global_load_lds_dwordx4 v128, s[40:41]
	s_addc_u32 s13, s41, 0
	s_add_i32 m0, s37, 0x14000
	v_lshl_or_b32 v134, v0, 11, v1
	global_load_lds_dwordx4 v132, s[12:13]
	s_add_i32 m0, s37, 0x16000
	s_add_u32 s38, s44, s6
	s_addc_u32 s39, s45, s7
	s_add_i32 s50, s37, 0x2000
	global_load_lds_dwordx4 v128, s[12:13]
	s_mov_b32 m0, s37
	s_add_u32 s6, s38, 0x40000
	global_load_lds_dwordx4 v134, s[38:39]
	s_mov_b32 m0, s50
	s_addc_u32 s7, s39, 0
	s_add_i32 s51, s37, 0x4000
	global_load_lds_dwordx4 v130, s[38:39]
	s_mov_b32 m0, s51
	s_add_i32 s52, s37, 0x6000
	global_load_lds_dwordx4 v134, s[6:7]
	s_mov_b32 m0, s52
	v_mov_b32_e32 v133, 0
	global_load_lds_dwordx4 v130, s[6:7]
	v_mov_b32_e32 v129, v133
	v_mov_b32_e32 v135, v133
	v_mov_b32_e32 v131, v133
	s_cmp_eq_u32 s18, 1
	s_mul_hi_u32 s12, s9, s15
	v_lshl_add_u64 v[6:7], s[40:41], 0, v[132:133]
	v_lshl_add_u64 v[4:5], s[40:41], 0, v[128:129]
	v_lshl_add_u64 v[0:1], s[38:39], 0, v[134:135]
	s_cselect_b64 s[6:7], -1, 0
	s_cmp_lg_u32 s18, 1
	v_lshl_add_u64 v[2:3], s[38:39], 0, v[130:131]
	s_cbranch_scc1 .LBB0_1544
	s_barrier
.LBB0_1544:
	s_mul_i32 s12, s12, s8
	s_sub_i32 s9, s9, s12
	s_sub_i32 s12, s9, s8
	s_cmp_ge_u32 s9, s8
	s_cselect_b32 s9, s12, s9
	s_sub_i32 s12, s9, s8
	s_cmp_ge_u32 s9, s8
	s_cselect_b32 s8, s12, s9
	s_xor_b32 s8, s8, s3
	s_sub_i32 s8, s8, s3
	s_ashr_i32 s9, s8, 31
	s_and_b64 s[12:13], s[30:31], exec
	s_cselect_b32 s12, 25, 28
	s_lshl_b64 s[12:13], s[8:9], s12
	s_add_u32 s15, s4, s12
	s_addc_u32 s19, s5, s13
	s_and_b64 s[12:13], s[30:31], exec
	s_cselect_b32 s12, 12, 15
	s_lshl_b64 s[8:9], s[8:9], s12
	s_mul_hi_u32 s12, s8, 0xffffea00
	s_sub_i32 s12, s12, s8
	s_mulk_i32 s9, 0xea00
	s_add_i32 s12, s12, s9
	s_mulk_i32 s8, 0xea00
	s_add_u32 s8, s15, s8
	s_addc_u32 s9, s19, s12
	s_add_u32 s8, s8, 0xa000000
	s_addc_u32 s9, s9, 0
	s_add_u32 s12, s4, 0x5c0000
	s_addc_u32 s13, s5, 0
	s_lshl_b32 s4, s14, 5
	s_mov_b64 s[14:15], 0x80
	s_and_b32 s20, s4, 0x60
	s_add_i32 m0, s37, 0x18000
	v_lshl_add_u64 v[6:7], v[6:7], 0, s[14:15]
	s_lshl_b32 s19, s18, 13
	s_lshl_b32 s21, s20, 7
	s_waitcnt vmcnt(2)
	s_barrier
	global_load_lds_dwordx4 v[6:7], off
	v_lshl_add_u64 v[4:5], v[4:5], 0, s[14:15]
	s_add_i32 m0, s37, 0x1a000
	s_add_i32 s53, s37, 0x8000
	s_add_i32 s54, s37, 0xa000
	global_load_lds_dwordx4 v[4:5], off
	v_lshl_add_u64 v[0:1], v[0:1], 0, s[14:15]
	s_mov_b32 m0, s53
	s_add_u32 s4, s40, 0x40080
	global_load_lds_dwordx4 v[0:1], off
	v_lshl_add_u64 v[0:1], v[2:3], 0, s[14:15]
	s_mov_b32 m0, s54
	s_addc_u32 s5, s41, 0
	global_load_lds_dwordx4 v[0:1], off
	s_add_i32 m0, s37, 0x1c000
	v_lshl_add_u64 v[0:1], s[4:5], 0, v[132:133]
	global_load_lds_dwordx4 v[0:1], off
	v_lshl_add_u64 v[0:1], s[4:5], 0, v[128:129]
	s_add_i32 m0, s37, 0x1e000
	v_lshlrev_b32_e32 v2, 2, v242
	global_load_lds_dwordx4 v[0:1], off
	v_and_b32_e32 v0, 15, v242
	v_lshlrev_b32_e32 v1, 1, v11
	v_lshlrev_b32_e32 v3, 6, v242
	s_movk_i32 s4, 0x3c0
	v_lshl_or_b32 v146, s18, 6, v0
	v_lshl_or_b32 v0, v0, 6, v1
	v_and_b32_e32 v2, 32, v2
	v_and_or_b32 v1, v3, s4, v1
	v_bitop3_b32 v147, s21, v1, v2 bitop3:0xf6
	v_lshlrev_b32_e32 v1, 8, v242
	v_bitop3_b32 v0, v0, s19, v2 bitop3:0xde
	v_and_b32_e32 v1, 0x38000, v1
	v_lshlrev_b32_e32 v2, 11, v12
	v_or3_b32 v1, v9, v1, v2
	v_add_u32_e32 v136, v1, v10
	v_lshlrev_b32_e32 v1, 4, v8
	s_waitcnt vmcnt(6)
	s_cmpk_lt_u32 s17, 0x100
	v_and_b32_e32 v1, 0x78000, v1
	s_sext_i32_i16 s63, s16
	s_cselect_b64 s[16:17], -1, 0
	v_or3_b32 v1, v9, v1, v2
	s_add_i32 s57, 0, 0x10000
	s_add_i32 s58, 0, 0x14000
	s_mov_b32 s55, 0
	s_ashr_i32 s56, s61, 31
	v_or_b32_e32 v148, s20, v11
	v_mov_b32_e32 v137, v133
	v_add_u32_e32 v138, v1, v10
	v_mov_b32_e32 v139, v133
	v_mov_b64_e32 v[140:141], 0xb00
	v_mov_b64_e32 v[142:143], 0xaff
	v_add_u32_e32 v149, s57, v147
	v_add_u32_e32 v150, s58, v147
	v_add_u32_e32 v151, 0, v0
	v_mov_b32_e32 v152, 0x358637bd
	s_movk_i32 s59, 0x1600
	s_barrier
	v_readfirstlane_b32 s99, v242
	s_nop 3
	s_cmp_ge_u32 s99, 0x100
	s_cbranch_scc1 .Lprio_skip_6
	s_setprio 1
.Lprio_skip_6:
	s_branch .LBB0_1547
.LBB0_1545:
	s_mov_b64 s[4:5], 0

; #define LAS __attribute__((address_space(3)))
; __device__ __forceinline__ void run_phase(const int ph, const Args& a, LAS unsigned char* lds, unsigned char* ldsg, const bool dummy = false) {
;     const int tid = threadIdx.x, lane = tid & 63, wave = __builtin_amdgcn_readfirstlane(tid >> 6);
;     const int G = gridDim.x, bx = blockIdx.x;
;     const int gw = bx * 8 + wave, NGW = G * 8;
;     const int ngrp = (G == 256) ? 8 : 1, gsize = G / ngrp, gx = bx % ngrp, gj = bx / ngrp;
;     unsigned char* ws = a.ws;
;     pg8::rss_t* RS = (pg8::rss_t*)(ws + WS_ROWSS);
;     bf16* HB = (bf16*)(ws + WS_HB);
;     const size_t rpg = (size_t)(M / ngrp), RPG = (256 * MiB) / ngrp;
;     unsigned char* reg = ws + WS_ACT + (size_t)gx * RPG;
;     bf16* ACT = (bf16*)(reg - (size_t)gx * rpg * FF * 2);
;     bf16* QX = (bf16*)(reg - (size_t)gx * rpg * D * 2); bf16* KX = QX + rpg * D; bf16* VX = QX + 2 * rpg * D; bf16* OB = QX + 3 * rpg * D;
.LBB0_1703:
	s_waitcnt lgkmcnt(0)
	s_setprio 0
	s_cmp_lt_i32 s6, 10
	s_cselect_b64 s[4:5], -1, 0
	s_cmp_gt_i32 s7, 9
	s_cselect_b64 s[8:9], -1, 0
	s_and_b64 s[4:5], s[4:5], s[8:9]
	s_andn2_b64 vcc, exec, s[4:5]
	s_cbranch_vccnz .LBB0_1896
	s_and_b64 s[4:5], s[30:31], exec
	s_cselect_b32 s14, 8, 1
	v_cvt_f32_ubyte0_e32 v0, s14
	v_rcp_iflag_f32_e32 v0, v0
	s_sub_i32 s8, 0, s14
	s_load_dwordx2 s[4:5], s[0:1], 0xd8
	s_ashr_i32 s3, s2, 31
	v_mul_f32_e32 v0, 0x4f7ffffe, v0
	v_cvt_u32_f32_e32 v0, v0
	s_abs_i32 s15, s2
	v_readfirstlane_b32 s20, v242
	v_readfirstlane_b32 s9, v0
	s_mul_i32 s8, s8, s9
	s_mul_hi_u32 s8, s9, s8
	s_add_i32 s12, s9, s8
	s_cmpk_lt_i32 s2, 0x200
	s_cselect_b64 s[8:9], -1, 0
	s_cmpk_gt_i32 s2, 0x1ff
	s_mul_hi_u32 s16, s15, s12
	s_cbranch_scc1 .LBB0_1707
	s_lshr_b32 s12, s3, 29
	s_add_i32 s17, s2, s12
	s_and_b32 s12, s17, -8
	s_sub_i32 s18, s2, s12
	s_cmp_gt_i32 s18, -1
	s_cbranch_scc0 .LBB0_1747
	s_lshl_b32 s19, s18, 6
	s_cbranch_execz .LBB0_1748
	s_branch .LBB0_1749

; #define PG8_STAGE(bufoff, gbase, voff) do { _Pragma("unroll") for (int _i = 0; _i < 2; ++_i) \
;         __builtin_amdgcn_global_load_lds((const unsigned*)((const char*)(gbase) + (voff)[_i]), (PG8_LAS unsigned*)(lds + (bufoff) + ldsw + _i * 8192), 16, 0, 0); } while (0)
; #define PG8_WAIT_V(n) asm volatile("s_waitcnt vmcnt(" #n ")" ::: "memory")
; #define PG8_BAR __builtin_amdgcn_s_barrier()
; template <class Epi, class Sched, bool ALIGN_EPI = false, bool SP2 = false>
; __device__ __forceinline__ void gemm_phase(PG8_LAS unsigned char* lds, const Gemm g, const Sched& S, const Epi& E) {
;     ...
;         if (wr == 1) PG8_BAR;
;         PG8_WAIT_V(4); PG8_BAR;
;         PG8_STAGE(PG8_SB(1, 0), cB + kstep, voffB); PG8_STAGE(PG8_SA(1, 0), cA + kstep, voffA); PG8_STAGE(PG8_SB(1, 1), cB + hstep + kstep, voffB);
;         PG8_WAIT_V(6); PG8_BAR;
;     }
.LBB0_1710:
	s_add_u32 s14, s4, 0x6000000
	s_addc_u32 s15, s5, 0
	s_add_u32 s16, s4, 0x600000
	s_addc_u32 s17, s5, 0
	s_lshl_b32 s4, s7, 5
	s_mov_b64 s[18:19], 0x80
	s_and_b32 s7, s4, 0x60
	s_add_i32 m0, s45, 0x18000
	v_lshl_add_u64 v[6:7], v[6:7], 0, s[18:19]
	s_lshl_b32 s8, s6, 13
	s_lshl_b32 s9, s7, 7
	s_waitcnt vmcnt(2)
	s_barrier
	global_load_lds_dwordx4 v[6:7], off
	v_lshl_add_u64 v[4:5], v[4:5], 0, s[18:19]
	s_add_i32 m0, s45, 0x1a000
	s_add_i32 s50, s45, 0x8000
	s_add_i32 s51, s45, 0xa000
	global_load_lds_dwordx4 v[4:5], off
	v_lshl_add_u64 v[0:1], v[0:1], 0, s[18:19]
	s_mov_b32 m0, s50
	s_add_u32 s4, s36, 0xb0080
	global_load_lds_dwordx4 v[0:1], off
	v_lshl_add_u64 v[0:1], v[2:3], 0, s[18:19]
	s_mov_b32 m0, s51
	s_addc_u32 s5, s37, 0
	global_load_lds_dwordx4 v[0:1], off
	s_add_i32 m0, s45, 0x1c000
	v_lshl_add_u64 v[0:1], s[4:5], 0, v[194:195]
	global_load_lds_dwordx4 v[0:1], off
	v_lshl_add_u64 v[0:1], s[4:5], 0, v[198:199]
	s_add_i32 m0, s45, 0x1e000
	v_lshlrev_b32_e32 v4, 6, v242
	global_load_lds_dwordx4 v[0:1], off
	v_bfe_u32 v0, v242, 4, 2
	v_and_b32_e32 v1, 15, v242
	v_lshlrev_b32_e32 v2, 4, v0
	s_movk_i32 s4, 0x3c0
	v_lshl_or_b32 v243, s6, 6, v1
	v_lshl_or_b32 v1, v1, 6, v2
	v_lshlrev_b32_e32 v3, 2, v242
	v_and_or_b32 v2, v4, s4, v2
	v_cmp_eq_u32_e64 s[4:5], 0, v0
	v_lshl_or_b32 v245, v0, 3, s7
	v_add_u16_e32 v0, v8, v9
	v_and_b32_e32 v3, 32, v3
	s_waitcnt vmcnt(6)
	s_cmpk_lt_u32 s20, 0x100
	v_lshrrev_b16_e32 v0, 1, v0
	v_bitop3_b32 v1, v1, s8, v3 bitop3:0xde
	v_bitop3_b32 v244, s9, v2, v3 bitop3:0xf6
	s_cselect_b64 s[20:21], -1, 0
	v_add_lshl_u32 v200, v10, v0, 1
	v_add_lshl_u32 v202, v11, v0, 1
	s_add_i32 s53, 0, 0x10000
	s_add_i32 s54, 0, 0x14000
	v_mbcnt_lo_u32_b32 v0, -1, 0
	s_ashr_i32 s52, s61, 31
	v_mov_b32_e32 v201, v195
	v_mov_b32_e32 v203, v195
	v_mov_b64_e32 v[204:205], 0x1ff
	v_add_u32_e32 v246, s53, v244
	v_add_u32_e32 v247, s54, v244
	v_add_u32_e32 v248, 0, v1
	v_mbcnt_hi_u32_b32 v249, -1, v0
	s_barrier
	v_readfirstlane_b32 s99, v242
	s_nop 3
	s_cmp_ge_u32 s99, 0x100
	s_cbranch_scc1 .Lprio_skip_7
	s_setprio 1
.Lprio_skip_7:
	s_branch .LBB0_1713
.LBB0_1711:
	s_mov_b64 s[6:7], 0

; #define PG8_STAGE(bufoff, gbase, voff) do { _Pragma("unroll") for (int _i = 0; _i < 2; ++_i) \
;         __builtin_amdgcn_global_load_lds((const unsigned*)((const char*)(gbase) + (voff)[_i]), (PG8_LAS unsigned*)(lds + (bufoff) + ldsw + _i * 8192), 16, 0, 0); } while (0)
; #define PG8_WAIT_V(n) asm volatile("s_waitcnt vmcnt(" #n ")" ::: "memory")
; #define PG8_BAR __builtin_amdgcn_s_barrier()
; template <class Epi, class Sched, bool ALIGN_EPI = false, bool SP2 = false>
; __device__ __forceinline__ void gemm_phase(PG8_LAS unsigned char* lds, const Gemm g, const Sched& S, const Epi& E) {
;     ...
;     const char* cA = (const char*)g.A + (size_t)cur.pm * tstep; const char* cB = (const char*)g.Bt + (size_t)cur.pn * tstep;
;     S.a_ready(cur);
;     if constexpr (SP2) {
;         PG8_STAGE(PG8_SB(0, 0), cB, voffB); PG8_STAGE(PG8_SB(0, 1), cB + hstep, voffB); PG8_STAGE(PG8_SA(0, 0), cA, voffA); PG8_STAGE(PG8_SA(0, 1), cA + hstep, voffA);
;         if (wr == 1) PG8_BAR;
;         PG8_WAIT_V(2); PG8_BAR;
;         PG8_STAGE(PG8_SB(1, 0), cB + kstep, voffB); PG8_STAGE(PG8_SA(1, 0), cA + kstep, voffA); PG8_STAGE(PG8_SB(1, 1), cB + hstep + kstep, voffB);
;         PG8_WAIT_V(6); PG8_BAR;
;     } else {
;         PG8_STAGE(PG8_SB(0, 0), cB, voffB); PG8_STAGE(PG8_SA(0, 0), cA, voffA); PG8_STAGE(PG8_SB(0, 1), cB + hstep, voffB); PG8_STAGE(PG8_SA(0, 1), cA + hstep, voffA);
;         if (wr == 1) PG8_BAR;
;         PG8_WAIT_V(4); PG8_BAR;
;         PG8_STAGE(PG8_SB(1, 0), cB + kstep, voffB); PG8_STAGE(PG8_SA(1, 0), cA + kstep, voffA); PG8_STAGE(PG8_SB(1, 1), cB + hstep + kstep, voffB);
;         PG8_WAIT_V(6); PG8_BAR;
;     }
.LBB0_1896:
	s_waitcnt lgkmcnt(0)
	s_setprio 0
	s_cmp_lt_i32 s6, 11
	s_cselect_b64 s[4:5], -1, 0
	s_cmp_gt_i32 s7, 10
	s_cselect_b64 s[8:9], -1, 0
	s_and_b64 s[4:5], s[4:5], s[8:9]
	s_andn2_b64 vcc, exec, s[4:5]
	s_cbranch_vccnz .LBB0_2059
	s_and_b64 s[4:5], s[30:31], exec
	s_cselect_b32 s8, 8, 1
	v_cvt_f32_ubyte0_e32 v0, s8
	v_rcp_iflag_f32_e32 v0, v0
	v_readfirstlane_b32 s17, v242
	s_cmpk_gt_i32 s2, 0x27f
	v_mul_f32_e32 v0, 0x4f7ffffe, v0
	v_cvt_u32_f32_e32 v0, v0
	s_nop 0
	v_readfirstlane_b32 s12, v0
	s_cbranch_scc1 .LBB0_1913
	v_lshrrev_b32_e32 v0, 5, v242
	v_lshrrev_b32_e32 v2, 1, v242
	s_sub_i32 s6, 0, s8
	s_load_dwordx2 s[4:5], s[0:1], 0xd8
	v_and_b32_e32 v0, 4, v0
	v_bfe_u32 v1, v242, 2, 2
	v_and_b32_e32 v11, 24, v2
	s_mul_i32 s6, s6, s12
	v_or3_b32 v0, v0, v1, v11
	v_lshlrev_b32_e32 v1, 4, v242
	s_mul_hi_u32 s6, s12, s6
	v_add_u32_e32 v8, 0x2000, v1
	s_add_i32 s15, s12, s6
	v_lshrrev_b32_e32 v2, 7, v8
	s_movk_i32 s6, 0xe0
	v_and_b32_e32 v4, 32, v242
	s_ashr_i32 s3, s2, 31
	s_abs_i32 s9, s2
	s_lshr_b32 s14, s17, 6
	v_and_or_b32 v3, v2, s6, v0
	v_bitop3_b32 v9, v1, v4, 48 bitop3:0x6c
	v_and_b32_e32 v10, 64, v242
	v_bfe_u32 v12, v242, 2, 4
	s_movk_i32 s6, 0xf0
	s_waitcnt lgkmcnt(0)
	s_add_u32 s44, s4, 0x6000000
	v_or_b32_e32 v1, v9, v10
	v_and_or_b32 v2, v2, s6, v12
	s_addc_u32 s45, s5, 0
	v_lshl_or_b32 v130, v2, 11, v1
	v_lshrrev_b32_e32 v2, 3, v242
	s_movk_i32 s6, 0x60
	s_add_u32 s46, s4, 0x5400000
	v_and_or_b32 v0, v2, s6, v0
	s_movk_i32 s6, 0x70
	s_addc_u32 s47, s5, 0
	v_lshl_or_b32 v132, v0, 11, v1
	v_and_or_b32 v0, v2, s6, v12
	s_lshr_b32 s6, s3, 29
	s_add_i32 s6, s2, s6
	s_ashr_i32 s7, s6, 3
	s_and_b32 s6, s6, -8
	s_lshr_b32 s18, s17, 8
	s_lshl_b32 s48, s14, 10
	s_sub_i32 s6, s2, s6
	s_cmp_lt_i32 s6, 0
	s_movk_i32 s49, 0x51
	s_cselect_b32 s12, s49, 0x50
	s_mul_i32 s6, s12, s6
	s_add_i32 s6, s6, s7
	s_mul_hi_i32 s7, s6, 0x66666667
	s_lshr_b32 s12, s7, 31
	s_ashr_i32 s7, s7, 4
	s_add_i32 s7, s7, s12
	s_lshl_b32 s12, s7, 3
	s_mul_i32 s7, s7, 40
	s_sub_i32 s6, s6, s7
	s_bfe_i32 s7, s6, 0x80000
	s_bfe_u32 s7, s7, 0x3000c
	s_add_i32 s7, s6, s7
	s_bfe_i32 s13, s7, 0x80000
	s_and_b32 s7, s7, 0xf8
	s_sub_i32 s6, s6, s7
	s_sext_i32_i16 s13, s13
	s_sext_i32_i8 s6, s6
	s_lshr_b32 s16, s13, 3
	s_add_i32 s36, s12, s6
	s_ashr_i32 s37, s36, 31
	s_bfe_i64 s[12:13], s[16:17], 0x100000
	s_lshl_b64 s[6:7], s[36:37], 19
	s_lshl_b64 s[12:13], s[12:13], 19
	s_add_u32 s40, s46, s12
	s_addc_u32 s41, s47, s13
	s_add_i32 s37, s48, 0
	s_add_i32 m0, s37, 0x10000
	v_lshl_or_b32 v128, v3, 11, v1
	global_load_lds_dwordx4 v132, s[40:41]
	s_add_i32 m0, s37, 0x12000
	s_add_u32 s12, s40, 0x40000
	global_load_lds_dwordx4 v128, s[40:41]
	s_addc_u32 s13, s41, 0
	s_add_i32 m0, s37, 0x14000
	v_lshl_or_b32 v134, v0, 11, v1
	global_load_lds_dwordx4 v132, s[12:13]
	s_add_i32 m0, s37, 0x16000
	s_add_u32 s38, s44, s6
	s_addc_u32 s39, s45, s7
	s_add_i32 s50, s37, 0x2000
	global_load_lds_dwordx4 v128, s[12:13]
	s_mov_b32 m0, s37
	s_add_u32 s6, s38, 0x40000
	global_load_lds_dwordx4 v134, s[38:39]
	s_mov_b32 m0, s50
	s_addc_u32 s7, s39, 0
	s_add_i32 s51, s37, 0x4000
	global_load_lds_dwordx4 v130, s[38:39]
	s_mov_b32 m0, s51
	s_add_i32 s52, s37, 0x6000
	global_load_lds_dwordx4 v134, s[6:7]
	s_mov_b32 m0, s52
	v_mov_b32_e32 v133, 0
	global_load_lds_dwordx4 v130, s[6:7]
	v_mov_b32_e32 v129, v133
	v_mov_b32_e32 v135, v133
	v_mov_b32_e32 v131, v133
	s_cmp_eq_u32 s18, 1
	s_mul_hi_u32 s12, s9, s15
	v_lshl_add_u64 v[6:7], s[40:41], 0, v[132:133]
	v_lshl_add_u64 v[4:5], s[40:41], 0, v[128:129]
	v_lshl_add_u64 v[0:1], s[38:39], 0, v[134:135]
	s_cselect_b64 s[6:7], -1, 0
	s_cmp_lg_u32 s18, 1
	v_lshl_add_u64 v[2:3], s[38:39], 0, v[130:131]
	s_cbranch_scc1 .LBB0_1900
	s_barrier
.LBB0_1900:
	s_mul_i32 s12, s12, s8
	s_sub_i32 s9, s9, s12
	s_sub_i32 s12, s9, s8
	s_cmp_ge_u32 s9, s8
	s_cselect_b32 s9, s12, s9
	s_sub_i32 s12, s9, s8
	s_cmp_ge_u32 s9, s8
	s_cselect_b32 s8, s12, s9
	s_xor_b32 s8, s8, s3
	s_sub_i32 s8, s8, s3
	s_ashr_i32 s9, s8, 31
	s_and_b64 s[12:13], s[30:31], exec
	s_cselect_b32 s12, 25, 28
	s_lshl_b64 s[12:13], s[8:9], s12
	s_add_u32 s15, s4, s12
	s_addc_u32 s19, s5, s13
	s_and_b64 s[12:13], s[30:31], exec
	s_cselect_b32 s12, 12, 15
	s_lshl_b64 s[8:9], s[8:9], s12
	s_mul_hi_u32 s12, s8, 0xfffff600
	s_sub_i32 s12, s12, s8
	s_mulk_i32 s9, 0xf600
	s_add_i32 s12, s12, s9
	s_mulk_i32 s8, 0xf600
	s_add_u32 s8, s15, s8
	s_addc_u32 s9, s19, s12
	s_add_u32 s8, s8, 0xa000000
	s_addc_u32 s9, s9, 0
	s_add_u32 s12, s4, 0x600000
	s_addc_u32 s13, s5, 0
	s_lshl_b32 s4, s14, 5
	s_mov_b64 s[14:15], 0x80
	s_and_b32 s20, s4, 0x60
	s_add_i32 m0, s37, 0x18000
	v_lshl_add_u64 v[6:7], v[6:7], 0, s[14:15]
	s_lshl_b32 s19, s18, 13
	s_lshl_b32 s21, s20, 7
	s_waitcnt vmcnt(2)
	s_barrier
	global_load_lds_dwordx4 v[6:7], off
	v_lshl_add_u64 v[4:5], v[4:5], 0, s[14:15]
	s_add_i32 m0, s37, 0x1a000
	s_add_i32 s53, s37, 0x8000
	s_add_i32 s54, s37, 0xa000
	global_load_lds_dwordx4 v[4:5], off
	v_lshl_add_u64 v[0:1], v[0:1], 0, s[14:15]
	s_mov_b32 m0, s53
	s_add_u32 s4, s40, 0x40080
	global_load_lds_dwordx4 v[0:1], off
	v_lshl_add_u64 v[0:1], v[2:3], 0, s[14:15]
	s_mov_b32 m0, s54
	s_addc_u32 s5, s41, 0
	global_load_lds_dwordx4 v[0:1], off
	s_add_i32 m0, s37, 0x1c000
	v_lshl_add_u64 v[0:1], s[4:5], 0, v[132:133]
	global_load_lds_dwordx4 v[0:1], off
	v_lshl_add_u64 v[0:1], s[4:5], 0, v[128:129]
	s_add_i32 m0, s37, 0x1e000
	v_lshlrev_b32_e32 v2, 2, v242
	global_load_lds_dwordx4 v[0:1], off
	v_and_b32_e32 v0, 15, v242
	v_lshlrev_b32_e32 v1, 1, v11
	v_lshlrev_b32_e32 v3, 6, v242
	s_movk_i32 s4, 0x3c0
	v_lshl_or_b32 v148, s18, 6, v0
	v_lshl_or_b32 v0, v0, 6, v1
	v_and_b32_e32 v2, 32, v2
	v_and_or_b32 v1, v3, s4, v1
	v_bitop3_b32 v149, s21, v1, v2 bitop3:0xf6
	v_lshlrev_b32_e32 v1, 8, v242
	v_bitop3_b32 v0, v0, s19, v2 bitop3:0xde
	v_and_b32_e32 v1, 0x38000, v1
	v_lshlrev_b32_e32 v2, 11, v12
	v_or3_b32 v1, v9, v1, v2
	v_add_u32_e32 v136, v1, v10
	v_lshlrev_b32_e32 v1, 4, v8
	s_waitcnt vmcnt(6)
	s_cmpk_lt_u32 s17, 0x100
	v_and_b32_e32 v1, 0x78000, v1
	s_sext_i32_i8 s63, s16
	s_cselect_b64 s[16:17], -1, 0
	v_or3_b32 v1, v9, v1, v2
	s_add_i32 s57, 0, 0x10000
	s_add_i32 s58, 0, 0x14000
	s_mov_b32 s55, 0
	s_ashr_i32 s56, s61, 31
	v_or_b32_e32 v150, s20, v11
	v_mov_b32_e32 v137, v133
	v_add_u32_e32 v138, v1, v10
	v_mov_b32_e32 v139, v133
	v_mov_b64_e32 v[140:141], 0x280
	v_mov_b64_e32 v[142:143], 0x27f
	v_add_u32_e32 v151, s57, v149
	v_add_u32_e32 v152, s58, v149
	v_add_u32_e32 v153, 0, v0
	v_mov_b32_e32 v154, 0x358637bd
	s_movk_i32 s59, 0xa00
	v_mov_b32_e32 v155, 0x3e38aa3b
	s_barrier
	v_readfirstlane_b32 s99, v242
	s_nop 3
	s_cmp_ge_u32 s99, 0x100
	s_cbranch_scc1 .Lprio_skip_8
	s_setprio 1
.Lprio_skip_8:
	s_branch .LBB0_1903
.LBB0_1901:
	s_mov_b64 s[4:5], 0

; #define PG8_STAGE(bufoff, gbase, voff) do { _Pragma("unroll") for (int _i = 0; _i < 2; ++_i) \
;         __builtin_amdgcn_global_load_lds((const unsigned*)((const char*)(gbase) + (voff)[_i]), (PG8_LAS unsigned*)(lds + (bufoff) + ldsw + _i * 8192), 16, 0, 0); } while (0)
; #define PG8_LDA(dst, b, h) do { _Pragma("unroll") for (int m = 0; m < 4; ++m) _Pragma("unroll") for (int k = 0; k < 2; ++k) dst[m][k] = *(const PG8_LAS bf16x8*)(lds + PG8_SA(b, h) + aoff + m * 2048 + k * 1024); } while (0)
; #define PG8_LDB(dst, b, h) do { _Pragma("unroll") for (int n = 0; n < 2; ++n) _Pragma("unroll") for (int k = 0; k < 2; ++k) dst[n][k] = *(const PG8_LAS bf16x8*)(lds + PG8_SB(b, h) + boff + n * 2048 + k * 1024); } while (0)
; #define PG8_WAIT_V(n) asm volatile("s_waitcnt vmcnt(" #n ")" ::: "memory")
; #define PG8_WAIT_L(n) asm volatile("s_waitcnt lgkmcnt(" #n ")" ::: "memory")
; template <class Epi, class Sched, bool ALIGN_EPI = false, bool SP2 = false>
; __device__ __forceinline__ void gemm_phase(PG8_LAS unsigned char* lds, const Gemm g, const Sched& S, const Epi& E) {
;     ...
;         const bool has_next = S.next(ui + 1, nxt);
;         const char* nA = has_next ? (const char*)g.A + (size_t)nxt.pm * tstep : cA; const char* nB = has_next ? (const char*)g.Bt + (size_t)nxt.pn * tstep : cB;
;         for (int t = 0; t < nt; t += 2) {
;             const bool last = (t == nt - 2);
;             if constexpr (Epi::PREFETCH) { if (t == nt - 4) E.prefetch(cur, lds + STAGE_BYTES + 1024, tid); }
;             const char* a1 = cA + (size_t)(t + 1) * kstep;
;             const char* a2 = last ? nA : cA + (size_t)(t + 2) * kstep; const char* b2 = last ? nB : cB + (size_t)(t + 2) * kstep;
;             const char* a3 = a2 + kstep; const char* b3 = b2 + kstep;
;             if (last && has_next) S.a_ready(nxt);
;             if constexpr (SP2) {
;             PG8_LDB(B0, 0, 0); PG8_LDB(B1, 0, 1); PG8_SCHED; PG8_LDA(At, 0, 0); PG8_STAGE(PG8_SA(1, 1), a1 + hstep, voffA);
;             PG8_WAIT_V(8); PG8_WAIT_L(0); PG8_BAR; PG8_MMA(0, 0, At, B0); PG8_MMA(0, 1, At, B1); PG8_BAR; PG8_SCHED;
;             PG8_LDA(At, 0, 1); PG8_STAGE(PG8_SB(0, 0), b2, voffB); PG8_STAGE(PG8_SB(0, 1), b2 + hstep, voffB); PG8_STAGE(PG8_SA(0, 0), a2, voffA);
;             PG8_WAIT_V(8); PG8_WAIT_L(0); PG8_BAR; PG8_MMA(1, 0, At, B0); PG8_MMA(1, 1, At, B1); PG8_BAR; PG8_SCHED;
.LBB0_1905:
	s_ashr_i32 s21, s20, 31
	s_lshl_b64 s[22:23], s[20:21], 19
	s_add_u32 s22, s44, s22
	s_addc_u32 s23, s45, s23
	s_and_b64 s[34:35], s[4:5], exec
	s_cselect_b32 s21, s23, s39
	s_cselect_b32 s64, s22, s38
	s_ashr_i32 s19, s18, 31
	s_lshl_b64 s[34:35], s[18:19], 19
	s_add_u32 s34, s46, s34
	s_addc_u32 s35, s47, s35
	s_and_b64 s[42:43], s[4:5], exec
	s_cselect_b32 s19, s35, s41
	s_cselect_b32 s65, s34, s40
	s_add_u32 s38, s38, 0x40080
	s_addc_u32 s39, s39, 0
	s_add_u32 s66, s40, 0x100
	s_addc_u32 s67, s41, 0
	s_mov_b32 s68, -2
	ds_read_b128 v[144:147], v151
	ds_read_b128 v[156:159], v151 offset:1024
	ds_read_b128 v[160:163], v151 offset:2048
	ds_read_b128 v[164:167], v151 offset:3072
	ds_read_b128 v[168:171], v152
	ds_read_b128 v[172:175], v152 offset:1024
	ds_read_b128 v[176:179], v152 offset:2048
	ds_read_b128 v[180:183], v152 offset:3072
	s_add_u32 s40, s38, 0xfffc0080
	s_addc_u32 s41, s39, -1
	s_cmp_eq_u32 s68, 12
	s_cselect_b32 s43, s21, s41
	s_cselect_b32 s42, s64, s40
	s_cselect_b32 s41, s19, s67
	s_cselect_b32 s40, s65, s66
	v_lshl_add_u64 v[216:217], s[38:39], 0, v[136:137]
	s_add_i32 m0, s37, 0xc000
	ds_read_b128 v[184:187], v153
	ds_read_b128 v[188:191], v153 offset:1024
	ds_read_b128 v[192:195], v153 offset:2048
	ds_read_b128 v[196:199], v153 offset:3072
	ds_read_b128 v[200:203], v153 offset:4096
	ds_read_b128 v[204:207], v153 offset:5120
	ds_read_b128 v[208:211], v153 offset:6144
	ds_read_b128 v[212:215], v153 offset:7168
	global_load_lds_dwordx4 v[216:217], off
	v_lshl_add_u64 v[216:217], s[38:39], 0, v[138:139]
	s_add_i32 m0, s37, 0xe000
	s_nop 0
	global_load_lds_dwordx4 v[216:217], off
	s_waitcnt vmcnt(8)
	s_waitcnt lgkmcnt(0)
	s_barrier
	v_mfma_f32_16x16x32_bf16 v[124:127], v[144:147], v[184:187], 0
	v_mfma_f32_16x16x32_bf16 v[120:123], v[160:163], v[184:187], 0
	v_mfma_f32_16x16x32_bf16 v[108:111], v[144:147], v[192:195], 0
	v_mfma_f32_16x16x32_bf16 v[104:107], v[160:163], v[192:195], 0
	v_mfma_f32_16x16x32_bf16 v[92:95], v[144:147], v[200:203], 0
	v_mfma_f32_16x16x32_bf16 v[88:91], v[160:163], v[200:203], 0
	v_mfma_f32_16x16x32_bf16 v[76:79], v[144:147], v[208:211], 0
	v_mfma_f32_16x16x32_bf16 v[72:75], v[160:163], v[208:211], 0
	v_mfma_f32_16x16x32_bf16 v[124:127], v[156:159], v[188:191], v[124:127]
	v_mfma_f32_16x16x32_bf16 v[120:123], v[164:167], v[188:191], v[120:123]
	v_mfma_f32_16x16x32_bf16 v[108:111], v[156:159], v[196:199], v[108:111]
	v_mfma_f32_16x16x32_bf16 v[104:107], v[164:167], v[196:199], v[104:107]
	v_mfma_f32_16x16x32_bf16 v[92:95], v[156:159], v[204:207], v[92:95]
	v_mfma_f32_16x16x32_bf16 v[88:91], v[164:167], v[204:207], v[88:91]
	v_mfma_f32_16x16x32_bf16 v[76:79], v[156:159], v[212:215], v[76:79]
	v_mfma_f32_16x16x32_bf16 v[72:75], v[164:167], v[212:215], v[72:75]
	v_mfma_f32_16x16x32_bf16 v[116:119], v[168:171], v[184:187], 0
	v_mfma_f32_16x16x32_bf16 v[112:115], v[176:179], v[184:187], 0
	v_mfma_f32_16x16x32_bf16 v[100:103], v[168:171], v[192:195], 0
	v_mfma_f32_16x16x32_bf16 v[96:99], v[176:179], v[192:195], 0
	v_mfma_f32_16x16x32_bf16 v[84:87], v[168:171], v[200:203], 0
	v_mfma_f32_16x16x32_bf16 v[80:83], v[176:179], v[200:203], 0
	v_mfma_f32_16x16x32_bf16 v[68:71], v[168:171], v[208:211], 0
	v_mfma_f32_16x16x32_bf16 v[64:67], v[176:179], v[208:211], 0
	v_mfma_f32_16x16x32_bf16 v[116:119], v[172:175], v[188:191], v[116:119]
	v_mfma_f32_16x16x32_bf16 v[112:115], v[180:183], v[188:191], v[112:115]
	v_mfma_f32_16x16x32_bf16 v[100:103], v[172:175], v[196:199], v[100:103]
	v_mfma_f32_16x16x32_bf16 v[96:99], v[180:183], v[196:199], v[96:99]
	v_mfma_f32_16x16x32_bf16 v[84:87], v[172:175], v[204:207], v[84:87]
	v_mfma_f32_16x16x32_bf16 v[80:83], v[180:183], v[204:207], v[80:83]
	v_mfma_f32_16x16x32_bf16 v[68:71], v[172:175], v[212:215], v[68:71]
	v_mfma_f32_16x16x32_bf16 v[64:67], v[180:183], v[212:215], v[64:67]
	s_barrier
	s_add_i32 s69, s57, s48
	v_lshl_add_u64 v[216:217], s[40:41], 0, v[132:133]
	s_mov_b32 m0, s69
	ds_read_b128 v[184:187], v153 offset:16384
	ds_read_b128 v[188:191], v153 offset:17408
	ds_read_b128 v[192:195], v153 offset:18432
	ds_read_b128 v[196:199], v153 offset:19456
	ds_read_b128 v[200:203], v153 offset:20480
	ds_read_b128 v[204:207], v153 offset:21504
	ds_read_b128 v[208:211], v153 offset:22528
	ds_read_b128 v[212:215], v153 offset:23552
	global_load_lds_dwordx4 v[216:217], off
	s_add_i32 m0, s69, 0x2000
	s_add_u32 s70, s40, 0x40000
	v_lshl_add_u64 v[218:219], s[40:41], 0, v[128:129]
	s_addc_u32 s71, s41, 0
	s_add_i32 s69, s58, s48
	global_load_lds_dwordx4 v[218:219], off
	v_lshl_add_u64 v[220:221], s[70:71], 0, v[132:133]
	s_mov_b32 m0, s69
	v_lshl_add_u64 v[222:223], s[42:43], 0, v[130:131]
	global_load_lds_dwordx4 v[220:221], off
	v_lshl_add_u64 v[220:221], s[70:71], 0, v[128:129]
	s_add_i32 m0, s69, 0x2000
	s_nop 0
	global_load_lds_dwordx4 v[220:221], off
	v_lshl_add_u64 v[220:221], s[42:43], 0, v[134:135]
	s_mov_b32 m0, s37
	s_nop 0
	global_load_lds_dwordx4 v[220:221], off
	s_mov_b32 m0, s50
	s_nop 0
	global_load_lds_dwordx4 v[222:223], off
	s_waitcnt vmcnt(8)
	s_waitcnt lgkmcnt(0)
	s_barrier
; #define PG8_STAGE(bufoff, gbase, voff) do { _Pragma("unroll") for (int _i = 0; _i < 2; ++_i) \
;         __builtin_amdgcn_global_load_lds((const unsigned*)((const char*)(gbase) + (voff)[_i]), (PG8_LAS unsigned*)(lds + (bufoff) + ldsw + _i * 8192), 16, 0, 0); } while (0)
; #define PG8_LDA(dst, b, h) do { _Pragma("unroll") for (int m = 0; m < 4; ++m) _Pragma("unroll") for (int k = 0; k < 2; ++k) dst[m][k] = *(const PG8_LAS bf16x8*)(lds + PG8_SA(b, h) + aoff + m * 2048 + k * 1024); } while (0)
; #define PG8_LDB(dst, b, h) do { _Pragma("unroll") for (int n = 0; n < 2; ++n) _Pragma("unroll") for (int k = 0; k < 2; ++k) dst[n][k] = *(const PG8_LAS bf16x8*)(lds + PG8_SB(b, h) + boff + n * 2048 + k * 1024); } while (0)
; #define PG8_MMA(ai, bj, At, Bt) do { __builtin_amdgcn_s_setprio(1); _Pragma("unroll") for (int m = 0; m < 4; ++m) _Pragma("unroll") for (int n = 0; n < 2; ++n) _Pragma("unroll") for (int k = 0; k < 2; ++k) \
;         acc[ai][bj][m][n] = __builtin_amdgcn_mfma_f32_16x16x32_bf16(Bt[n][k], At[m][k], acc[ai][bj][m][n], 0, 0, 0); __builtin_amdgcn_s_setprio(0); } while (0)
; #define PG8_WAIT_V(n) asm volatile("s_waitcnt vmcnt(" #n ")" ::: "memory")
; #define PG8_WAIT_L(n) asm volatile("s_waitcnt lgkmcnt(" #n ")" ::: "memory")
; #define PG8_BAR __builtin_amdgcn_s_barrier()
; #define PG8_SCHED __builtin_amdgcn_sched_barrier(0)
; template <class Epi, class Sched, bool ALIGN_EPI = false, bool SP2 = false>
; __device__ __forceinline__ void gemm_phase(PG8_LAS unsigned char* lds, const Gemm g, const Sched& S, const Epi& E) {
;     ...
;             PG8_WAIT_V(8); PG8_WAIT_L(0); PG8_BAR; PG8_MMA(1, 0, At, B0); PG8_MMA(1, 1, At, B1); PG8_BAR; PG8_SCHED;
;             PG8_LDB(B0, 1, 0); PG8_LDB(B1, 1, 1); PG8_SCHED; PG8_LDA(At, 1, 0); PG8_STAGE(PG8_SA(0, 1), a2 + hstep, voffA);
;             PG8_WAIT_V(8); PG8_WAIT_L(0); PG8_BAR; PG8_MMA(0, 0, At, B0); PG8_MMA(0, 1, At, B1); PG8_BAR; PG8_SCHED;
	v_mfma_f32_16x16x32_bf16 v[60:63], v[144:147], v[184:187], 0
	v_mfma_f32_16x16x32_bf16 v[56:59], v[160:163], v[184:187], 0
	v_mfma_f32_16x16x32_bf16 v[44:47], v[144:147], v[192:195], 0
	v_mfma_f32_16x16x32_bf16 v[40:43], v[160:163], v[192:195], 0
	v_mfma_f32_16x16x32_bf16 v[28:31], v[144:147], v[200:203], 0
	v_mfma_f32_16x16x32_bf16 v[24:27], v[160:163], v[200:203], 0
	v_mfma_f32_16x16x32_bf16 v[12:15], v[144:147], v[208:211], 0
	v_mfma_f32_16x16x32_bf16 v[8:11], v[160:163], v[208:211], 0
	v_mfma_f32_16x16x32_bf16 v[60:63], v[156:159], v[188:191], v[60:63]
	v_mfma_f32_16x16x32_bf16 v[56:59], v[164:167], v[188:191], v[56:59]
	v_mfma_f32_16x16x32_bf16 v[44:47], v[156:159], v[196:199], v[44:47]
	v_mfma_f32_16x16x32_bf16 v[40:43], v[164:167], v[196:199], v[40:43]
	v_mfma_f32_16x16x32_bf16 v[28:31], v[156:159], v[204:207], v[28:31]
	v_mfma_f32_16x16x32_bf16 v[24:27], v[164:167], v[204:207], v[24:27]
	v_mfma_f32_16x16x32_bf16 v[12:15], v[156:159], v[212:215], v[12:15]
	v_mfma_f32_16x16x32_bf16 v[8:11], v[164:167], v[212:215], v[8:11]
	v_mfma_f32_16x16x32_bf16 v[52:55], v[168:171], v[184:187], 0
	v_mfma_f32_16x16x32_bf16 v[48:51], v[176:179], v[184:187], 0
	v_mfma_f32_16x16x32_bf16 v[36:39], v[168:171], v[192:195], 0
	v_mfma_f32_16x16x32_bf16 v[32:35], v[176:179], v[192:195], 0
	v_mfma_f32_16x16x32_bf16 v[20:23], v[168:171], v[200:203], 0
	v_mfma_f32_16x16x32_bf16 v[16:19], v[176:179], v[200:203], 0
	v_mfma_f32_16x16x32_bf16 v[4:7], v[168:171], v[208:211], 0
	v_mfma_f32_16x16x32_bf16 v[0:3], v[176:179], v[208:211], 0
	v_mfma_f32_16x16x32_bf16 v[52:55], v[172:175], v[188:191], v[52:55]
	v_mfma_f32_16x16x32_bf16 v[48:51], v[180:183], v[188:191], v[48:51]
	v_mfma_f32_16x16x32_bf16 v[36:39], v[172:175], v[196:199], v[36:39]
	v_mfma_f32_16x16x32_bf16 v[32:35], v[180:183], v[196:199], v[32:35]
	v_mfma_f32_16x16x32_bf16 v[20:23], v[172:175], v[204:207], v[20:23]
	v_mfma_f32_16x16x32_bf16 v[16:19], v[180:183], v[204:207], v[16:19]
	v_mfma_f32_16x16x32_bf16 v[4:7], v[172:175], v[212:215], v[4:7]
	v_mfma_f32_16x16x32_bf16 v[0:3], v[180:183], v[212:215], v[0:3]
	s_barrier
	s_add_i32 s69, 0, 0x18000
	s_add_i32 s70, 0, 0x1c000
	v_add_u32_e32 v164, s69, v149
	v_add_u32_e32 v180, s70, v149
	ds_read_b128 v[144:147], v164
	ds_read_b128 v[156:159], v164 offset:1024
	ds_read_b128 v[160:163], v164 offset:2048
	ds_read_b128 v[164:167], v164 offset:3072
	ds_read_b128 v[168:171], v180
	ds_read_b128 v[172:175], v180 offset:1024
	ds_read_b128 v[176:179], v180 offset:2048
	ds_read_b128 v[180:183], v180 offset:3072
	s_add_u32 s42, s42, 0x40000
	s_addc_u32 s43, s43, 0
	s_mov_b32 m0, s51
	v_lshl_add_u64 v[224:225], s[42:43], 0, v[134:135]
	ds_read_b128 v[184:187], v153 offset:32768
	ds_read_b128 v[188:191], v153 offset:33792
	ds_read_b128 v[192:195], v153 offset:34816
	ds_read_b128 v[196:199], v153 offset:35840
	ds_read_b128 v[200:203], v153 offset:36864
	ds_read_b128 v[204:207], v153 offset:37888
	ds_read_b128 v[208:211], v153 offset:38912
	ds_read_b128 v[212:215], v153 offset:39936
	global_load_lds_dwordx4 v[224:225], off
	v_lshl_add_u64 v[224:225], s[42:43], 0, v[130:131]
	s_mov_b32 m0, s52
	s_nop 0
	global_load_lds_dwordx4 v[224:225], off
	s_waitcnt vmcnt(8)
	s_waitcnt lgkmcnt(0)
	s_barrier
	v_mfma_f32_16x16x32_bf16 v[124:127], v[144:147], v[184:187], v[124:127]
	v_mfma_f32_16x16x32_bf16 v[120:123], v[160:163], v[184:187], v[120:123]
	v_mfma_f32_16x16x32_bf16 v[108:111], v[144:147], v[192:195], v[108:111]
	v_mfma_f32_16x16x32_bf16 v[104:107], v[160:163], v[192:195], v[104:107]
	v_mfma_f32_16x16x32_bf16 v[92:95], v[144:147], v[200:203], v[92:95]
	v_mfma_f32_16x16x32_bf16 v[88:91], v[160:163], v[200:203], v[88:91]
	v_mfma_f32_16x16x32_bf16 v[76:79], v[144:147], v[208:211], v[76:79]
	v_mfma_f32_16x16x32_bf16 v[72:75], v[160:163], v[208:211], v[72:75]
	v_mfma_f32_16x16x32_bf16 v[124:127], v[156:159], v[188:191], v[124:127]
	v_mfma_f32_16x16x32_bf16 v[120:123], v[164:167], v[188:191], v[120:123]
	v_mfma_f32_16x16x32_bf16 v[108:111], v[156:159], v[196:199], v[108:111]
	v_mfma_f32_16x16x32_bf16 v[104:107], v[164:167], v[196:199], v[104:107]
	v_mfma_f32_16x16x32_bf16 v[92:95], v[156:159], v[204:207], v[92:95]
	v_mfma_f32_16x16x32_bf16 v[88:91], v[164:167], v[204:207], v[88:91]
	v_mfma_f32_16x16x32_bf16 v[76:79], v[156:159], v[212:215], v[76:79]
	v_mfma_f32_16x16x32_bf16 v[72:75], v[164:167], v[212:215], v[72:75]
	v_mfma_f32_16x16x32_bf16 v[116:119], v[168:171], v[184:187], v[116:119]
	v_mfma_f32_16x16x32_bf16 v[112:115], v[176:179], v[184:187], v[112:115]
	v_mfma_f32_16x16x32_bf16 v[100:103], v[168:171], v[192:195], v[100:103]
	v_mfma_f32_16x16x32_bf16 v[96:99], v[176:179], v[192:195], v[96:99]
	v_mfma_f32_16x16x32_bf16 v[84:87], v[168:171], v[200:203], v[84:87]
	v_mfma_f32_16x16x32_bf16 v[80:83], v[176:179], v[200:203], v[80:83]
	v_mfma_f32_16x16x32_bf16 v[68:71], v[168:171], v[208:211], v[68:71]
	v_mfma_f32_16x16x32_bf16 v[64:67], v[176:179], v[208:211], v[64:67]
	v_mfma_f32_16x16x32_bf16 v[116:119], v[172:175], v[188:191], v[116:119]
	v_mfma_f32_16x16x32_bf16 v[112:115], v[180:183], v[188:191], v[112:115]
	v_mfma_f32_16x16x32_bf16 v[100:103], v[172:175], v[196:199], v[100:103]
	v_mfma_f32_16x16x32_bf16 v[96:99], v[180:183], v[196:199], v[96:99]
	v_mfma_f32_16x16x32_bf16 v[84:87], v[172:175], v[204:207], v[84:87]
	v_mfma_f32_16x16x32_bf16 v[80:83], v[180:183], v[204:207], v[80:83]
	v_mfma_f32_16x16x32_bf16 v[68:71], v[172:175], v[212:215], v[68:71]
	v_mfma_f32_16x16x32_bf16 v[64:67], v[180:183], v[212:215], v[64:67]
	s_barrier
; #define PG8_STAGE(bufoff, gbase, voff) do { _Pragma("unroll") for (int _i = 0; _i < 2; ++_i) \
;         __builtin_amdgcn_global_load_lds((const unsigned*)((const char*)(gbase) + (voff)[_i]), (PG8_LAS unsigned*)(lds + (bufoff) + ldsw + _i * 8192), 16, 0, 0); } while (0)
; #define PG8_LDA(dst, b, h) do { _Pragma("unroll") for (int m = 0; m < 4; ++m) _Pragma("unroll") for (int k = 0; k < 2; ++k) dst[m][k] = *(const PG8_LAS bf16x8*)(lds + PG8_SA(b, h) + aoff + m * 2048 + k * 1024); } while (0)
; #define PG8_MMA(ai, bj, At, Bt) do { __builtin_amdgcn_s_setprio(1); _Pragma("unroll") for (int m = 0; m < 4; ++m) _Pragma("unroll") for (int n = 0; n < 2; ++n) _Pragma("unroll") for (int k = 0; k < 2; ++k) \
;         acc[ai][bj][m][n] = __builtin_amdgcn_mfma_f32_16x16x32_bf16(Bt[n][k], At[m][k], acc[ai][bj][m][n], 0, 0, 0); __builtin_amdgcn_s_setprio(0); } while (0)
; #define PG8_WAIT_V(n) asm volatile("s_waitcnt vmcnt(" #n ")" ::: "memory")
; #define PG8_WAIT_L(n) asm volatile("s_waitcnt lgkmcnt(" #n ")" ::: "memory")
; #define PG8_BAR __builtin_amdgcn_s_barrier()
; #define PG8_SCHED __builtin_amdgcn_sched_barrier(0)
; template <class Epi, class Sched, bool ALIGN_EPI = false, bool SP2 = false>
; __device__ __forceinline__ void gemm_phase(PG8_LAS unsigned char* lds, const Gemm g, const Sched& S, const Epi& E) {
;     ...
;             PG8_LDA(At, 1, 1); PG8_STAGE(PG8_SB(1, 0), b3, voffB); PG8_STAGE(PG8_SB(1, 1), b3 + hstep, voffB); PG8_STAGE(PG8_SA(1, 0), a3, voffA);
;             PG8_WAIT_V(8); PG8_WAIT_L(0); PG8_BAR; PG8_MMA(1, 0, At, B0); PG8_MMA(1, 1, At, B1); PG8_BAR; PG8_SCHED;
	s_add_i32 s42, s69, s48
	v_lshl_add_u64 v[216:217], v[216:217], 0, s[14:15]
	s_mov_b32 m0, s42
	ds_read_b128 v[184:187], v153 offset:49152
	ds_read_b128 v[188:191], v153 offset:50176
	ds_read_b128 v[192:195], v153 offset:51200
	ds_read_b128 v[196:199], v153 offset:52224
	ds_read_b128 v[200:203], v153 offset:53248
	ds_read_b128 v[204:207], v153 offset:54272
	ds_read_b128 v[208:211], v153 offset:55296
	ds_read_b128 v[212:215], v153 offset:56320
	global_load_lds_dwordx4 v[216:217], off
	s_add_i32 m0, s42, 0x2000
	s_add_u32 s40, s40, 0x40080
	v_lshl_add_u64 v[216:217], v[218:219], 0, s[14:15]
	s_addc_u32 s41, s41, 0
	s_add_i32 s42, s70, s48
	global_load_lds_dwordx4 v[216:217], off
	v_lshl_add_u64 v[216:217], s[40:41], 0, v[132:133]
	s_mov_b32 m0, s42
	s_nop 0
	global_load_lds_dwordx4 v[216:217], off
	v_lshl_add_u64 v[216:217], s[40:41], 0, v[128:129]
	s_add_i32 m0, s42, 0x2000
	s_nop 0
	global_load_lds_dwordx4 v[216:217], off
	v_lshl_add_u64 v[216:217], v[220:221], 0, s[14:15]
	s_mov_b32 m0, s53
	s_nop 0
	global_load_lds_dwordx4 v[216:217], off
	v_lshl_add_u64 v[216:217], v[222:223], 0, s[14:15]
	s_mov_b32 m0, s54
	s_nop 0
	global_load_lds_dwordx4 v[216:217], off
	s_waitcnt vmcnt(8)
	s_waitcnt lgkmcnt(0)
	s_barrier
	v_mfma_f32_16x16x32_bf16 v[60:63], v[144:147], v[184:187], v[60:63]
	v_mfma_f32_16x16x32_bf16 v[56:59], v[160:163], v[184:187], v[56:59]
	v_mfma_f32_16x16x32_bf16 v[44:47], v[144:147], v[192:195], v[44:47]
	v_mfma_f32_16x16x32_bf16 v[40:43], v[160:163], v[192:195], v[40:43]
	v_mfma_f32_16x16x32_bf16 v[28:31], v[144:147], v[200:203], v[28:31]
	v_mfma_f32_16x16x32_bf16 v[24:27], v[160:163], v[200:203], v[24:27]
	v_mfma_f32_16x16x32_bf16 v[12:15], v[144:147], v[208:211], v[12:15]
	v_mfma_f32_16x16x32_bf16 v[8:11], v[160:163], v[208:211], v[8:11]
	v_mfma_f32_16x16x32_bf16 v[60:63], v[156:159], v[188:191], v[60:63]
	v_mfma_f32_16x16x32_bf16 v[56:59], v[164:167], v[188:191], v[56:59]
	v_mfma_f32_16x16x32_bf16 v[44:47], v[156:159], v[196:199], v[44:47]
	v_mfma_f32_16x16x32_bf16 v[40:43], v[164:167], v[196:199], v[40:43]
	v_mfma_f32_16x16x32_bf16 v[28:31], v[156:159], v[204:207], v[28:31]
	v_mfma_f32_16x16x32_bf16 v[24:27], v[164:167], v[204:207], v[24:27]
	v_mfma_f32_16x16x32_bf16 v[12:15], v[156:159], v[212:215], v[12:15]
	v_mfma_f32_16x16x32_bf16 v[8:11], v[164:167], v[212:215], v[8:11]
	v_mfma_f32_16x16x32_bf16 v[52:55], v[168:171], v[184:187], v[52:55]
	v_mfma_f32_16x16x32_bf16 v[48:51], v[176:179], v[184:187], v[48:51]
	v_mfma_f32_16x16x32_bf16 v[36:39], v[168:171], v[192:195], v[36:39]
	v_mfma_f32_16x16x32_bf16 v[32:35], v[176:179], v[192:195], v[32:35]
	v_mfma_f32_16x16x32_bf16 v[20:23], v[168:171], v[200:203], v[20:23]
	v_mfma_f32_16x16x32_bf16 v[16:19], v[176:179], v[200:203], v[16:19]
	v_mfma_f32_16x16x32_bf16 v[4:7], v[168:171], v[208:211], v[4:7]
	v_mfma_f32_16x16x32_bf16 v[0:3], v[176:179], v[208:211], v[0:3]
	v_mfma_f32_16x16x32_bf16 v[52:55], v[172:175], v[188:191], v[52:55]
	v_mfma_f32_16x16x32_bf16 v[48:51], v[180:183], v[188:191], v[48:51]
	v_mfma_f32_16x16x32_bf16 v[36:39], v[172:175], v[196:199], v[36:39]
	v_mfma_f32_16x16x32_bf16 v[32:35], v[180:183], v[196:199], v[32:35]
	v_mfma_f32_16x16x32_bf16 v[20:23], v[172:175], v[204:207], v[20:23]
	v_mfma_f32_16x16x32_bf16 v[16:19], v[180:183], v[204:207], v[16:19]
	v_mfma_f32_16x16x32_bf16 v[4:7], v[172:175], v[212:215], v[4:7]
	v_mfma_f32_16x16x32_bf16 v[0:3], v[180:183], v[212:215], v[0:3]
	s_barrier
	s_add_i32 s68, s68, 2
	s_add_u32 s38, s38, 0x100
	s_addc_u32 s39, s39, 0
	s_add_u32 s66, s66, 0x100
	s_addc_u32 s67, s67, 0

; #define LAS __attribute__((address_space(3)))
; __device__ __forceinline__ void swa_phase(LAS unsigned char* lds, const bf16* QKV, bf16* O, const float* sinks, int gx, int ngrp, int gj, int gsize) {
;     const int tid = threadIdx.x, lane = tid & 63, wid = tid >> 6, r32 = lane & 31, hi = lane >> 5;
;     LAS bf16* Kb = (LAS bf16*)lds;
;     LAS bf16* Vt = (LAS bf16*)(lds + 36864);
;     const float NEG = -INFINITY;
;     const int per = (BATCH * 2 * (SEQ / WIN)) / ngrp;
;     for (int ii = gj; ii < per; ii += gsize) { const int item = gx * per + ii;
;         const int b = item / 32, kvh = (item >> 4) & 1, blk = item & 15;
;         __syncthreads();
; #pragma unroll
;         for (int pass = 0; pass < 4; ++pass) { const int j = pass * 64 + (tid >> 3), ch = tid & 7, pos = WIN * (blk - 1) + j;
;             u32x4 kk = {0u, 0u, 0u, 0u}; bf16x8 vv = {0, 0, 0, 0, 0, 0, 0, 0};
;             if (pos >= 0) { const size_t g = (size_t)(b * SEQ + pos) * NQKV_SWA + D + kvh * HD + ch * 8; kk = *(const u32x4*)(QKV + g); vv = *(const bf16x8*)(QKV + g + 2 * HD); }
;             *(LAS u32x4*)(Kb + j * 72 + ch * 8) = kk;
; #pragma unroll
;             for (int jj = 0; jj < 8; ++jj) Vt[(ch * 8 + jj) * 264 + j] = (bf16)vv[jj]; }
;         __syncthreads();
;         const int h = kvh * 8 + wid;
;         const float slope2 = exp2f(-8.0f * (float)(h + 1) / 16.0f) * L2E, sink2 = sinks[h] * L2E;
;         for (int i = 0; i < 4; ++i) {
;             const int qin = 32 * i + r32, qrow = WIN * blk + qin;
;             const bf16* qptr = QKV + (size_t)(b * SEQ + qrow) * NQKV_SWA + h * HD;
;             bf16x8 qr[4];
; #pragma unroll
;             for (int d0 = 0; d0 < 4; ++d0) qr[d0] = *(const bf16x8*)(qptr + d0 * 16 + hi * 8);
;             float m = -1e30f, l = 0.f; f32x16 o0 = {}, o1 = {};
;             const int jt0 = (i < 2) ? 0 : 1;
;             const float lc = -slope2 * (float)(WIN + qin - 4 * hi);
; #pragma unroll
;             for (int js = 0; js < 3; ++js) { const int jt = jt0 + js;
;                 if (blk == 0 && jt < 2) continue;
;                 const float tb = lc + slope2 * (float)(64 * jt);
;                 f32x16 p0, p1;
; #pragma unroll
;                 for (int r = 0; r < 16; ++r) { const float kr = (float)((r & 3) + 8 * (r >> 2)); p0[r] = __builtin_fmaf(slope2, kr, tb); p1[r] = __builtin_fmaf(slope2, kr + 32.0f, tb); }
.LBB0_2059:
	s_waitcnt lgkmcnt(0)
	s_setprio 0
	s_cmp_lt_i32 s6, 12
	s_cselect_b64 s[4:5], -1, 0
	s_cmp_gt_i32 s7, 11
	s_cselect_b64 s[8:9], -1, 0
	s_and_b64 s[4:5], s[4:5], s[8:9]
	s_andn2_b64 vcc, exec, s[4:5]
	s_cbranch_vccnz .LBB0_2223
	s_and_b64 s[4:5], s[30:31], exec
	s_cselect_b32 s8, 8, 1
	v_cvt_f32_ubyte0_e32 v0, s8
	v_rcp_iflag_f32_e32 v0, v0
	s_sub_i32 s5, 0, s8
	s_abs_i32 s3, s2
	s_ashr_i32 s4, s2, 31
	v_mul_f32_e32 v0, 0x4f7ffffe, v0
	v_cvt_u32_f32_e32 v0, v0
	s_nop 0
	v_readfirstlane_b32 s9, v0
	s_mul_i32 s5, s5, s9
	s_mul_hi_u32 s5, s9, s5
	s_add_i32 s9, s9, s5
	s_mul_hi_u32 s5, s3, s9
	s_mul_i32 s12, s5, s8
	s_sub_i32 s3, s3, s12
	s_add_i32 s13, s5, 1
	s_sub_i32 s12, s3, s8
	s_cmp_ge_u32 s3, s8
	s_cselect_b32 s5, s13, s5
	s_cselect_b32 s3, s12, s3
	s_add_i32 s12, s5, 1
	s_cmp_ge_u32 s3, s8
	s_cselect_b32 s3, s12, s5
	s_xor_b32 s12, s3, s4
	s_sub_i32 s3, s12, s4
	s_and_b64 s[14:15], s[30:31], exec
	s_cselect_b32 s63, 64, 0x200
	s_cmp_ge_i32 s3, s63
	s_mov_b32 s5, 0
	s_cbranch_scc1 .LBB0_2077
	s_abs_i32 s7, s61
	s_mul_hi_u32 s9, s7, s9
	s_mul_i32 s13, s9, s8
	s_sub_i32 s7, s7, s13
	s_ashr_i32 s6, s61, 31
	s_add_i32 s13, s9, 1
	s_sub_i32 s14, s7, s8
	s_cmp_ge_u32 s7, s8
	s_cselect_b32 s9, s13, s9
	s_cselect_b32 s7, s14, s7
	s_add_i32 s13, s9, 1
	s_cmp_ge_u32 s7, s8
	s_cselect_b32 s7, s13, s9
	s_xor_b32 s7, s7, s6
	s_sub_i32 s64, s7, s6
	s_mul_i32 s6, s3, s8
	s_sub_i32 s14, s2, s6
	s_load_dwordx2 s[8:9], s[0:1], 0xd8
	s_ashr_i32 s15, s14, 31
	s_and_b64 s[6:7], s[30:31], exec
	s_cselect_b32 s6, 25, 28
	s_lshl_b64 s[16:17], s[14:15], s6
	s_load_dwordx2 s[6:7], s[0:1], 0x98
	s_waitcnt lgkmcnt(0)
	s_add_u32 s13, s8, s16
	s_addc_u32 s18, s9, s17
	s_and_b64 s[8:9], s[30:31], exec
	s_cselect_b32 s8, 12, 15
	s_lshl_b64 s[8:9], s[14:15], s8
	s_lshl_b64 s[16:17], s[8:9], 11
	s_sub_u32 s15, 0, s16
	s_subb_u32 s16, 0, s17
	s_add_u32 s13, s13, s15
	s_addc_u32 s15, s18, s16
	s_add_u32 s13, s13, 0xa000000
	s_addc_u32 s15, s15, 0
	s_mov_b32 s18, 0x1800000
	s_and_b64 s[16:17], s[30:31], exec
	s_cselect_b32 s16, s18, 0xc000000
	s_add_u32 s16, s13, s16
	s_addc_u32 s17, s15, 0
	s_lshl_b64 s[8:9], s[8:9], 9
	s_sub_u32 s8, 0, s8
	s_subb_u32 s9, 0, s9
	s_add_u32 s8, s13, s8
	s_addc_u32 s9, s15, s9
	s_and_b64 s[18:19], s[30:31], exec
	v_lshlrev_b32_e32 v0, 3, v242
	v_bfe_u32 v1, v242, 5, 1
	s_cselect_b32 s13, 6, 9
	v_and_b32_e32 v2, 56, v0
	v_mov_b32_e32 v0, 0
	v_and_b32_e32 v129, 31, v242
	s_lshl_b32 s65, s14, s13
	v_lshlrev_b32_e32 v6, 4, v1
	v_mov_b32_e32 v7, v0
	v_lshrrev_b32_e32 v130, 3, v242
	v_lshlrev_b32_e32 v4, 3, v1
	v_mov_b32_e32 v5, v0
	v_lshl_add_u64 v[96:97], s[8:9], 0, v[6:7]
	v_mul_u32_u24_e32 v7, 0x210, v129
	s_add_i32 s12, s12, s65
	v_lshl_add_u32 v3, v2, 1, 0
	v_lshlrev_b32_e32 v1, 2, v1
	v_add3_u32 v131, 0, v7, v4
	v_mul_u32_u24_e32 v7, 0x90, v130
	v_lshl_add_u32 v8, v130, 1, 0
	v_mul_u32_u24_e32 v9, 0x210, v2
	v_lshl_add_u64 v[98:99], s[16:17], 0, v[4:5]
	s_sub_i32 s69, s12, s4
	s_mov_b32 s12, 2.0
	s_mov_b32 s14, 0x41000000
	s_mov_b32 s16, 0x41200000
	s_mov_b32 s18, 0x41800000
	s_mov_b32 s20, 0x41900000
	s_mov_b32 s22, 0x41c00000
	s_mov_b32 s34, 0x41d00000
	s_mov_b32 s36, 0x42680000
	s_mov_b32 s38, 0x42600000
	s_mov_b32 s40, 0x42480000
	s_mov_b32 s42, 0x42400000
	s_mov_b32 s44, 0x42280000
	s_mov_b32 s46, 0x42200000
	s_mov_b32 s48, 0x42080000
	s_mov_b32 s50, 0x42000000
	v_mbcnt_lo_u32_b32 v142, -1, 0
	v_lshrrev_b32_e32 v128, 6, v242
	s_movk_i32 s66, 0x90
	v_add_u32_e32 v132, 64, v130
	s_movk_i32 s67, 0x80
	v_or_b32_e32 v133, 0x80, v130
	s_movk_i32 s68, 0xc0
	v_add_u32_e32 v134, 0xc0, v130
	v_add_u32_e32 v135, 0, v6
	v_sub_u32_e32 v136, v129, v1
	s_movk_i32 s70, 0xa00
	v_add_u32_e32 v137, v3, v7
	v_add_u32_e32 v138, v8, v9
	v_lshlrev_b32_e32 v100, 1, v2
	s_mov_b32 s71, 0xc2fc0000
	s_mov_b32 s13, 0x40400000
	s_mov_b32 s15, 0x41100000
	s_mov_b32 s17, 0x41300000
	s_mov_b32 s19, 0x41880000
	s_mov_b32 s21, 0x41980000
	s_mov_b32 s23, 0x41c80000
	s_mov_b32 s35, 0x41d80000
	s_mov_b32 s37, 0x426c0000
	s_mov_b32 s39, 0x42640000
	s_mov_b32 s41, 0x424c0000
	s_mov_b32 s43, 0x42440000
	s_mov_b32 s45, 0x422c0000
	s_mov_b32 s47, 0x42240000
	s_mov_b32 s49, 0x420c0000
	s_mov_b32 s51, 0x42040000
	s_movk_i32 s72, 0xa0
	s_mov_b32 s73, 0xf149f2ca
	v_mov_b32_e32 v139, 0x42800000
	v_not_b32_e32 v140, 63
	v_mov_b32_e32 v141, 0xff800000
	v_mbcnt_hi_u32_b32 v143, -1, v142
	s_branch .LBB0_2063

; __device__ __forceinline__ void run_phase(const int ph, const Args& a, LAS unsigned char* lds, unsigned char* ldsg, const bool dummy = false) {
;     ...
;         } else if (EN_RES && kind == K_RES) {
;             const bf16* A = f < 4 ? ACT : OB; const int K = f < 4 ? FF : D;
;             const bf16* W = f < 4 ? (const bf16*)(ws + WS_W + f * FFN_STRIDE + WD_OFF) : f == 4 ? (const bf16*)(ws + WS_WOFOX) : (const bf16*)(ws + WS_WOSWA);
;             pg8::Gemm g{A, W, M, D, K}; pg8::StaticOrder S; S.init(M, D, G, bx);
;             pg8::EpiResid E{nullptr, HB, nullptr, dummy ? (bf16*)(ws + 416 * MiB) : HB, rso >= 0 ? (dummy ? (pg8::rss_t*)(ws + 480 * MiB) : RS + (size_t)rso * M) : nullptr, alpha};
;             pg8::gemm_phase<pg8::EpiResid, pg8::StaticOrder, PG8_ALIGN, PG8_SP2>(lds, g, S, E);
.LBB0_2223:
	s_waitcnt lgkmcnt(0)
	s_setprio 0
	s_cmp_lt_i32 s6, 13
	s_cselect_b64 s[4:5], -1, 0
	s_cmp_gt_i32 s7, 12
	s_cselect_b64 s[8:9], -1, 0
	s_and_b64 s[4:5], s[4:5], s[8:9]
	s_andn2_b64 vcc, exec, s[4:5]
	s_cbranch_vccnz .LBB0_2412
	s_and_b64 s[4:5], s[30:31], exec
	s_cselect_b32 s14, 8, 1
	v_cvt_f32_ubyte0_e32 v0, s14
	v_rcp_iflag_f32_e32 v0, v0
	s_sub_i32 s8, 0, s14
	s_load_dwordx2 s[4:5], s[0:1], 0xd8
	s_ashr_i32 s3, s2, 31
	v_mul_f32_e32 v0, 0x4f7ffffe, v0
	v_cvt_u32_f32_e32 v0, v0
	s_abs_i32 s15, s2
	v_readfirstlane_b32 s18, v242
	v_readfirstlane_b32 s9, v0
	s_mul_i32 s8, s8, s9
	s_mul_hi_u32 s8, s9, s8
	s_add_i32 s12, s9, s8
	s_cmpk_lt_i32 s2, 0x200
	s_cselect_b64 s[8:9], -1, 0
	s_cmpk_gt_i32 s2, 0x1ff
	s_mul_hi_u32 s16, s15, s12
	s_cbranch_scc1 .LBB0_2227
	s_lshr_b32 s12, s3, 29
	s_add_i32 s17, s2, s12
	s_and_b32 s12, s17, -8
	s_sub_i32 s19, s2, s12
	s_cmp_gt_i32 s19, -1
	s_cbranch_scc0 .LBB0_2263
	s_lshl_b32 s20, s19, 6
	s_cbranch_execz .LBB0_2264
	s_branch .LBB0_2265

; #define PG8_STAGE(bufoff, gbase, voff) do { _Pragma("unroll") for (int _i = 0; _i < 2; ++_i) \
;         __builtin_amdgcn_global_load_lds((const unsigned*)((const char*)(gbase) + (voff)[_i]), (PG8_LAS unsigned*)(lds + (bufoff) + ldsw + _i * 8192), 16, 0, 0); } while (0)
; #define PG8_WAIT_V(n) asm volatile("s_waitcnt vmcnt(" #n ")" ::: "memory")
; #define PG8_BAR __builtin_amdgcn_s_barrier()
; template <class Epi, class Sched, bool ALIGN_EPI = false, bool SP2 = false>
; __device__ __forceinline__ void gemm_phase(PG8_LAS unsigned char* lds, const Gemm g, const Sched& S, const Epi& E) {
;     const int tid = threadIdx.x, wid = __builtin_amdgcn_readfirstlane(tid >> 6), lane = tid & 63, wr = wid >> 2, wc = wid & 3, fr = lane & 15, fq = lane >> 4;
;     const int K = g.K, nt = K / BK;
;     unsigned voffA[2], voffB[2];
; #pragma unroll
;     for (int i = 0; i < 2; ++i) { int R, C; stage_rc(tid * 16 + i * 8192, R, C); const int Rb = Epi::PERM ? ((R & ~31) + perm32(R & 31)) : R;
;         voffA[i] = (unsigned)(R * K + C) * 2u; voffB[i] = (unsigned)(Rb * K + C) * 2u; }
;     const size_t kstep = (size_t)(BK * 2);
;     const size_t hstep = (size_t)HALF * K * 2;
;     const size_t tstep = 2 * hstep;
;     const unsigned ldsw = (unsigned)wid * 1024u;
;     const int aoff = lds_byte(wr * 64 + fr, fq * 8), boff = lds_byte(wc * 32 + fr, fq * 8);
;     ...
;         PG8_STAGE(PG8_SB(0, 0), cB, voffB); PG8_STAGE(PG8_SB(0, 1), cB + hstep, voffB); PG8_STAGE(PG8_SA(0, 0), cA, voffA); PG8_STAGE(PG8_SA(0, 1), cA + hstep, voffA);
;         if (wr == 1) PG8_BAR;
;         PG8_WAIT_V(2); PG8_BAR;
;         PG8_STAGE(PG8_SB(1, 0), cB + kstep, voffB); PG8_STAGE(PG8_SA(1, 0), cA + kstep, voffA); PG8_STAGE(PG8_SB(1, 1), cB + hstep + kstep, voffB);
;         PG8_WAIT_V(6); PG8_BAR;
;     } else {
;         PG8_STAGE(PG8_SB(0, 0), cB, voffB); PG8_STAGE(PG8_SA(0, 0), cA, voffA); PG8_STAGE(PG8_SB(0, 1), cB + hstep, voffB); PG8_STAGE(PG8_SA(0, 1), cA + hstep, voffA);
;         if (wr == 1) PG8_BAR;
;         PG8_WAIT_V(4); PG8_BAR;
;         PG8_STAGE(PG8_SB(1, 0), cB + kstep, voffB); PG8_STAGE(PG8_SA(1, 0), cA + kstep, voffA); PG8_STAGE(PG8_SB(1, 1), cB + hstep + kstep, voffB);
;         PG8_WAIT_V(6); PG8_BAR;
;     }
;     for (;;) {
;         const bool has_next = S.next(ui + 1, nxt);
.LBB0_2230:
	s_add_u32 s12, s4, 0x6000000
	s_addc_u32 s13, s5, 0
	s_add_u32 s14, s4, 0x640000
	s_addc_u32 s15, s5, 0
	s_lshl_b32 s4, s7, 5
	s_mov_b64 s[16:17], 0x80
	s_and_b32 s7, s4, 0x60
	s_add_i32 m0, s41, 0x18000
	v_lshl_add_u64 v[6:7], v[6:7], 0, s[16:17]
	s_lshl_b32 s19, s6, 13
	s_lshl_b32 s20, s7, 7
	s_waitcnt vmcnt(2)
	s_barrier
	global_load_lds_dwordx4 v[6:7], off
	v_lshl_add_u64 v[4:5], v[4:5], 0, s[16:17]
	s_add_i32 m0, s41, 0x1a000
	s_add_i32 s57, s41, 0x8000
	s_add_i32 s58, s41, 0xa000
	global_load_lds_dwordx4 v[4:5], off
	v_lshl_add_u64 v[0:1], v[0:1], 0, s[16:17]
	s_mov_b32 m0, s57
	s_add_u32 s4, s44, 0x40080
	global_load_lds_dwordx4 v[0:1], off
	v_lshl_add_u64 v[0:1], v[2:3], 0, s[16:17]
	s_mov_b32 m0, s58
	s_addc_u32 s5, s45, 0
	global_load_lds_dwordx4 v[0:1], off
	s_add_i32 m0, s41, 0x1c000
	v_lshl_add_u64 v[0:1], s[4:5], 0, v[194:195]
	global_load_lds_dwordx4 v[0:1], off
	v_lshl_add_u64 v[0:1], s[4:5], 0, v[198:199]
	s_add_i32 m0, s41, 0x1e000
	v_lshlrev_b32_e32 v3, 2, v242
	global_load_lds_dwordx4 v[0:1], off
	v_bfe_u32 v0, v242, 4, 2
	v_and_b32_e32 v1, 15, v242
	v_lshlrev_b32_e32 v2, 4, v0
	v_lshlrev_b32_e32 v4, 6, v242
	s_movk_i32 s4, 0x3c0
	v_lshl_or_b32 v243, s6, 6, v1
	v_lshl_or_b32 v1, v1, 6, v2
	v_and_b32_e32 v3, 32, v3
	v_and_or_b32 v2, v4, s4, v2
	v_cmp_eq_u32_e64 s[4:5], 0, v0
	v_lshl_or_b32 v245, v0, 3, s7
	v_lshlrev_b32_e32 v0, 8, v242
	v_bitop3_b32 v244, s20, v2, v3 bitop3:0xf6
	v_and_b32_e32 v0, 0x38000, v0
	v_lshlrev_b32_e32 v2, 11, v10
	v_or3_b32 v0, v8, v0, v2
	v_add_u32_e32 v200, v0, v9
	v_lshlrev_b32_e32 v0, 4, v11
	v_and_b32_e32 v0, 0x78000, v0
	s_waitcnt vmcnt(6)
	s_cmpk_lt_u32 s18, 0x100
	v_or3_b32 v0, v8, v0, v2
	v_bitop3_b32 v1, v1, s19, v3 bitop3:0xde
	s_cselect_b64 s[18:19], -1, 0
	v_add_u32_e32 v202, v0, v9
	s_add_i32 s63, 0, 0x10000
	s_add_i32 s64, 0, 0x14000
	v_mbcnt_lo_u32_b32 v0, -1, 0
	s_ashr_i32 s59, s61, 31
	v_mov_b32_e32 v201, v195
	v_mov_b32_e32 v203, v195
	v_mov_b64_e32 v[204:205], 0x1ff
	v_add_u32_e32 v246, s63, v244
	v_add_u32_e32 v247, s64, v244
	v_add_u32_e32 v248, 0, v1
	v_mbcnt_hi_u32_b32 v249, -1, v0
	s_barrier
	v_readfirstlane_b32 s99, v242
	s_nop 3
	s_cmp_ge_u32 s99, 0x100
	s_cbranch_scc1 .Lprio_skip_9
	s_setprio 1
.Lprio_skip_9:
	s_branch .LBB0_2233
.LBB0_2231:
	s_mov_b64 s[6:7], 0

; #define PG8_STAGE(bufoff, gbase, voff) do { _Pragma("unroll") for (int _i = 0; _i < 2; ++_i) \
;         __builtin_amdgcn_global_load_lds((const unsigned*)((const char*)(gbase) + (voff)[_i]), (PG8_LAS unsigned*)(lds + (bufoff) + ldsw + _i * 8192), 16, 0, 0); } while (0)
; #define PG8_WAIT_V(n) asm volatile("s_waitcnt vmcnt(" #n ")" ::: "memory")
; #define PG8_BAR __builtin_amdgcn_s_barrier()
; template <class Epi, class Sched, bool ALIGN_EPI = false, bool SP2 = false>
; __device__ __forceinline__ void gemm_phase(PG8_LAS unsigned char* lds, const Gemm g, const Sched& S, const Epi& E) {
;     ...
;     const char* cA = (const char*)g.A + (size_t)cur.pm * tstep; const char* cB = (const char*)g.Bt + (size_t)cur.pn * tstep;
;     S.a_ready(cur);
;     if constexpr (SP2) {
;         PG8_STAGE(PG8_SB(0, 0), cB, voffB); PG8_STAGE(PG8_SB(0, 1), cB + hstep, voffB); PG8_STAGE(PG8_SA(0, 0), cA, voffA); PG8_STAGE(PG8_SA(0, 1), cA + hstep, voffA);
;         if (wr == 1) PG8_BAR;
;         PG8_WAIT_V(2); PG8_BAR;
;         PG8_STAGE(PG8_SB(1, 0), cB + kstep, voffB); PG8_STAGE(PG8_SA(1, 0), cA + kstep, voffA); PG8_STAGE(PG8_SB(1, 1), cB + hstep + kstep, voffB);
;         PG8_WAIT_V(6); PG8_BAR;
;     } else {
;         PG8_STAGE(PG8_SB(0, 0), cB, voffB); PG8_STAGE(PG8_SA(0, 0), cA, voffA); PG8_STAGE(PG8_SB(0, 1), cB + hstep, voffB); PG8_STAGE(PG8_SA(0, 1), cA + hstep, voffA);
;         if (wr == 1) PG8_BAR;
;         PG8_WAIT_V(4); PG8_BAR;
;         PG8_STAGE(PG8_SB(1, 0), cB + kstep, voffB); PG8_STAGE(PG8_SA(1, 0), cA + kstep, voffA); PG8_STAGE(PG8_SB(1, 1), cB + hstep + kstep, voffB);
;         PG8_WAIT_V(6); PG8_BAR;
;     }
;     for (;;) {
;         const bool has_next = S.next(ui + 1, nxt);
;         const char* nA = has_next ? (const char*)g.A + (size_t)nxt.pm * tstep : cA; const char* nB = has_next ? (const char*)g.Bt + (size_t)nxt.pn * tstep : cB;
; __device__ __forceinline__ void run_phase(const int ph, const Args& a, LAS unsigned char* lds, unsigned char* ldsg, const bool dummy = false) {
;     ...
;         } else if (EN_GU && kind == K_GU) {
;             pg8::Gemm g{HB, (const bf16*)(ws + WS_W + f * FFN_STRIDE), M, 2 * FF, D}; pg8::StaticOrder S; S.init(M, 2 * FF, G, bx);
;             pg8::EpiSwiglu E{ACT, FF, RS + (size_t)rsi * M};
;             pg8::gemm_phase<pg8::EpiSwiglu, pg8::StaticOrder, PG8_ALIGN, PG8_SP2>(lds, g, S, E);
.LBB0_2412:
	s_waitcnt lgkmcnt(0)
	s_setprio 0
	s_cmp_lt_i32 s6, 14
	s_cselect_b64 s[4:5], -1, 0
	s_cmp_gt_i32 s7, 13
	s_cselect_b64 s[8:9], -1, 0
	s_and_b64 s[4:5], s[4:5], s[8:9]
	s_andn2_b64 vcc, exec, s[4:5]
	s_cbranch_vccnz .LBB0_2575
	s_and_b64 s[4:5], s[30:31], exec
	s_cselect_b32 s8, 8, 1
	v_cvt_f32_ubyte0_e32 v0, s8
	v_rcp_iflag_f32_e32 v0, v0
	v_readfirstlane_b32 s17, v242
	s_cmpk_gt_i32 s2, 0xaff
	v_mul_f32_e32 v0, 0x4f7ffffe, v0
	v_cvt_u32_f32_e32 v0, v0
	s_nop 0
	v_readfirstlane_b32 s12, v0
	s_cbranch_scc1 .LBB0_2429
	v_lshrrev_b32_e32 v0, 5, v242
	v_lshrrev_b32_e32 v2, 1, v242
	s_sub_i32 s6, 0, s8
	s_load_dwordx2 s[4:5], s[0:1], 0xd8
	v_and_b32_e32 v0, 4, v0
	v_bfe_u32 v1, v242, 2, 2
	v_and_b32_e32 v11, 24, v2
	s_mul_i32 s6, s6, s12
	v_or3_b32 v0, v0, v1, v11
	v_lshlrev_b32_e32 v1, 4, v242
	s_mul_hi_u32 s6, s12, s6
	v_add_u32_e32 v8, 0x2000, v1
	s_add_i32 s15, s12, s6
	v_lshrrev_b32_e32 v2, 7, v8
	s_movk_i32 s6, 0xe0
	v_and_b32_e32 v4, 32, v242
	s_ashr_i32 s3, s2, 31
	s_abs_i32 s9, s2
	s_lshr_b32 s14, s17, 6
	v_and_or_b32 v3, v2, s6, v0
	v_bitop3_b32 v9, v1, v4, 48 bitop3:0x6c
	v_and_b32_e32 v10, 64, v242
	v_bfe_u32 v12, v242, 2, 4
	s_movk_i32 s6, 0xf0
	s_waitcnt lgkmcnt(0)
	s_add_u32 s44, s4, 0x6000000
	v_or_b32_e32 v1, v9, v10
	v_and_or_b32 v2, v2, s6, v12
	s_addc_u32 s45, s5, 0
	v_lshl_or_b32 v130, v2, 11, v1
	v_lshrrev_b32_e32 v2, 3, v242
	s_movk_i32 s6, 0x60
	s_add_u32 s46, s4, 0x3b00000
	v_and_or_b32 v0, v2, s6, v0
	s_movk_i32 s6, 0x70
	s_addc_u32 s47, s5, 0
	v_lshl_or_b32 v132, v0, 11, v1
	v_and_or_b32 v0, v2, s6, v12
	s_lshr_b32 s6, s3, 29
	s_add_i32 s6, s2, s6
	s_ashr_i32 s7, s6, 3
	s_and_b32 s6, s6, -8
	s_lshr_b32 s18, s17, 8
	s_lshl_b32 s48, s14, 10
	s_sub_i32 s6, s2, s6
	s_cmp_lt_i32 s6, 0
	s_movk_i32 s49, 0x161
	s_cselect_b32 s12, s49, 0x160
	s_mul_i32 s6, s12, s6
	s_add_i32 s6, s6, s7
	s_mul_hi_i32 s7, s6, 0x2e8ba2e9
	s_lshr_b32 s12, s7, 31
	s_ashr_i32 s7, s7, 5
	s_add_i32 s7, s7, s12
	s_lshl_b32 s12, s7, 3
	s_mulk_i32 s7, 0xb0
	s_sub_i32 s6, s6, s7
	s_sext_i32_i16 s7, s6
	s_bfe_u32 s7, s7, 0x3001c
	s_add_i32 s7, s6, s7
	s_sext_i32_i16 s13, s7
	s_and_b32 s7, s7, 0xfff8
	s_sub_i32 s6, s6, s7
	s_sext_i32_i16 s6, s6
	s_lshr_b32 s16, s13, 3
	s_add_i32 s36, s12, s6
	s_ashr_i32 s37, s36, 31
	s_bfe_i64 s[12:13], s[16:17], 0x100000
	s_lshl_b64 s[6:7], s[36:37], 19
	s_lshl_b64 s[12:13], s[12:13], 19
	s_add_u32 s40, s46, s12
	s_addc_u32 s41, s47, s13
	s_add_i32 s37, s48, 0
	s_add_i32 m0, s37, 0x10000
	v_lshl_or_b32 v128, v3, 11, v1
	global_load_lds_dwordx4 v132, s[40:41]
	s_add_i32 m0, s37, 0x12000
	s_add_u32 s12, s40, 0x40000
	global_load_lds_dwordx4 v128, s[40:41]
	s_addc_u32 s13, s41, 0
	s_add_i32 m0, s37, 0x14000
	v_lshl_or_b32 v134, v0, 11, v1
	global_load_lds_dwordx4 v132, s[12:13]
	s_add_i32 m0, s37, 0x16000
	s_add_u32 s38, s44, s6
	s_addc_u32 s39, s45, s7
	s_add_i32 s50, s37, 0x2000
	global_load_lds_dwordx4 v128, s[12:13]
	s_mov_b32 m0, s37
	s_add_u32 s6, s38, 0x40000
	global_load_lds_dwordx4 v134, s[38:39]
	s_mov_b32 m0, s50
	s_addc_u32 s7, s39, 0
	s_add_i32 s51, s37, 0x4000
	global_load_lds_dwordx4 v130, s[38:39]
	s_mov_b32 m0, s51
	s_add_i32 s52, s37, 0x6000
	global_load_lds_dwordx4 v134, s[6:7]
	s_mov_b32 m0, s52
	v_mov_b32_e32 v133, 0
	global_load_lds_dwordx4 v130, s[6:7]
	v_mov_b32_e32 v129, v133
	v_mov_b32_e32 v135, v133
	v_mov_b32_e32 v131, v133
	s_cmp_eq_u32 s18, 1
	s_mul_hi_u32 s12, s9, s15
	v_lshl_add_u64 v[6:7], s[40:41], 0, v[132:133]
	v_lshl_add_u64 v[4:5], s[40:41], 0, v[128:129]
	v_lshl_add_u64 v[0:1], s[38:39], 0, v[134:135]
	s_cselect_b64 s[6:7], -1, 0
	s_cmp_lg_u32 s18, 1
	v_lshl_add_u64 v[2:3], s[38:39], 0, v[130:131]
	s_cbranch_scc1 .LBB0_2416
	s_barrier
.LBB0_2416:
	s_mul_i32 s12, s12, s8
	s_sub_i32 s9, s9, s12
	s_sub_i32 s12, s9, s8
	s_cmp_ge_u32 s9, s8
	s_cselect_b32 s9, s12, s9
	s_sub_i32 s12, s9, s8
	s_cmp_ge_u32 s9, s8
	s_cselect_b32 s8, s12, s9
	s_xor_b32 s8, s8, s3
	s_sub_i32 s8, s8, s3
	s_ashr_i32 s9, s8, 31
	s_and_b64 s[12:13], s[30:31], exec
	s_cselect_b32 s12, 25, 28
	s_lshl_b64 s[12:13], s[8:9], s12
	s_add_u32 s15, s4, s12
	s_addc_u32 s19, s5, s13
	s_and_b64 s[12:13], s[30:31], exec
	s_cselect_b32 s12, 12, 15
	s_lshl_b64 s[8:9], s[8:9], s12
	s_mul_hi_u32 s12, s8, 0xffffea00
	s_sub_i32 s12, s12, s8
	s_mulk_i32 s9, 0xea00
	s_add_i32 s12, s12, s9
	s_mulk_i32 s8, 0xea00
	s_add_u32 s8, s15, s8
	s_addc_u32 s9, s19, s12
	s_add_u32 s8, s8, 0xa000000
	s_addc_u32 s9, s9, 0
	s_add_u32 s12, s4, 0x640000
	s_addc_u32 s13, s5, 0
	s_lshl_b32 s4, s14, 5
	s_mov_b64 s[14:15], 0x80
	s_and_b32 s20, s4, 0x60
	s_add_i32 m0, s37, 0x18000
	v_lshl_add_u64 v[6:7], v[6:7], 0, s[14:15]
	s_lshl_b32 s19, s18, 13
	s_lshl_b32 s21, s20, 7
	s_waitcnt vmcnt(2)
	s_barrier
	global_load_lds_dwordx4 v[6:7], off
	v_lshl_add_u64 v[4:5], v[4:5], 0, s[14:15]
	s_add_i32 m0, s37, 0x1a000
	s_add_i32 s53, s37, 0x8000
	s_add_i32 s54, s37, 0xa000
	global_load_lds_dwordx4 v[4:5], off
	v_lshl_add_u64 v[0:1], v[0:1], 0, s[14:15]
	s_mov_b32 m0, s53
	s_add_u32 s4, s40, 0x40080
	global_load_lds_dwordx4 v[0:1], off
	v_lshl_add_u64 v[0:1], v[2:3], 0, s[14:15]
	s_mov_b32 m0, s54
	s_addc_u32 s5, s41, 0
	global_load_lds_dwordx4 v[0:1], off
	s_add_i32 m0, s37, 0x1c000
	v_lshl_add_u64 v[0:1], s[4:5], 0, v[132:133]
	global_load_lds_dwordx4 v[0:1], off
	v_lshl_add_u64 v[0:1], s[4:5], 0, v[128:129]
	s_add_i32 m0, s37, 0x1e000
	v_lshlrev_b32_e32 v2, 2, v242
	global_load_lds_dwordx4 v[0:1], off
	v_and_b32_e32 v0, 15, v242
	v_lshlrev_b32_e32 v1, 1, v11
	v_lshlrev_b32_e32 v3, 6, v242
	s_movk_i32 s4, 0x3c0
	v_lshl_or_b32 v146, s18, 6, v0
	v_lshl_or_b32 v0, v0, 6, v1
	v_and_b32_e32 v2, 32, v2
	v_and_or_b32 v1, v3, s4, v1
	v_bitop3_b32 v147, s21, v1, v2 bitop3:0xf6
	v_lshlrev_b32_e32 v1, 8, v242
	v_bitop3_b32 v0, v0, s19, v2 bitop3:0xde
	v_and_b32_e32 v1, 0x38000, v1
	v_lshlrev_b32_e32 v2, 11, v12
	v_or3_b32 v1, v9, v1, v2
	v_add_u32_e32 v136, v1, v10
	v_lshlrev_b32_e32 v1, 4, v8
	s_waitcnt vmcnt(6)
	s_cmpk_lt_u32 s17, 0x100
	v_and_b32_e32 v1, 0x78000, v1
	s_sext_i32_i16 s63, s16
	s_cselect_b64 s[16:17], -1, 0
	v_or3_b32 v1, v9, v1, v2
	s_add_i32 s57, 0, 0x10000
	s_add_i32 s58, 0, 0x14000
	s_mov_b32 s55, 0
	s_ashr_i32 s56, s61, 31
	v_or_b32_e32 v148, s20, v11
	v_mov_b32_e32 v137, v133
	v_add_u32_e32 v138, v1, v10
	v_mov_b32_e32 v139, v133
	v_mov_b64_e32 v[140:141], 0xb00
	v_mov_b64_e32 v[142:143], 0xaff
	v_add_u32_e32 v149, s57, v147
	v_add_u32_e32 v150, s58, v147
	v_add_u32_e32 v151, 0, v0
	v_mov_b32_e32 v152, 0x358637bd
	s_movk_i32 s59, 0x1600
	s_barrier
	v_readfirstlane_b32 s99, v242
	s_nop 3
	s_cmp_ge_u32 s99, 0x100
	s_cbranch_scc1 .Lprio_skip_10
	s_setprio 1
.Lprio_skip_10:
	s_branch .LBB0_2419
.LBB0_2417:
	s_mov_b64 s[4:5], 0

; __device__ __forceinline__ void run_phase(const int ph, const Args& a, LAS unsigned char* lds, unsigned char* ldsg, const bool dummy = false) {
;     ...
;         } else if (EN_RES && kind == K_RES) {
;             const bf16* A = f < 4 ? ACT : OB; const int K = f < 4 ? FF : D;
;             const bf16* W = f < 4 ? (const bf16*)(ws + WS_W + f * FFN_STRIDE + WD_OFF) : f == 4 ? (const bf16*)(ws + WS_WOFOX) : (const bf16*)(ws + WS_WOSWA);
;             pg8::Gemm g{A, W, M, D, K}; pg8::StaticOrder S; S.init(M, D, G, bx);
;             pg8::EpiResid E{nullptr, HB, nullptr, dummy ? (bf16*)(ws + 416 * MiB) : HB, rso >= 0 ? (dummy ? (pg8::rss_t*)(ws + 480 * MiB) : RS + (size_t)rso * M) : nullptr, alpha};
;             pg8::gemm_phase<pg8::EpiResid, pg8::StaticOrder, PG8_ALIGN, PG8_SP2>(lds, g, S, E);
.LBB0_2575:
	s_waitcnt lgkmcnt(0)
	s_setprio 0
	s_cmp_lt_i32 s6, 15
	s_cselect_b64 s[4:5], -1, 0
	s_cmp_gt_i32 s7, 14
	s_cselect_b64 s[8:9], -1, 0
	s_and_b64 s[4:5], s[4:5], s[8:9]
	s_andn2_b64 vcc, exec, s[4:5]
	s_cbranch_vccnz .LBB0_2750
	s_and_b64 s[4:5], s[30:31], exec
	s_cselect_b32 s12, 8, 1
	v_cvt_f32_ubyte0_e32 v0, s12
	v_rcp_iflag_f32_e32 v0, v0
	v_readfirstlane_b32 s16, v242
	s_cmpk_gt_i32 s2, 0x1ff
	v_mul_f32_e32 v0, 0x4f7ffffe, v0
	v_cvt_u32_f32_e32 v0, v0
	s_nop 0
	v_readfirstlane_b32 s4, v0
	s_cbranch_scc1 .LBB0_2604
	s_sub_i32 s5, 0, s12
	s_mul_i32 s5, s5, s4
	s_ashr_i32 s3, s2, 31
	s_mul_hi_u32 s5, s4, s5
	s_add_i32 s6, s4, s5
	s_load_dwordx2 s[4:5], s[0:1], 0xd8
	s_lshr_b32 s7, s3, 29
	s_add_i32 s9, s2, s7
	s_and_b32 s7, s9, -8
	s_abs_i32 s13, s2
	s_sub_i32 s15, s2, s7
	s_cmp_gt_i32 s15, -1
	s_mul_hi_u32 s14, s13, s6
	s_cbranch_scc0 .LBB0_2579
	s_lshl_b32 s8, s15, 6
	s_ashr_i32 s9, s9, 3
	s_cbranch_execz .LBB0_2580
	s_branch .LBB0_2581

; #define PG8_STAGE(bufoff, gbase, voff) do { _Pragma("unroll") for (int _i = 0; _i < 2; ++_i) \
;         __builtin_amdgcn_global_load_lds((const unsigned*)((const char*)(gbase) + (voff)[_i]), (PG8_LAS unsigned*)(lds + (bufoff) + ldsw + _i * 8192), 16, 0, 0); } while (0)
; #define PG8_WAIT_V(n) asm volatile("s_waitcnt vmcnt(" #n ")" ::: "memory")
; #define PG8_BAR __builtin_amdgcn_s_barrier()
; template <class Epi, class Sched, bool ALIGN_EPI = false, bool SP2 = false>
; __device__ __forceinline__ void gemm_phase(PG8_LAS unsigned char* lds, const Gemm g, const Sched& S, const Epi& E) {
;     const int tid = threadIdx.x, wid = __builtin_amdgcn_readfirstlane(tid >> 6), lane = tid & 63, wr = wid >> 2, wc = wid & 3, fr = lane & 15, fq = lane >> 4;
;     const int K = g.K, nt = K / BK;
;     unsigned voffA[2], voffB[2];
; #pragma unroll
;     for (int i = 0; i < 2; ++i) { int R, C; stage_rc(tid * 16 + i * 8192, R, C); const int Rb = Epi::PERM ? ((R & ~31) + perm32(R & 31)) : R;
;         voffA[i] = (unsigned)(R * K + C) * 2u; voffB[i] = (unsigned)(Rb * K + C) * 2u; }
;     const size_t kstep = (size_t)(BK * 2);
;     const size_t hstep = (size_t)HALF * K * 2;
;     const size_t tstep = 2 * hstep;
;     const unsigned ldsw = (unsigned)wid * 1024u;
;     const int aoff = lds_byte(wr * 64 + fr, fq * 8), boff = lds_byte(wc * 32 + fr, fq * 8);
;     ...
;         PG8_STAGE(PG8_SB(0, 0), cB, voffB); PG8_STAGE(PG8_SB(0, 1), cB + hstep, voffB); PG8_STAGE(PG8_SA(0, 0), cA, voffA); PG8_STAGE(PG8_SA(0, 1), cA + hstep, voffA);
;         if (wr == 1) PG8_BAR;
;         PG8_WAIT_V(2); PG8_BAR;
;         PG8_STAGE(PG8_SB(1, 0), cB + kstep, voffB); PG8_STAGE(PG8_SA(1, 0), cA + kstep, voffA); PG8_STAGE(PG8_SB(1, 1), cB + hstep + kstep, voffB);
;         PG8_WAIT_V(6); PG8_BAR;
;     } else {
;         PG8_STAGE(PG8_SB(0, 0), cB, voffB); PG8_STAGE(PG8_SA(0, 0), cA, voffA); PG8_STAGE(PG8_SB(0, 1), cB + hstep, voffB); PG8_STAGE(PG8_SA(0, 1), cA + hstep, voffA);
;         if (wr == 1) PG8_BAR;
;         PG8_WAIT_V(4); PG8_BAR;
;         PG8_STAGE(PG8_SB(1, 0), cB + kstep, voffB); PG8_STAGE(PG8_SA(1, 0), cA + kstep, voffA); PG8_STAGE(PG8_SB(1, 1), cB + hstep + kstep, voffB);
;         PG8_WAIT_V(6); PG8_BAR;
;     }
;     for (;;) {
;         const bool has_next = S.next(ui + 1, nxt);
.LBB0_2583:
	s_add_u32 s12, s4, 0x6000000
	s_addc_u32 s13, s5, 0
	s_lshl_b32 s4, s7, 5
	s_mov_b64 s[14:15], 0x80
	s_and_b32 s7, s4, 0x60
	s_add_i32 m0, s49, 0x18000
	v_lshl_add_u64 v[6:7], v[6:7], 0, s[14:15]
	s_lshl_b32 s18, s6, 13
	s_lshl_b32 s19, s7, 7
	s_waitcnt vmcnt(2)
	s_barrier
	global_load_lds_dwordx4 v[6:7], off
	v_lshl_add_u64 v[4:5], v[4:5], 0, s[14:15]
	s_add_i32 m0, s49, 0x1a000
	s_add_i32 s54, s49, 0x8000
	s_add_i32 s55, s49, 0xa000
	global_load_lds_dwordx4 v[4:5], off
	v_lshl_add_u64 v[0:1], v[0:1], 0, s[14:15]
	s_mov_b32 m0, s54
	s_add_u32 s4, s40, 0xb0080
	global_load_lds_dwordx4 v[0:1], off
	v_lshl_add_u64 v[0:1], v[2:3], 0, s[14:15]
	s_mov_b32 m0, s55
	s_addc_u32 s5, s41, 0
	global_load_lds_dwordx4 v[0:1], off
	s_add_i32 m0, s49, 0x1c000
	v_lshl_add_u64 v[0:1], s[4:5], 0, v[170:171]
	global_load_lds_dwordx4 v[0:1], off
	v_lshl_add_u64 v[0:1], s[4:5], 0, v[174:175]
	s_add_i32 m0, s49, 0x1e000
	v_lshlrev_b32_e32 v3, 2, v242
	global_load_lds_dwordx4 v[0:1], off
	v_bfe_u32 v0, v242, 4, 2
	v_and_b32_e32 v1, 15, v242
	v_lshlrev_b32_e32 v2, 4, v0
	v_lshlrev_b32_e32 v4, 6, v242
	s_movk_i32 s4, 0x3c0
	v_lshl_or_b32 v198, s6, 6, v1
	v_lshl_or_b32 v1, v1, 6, v2
	v_and_b32_e32 v3, 32, v3
	v_and_or_b32 v2, v4, s4, v2
	s_waitcnt vmcnt(6)
	s_cmpk_lt_u32 s16, 0x100
	v_lshl_or_b32 v200, v0, 3, s7
	v_add_u16_e32 v0, v8, v9
	s_sext_i32_i8 s65, s17
	v_bitop3_b32 v1, v1, s18, v3 bitop3:0xde
	v_bitop3_b32 v199, s19, v2, v3 bitop3:0xf6
	s_cselect_b64 s[16:17], -1, 0
	v_lshrrev_b16_e32 v0, 1, v0
	s_add_i32 s57, 0, 0x10000
	s_add_i32 s58, 0, 0x14000
	s_ashr_i32 s56, s61, 31
	v_add_lshl_u32 v176, v10, v0, 1
	v_mov_b32_e32 v177, v171
	v_add_lshl_u32 v178, v11, v0, 1
	v_mov_b32_e32 v179, v171
	v_mov_b64_e32 v[180:181], 0x200
	v_mov_b64_e32 v[182:183], 0x1ff
	v_add_u32_e32 v201, s57, v199
	v_add_u32_e32 v202, s58, v199
	v_add_u32_e32 v203, 0, v1
	s_mov_b64 s[18:19], 0x40000
	s_mov_b64 s[20:21], 0x48000
	s_mov_b64 s[22:23], 0x50000
	s_mov_b64 s[34:35], 0x58000
	s_barrier
	v_readfirstlane_b32 s99, v242
	s_nop 3
	s_cmp_ge_u32 s99, 0x100
	s_cbranch_scc1 .Lprio_skip_11
	s_setprio 1
.Lprio_skip_11:
	s_branch .LBB0_2586
.LBB0_2584:
	s_mov_b64 s[4:5], 0

; #define PG8_STAGE(bufoff, gbase, voff) do { _Pragma("unroll") for (int _i = 0; _i < 2; ++_i) \
;         __builtin_amdgcn_global_load_lds((const unsigned*)((const char*)(gbase) + (voff)[_i]), (PG8_LAS unsigned*)(lds + (bufoff) + ldsw + _i * 8192), 16, 0, 0); } while (0)
; #define PG8_LDA(dst, b, h) do { _Pragma("unroll") for (int m = 0; m < 4; ++m) _Pragma("unroll") for (int k = 0; k < 2; ++k) dst[m][k] = *(const PG8_LAS bf16x8*)(lds + PG8_SA(b, h) + aoff + m * 2048 + k * 1024); } while (0)
; #define PG8_LDB(dst, b, h) do { _Pragma("unroll") for (int n = 0; n < 2; ++n) _Pragma("unroll") for (int k = 0; k < 2; ++k) dst[n][k] = *(const PG8_LAS bf16x8*)(lds + PG8_SB(b, h) + boff + n * 2048 + k * 1024); } while (0)
; #define PG8_WAIT_V(n) asm volatile("s_waitcnt vmcnt(" #n ")" ::: "memory")
; #define PG8_WAIT_L(n) asm volatile("s_waitcnt lgkmcnt(" #n ")" ::: "memory")
; template <class Epi, class Sched, bool ALIGN_EPI = false, bool SP2 = false>
; __device__ __forceinline__ void gemm_phase(PG8_LAS unsigned char* lds, const Gemm g, const Sched& S, const Epi& E) {
;     ...
;         const bool has_next = S.next(ui + 1, nxt);
;         const char* nA = has_next ? (const char*)g.A + (size_t)nxt.pm * tstep : cA; const char* nB = has_next ? (const char*)g.Bt + (size_t)nxt.pn * tstep : cB;
;         for (int t = 0; t < nt; t += 2) {
;             const bool last = (t == nt - 2);
;             if constexpr (Epi::PREFETCH) { if (t == nt - 4) E.prefetch(cur, lds + STAGE_BYTES + 1024, tid); }
;             const char* a1 = cA + (size_t)(t + 1) * kstep;
;             const char* a2 = last ? nA : cA + (size_t)(t + 2) * kstep; const char* b2 = last ? nB : cB + (size_t)(t + 2) * kstep;
;             const char* a3 = a2 + kstep; const char* b3 = b2 + kstep;
;             if (last && has_next) S.a_ready(nxt);
;             if constexpr (SP2) {
;             PG8_LDB(B0, 0, 0); PG8_LDB(B1, 0, 1); PG8_SCHED; PG8_LDA(At, 0, 0); PG8_STAGE(PG8_SA(1, 1), a1 + hstep, voffA);
;             PG8_WAIT_V(8); PG8_WAIT_L(0); PG8_BAR; PG8_MMA(0, 0, At, B0); PG8_MMA(0, 1, At, B1); PG8_BAR; PG8_SCHED;
;             PG8_LDA(At, 0, 1); PG8_STAGE(PG8_SB(0, 0), b2, voffB); PG8_STAGE(PG8_SB(0, 1), b2 + hstep, voffB); PG8_STAGE(PG8_SA(0, 0), a2, voffA);
;             PG8_WAIT_V(8); PG8_WAIT_L(0); PG8_BAR; PG8_MMA(1, 0, At, B0); PG8_MMA(1, 1, At, B1); PG8_BAR; PG8_SCHED;
.LBB0_2596:
	s_add_u32 s38, s38, 0xb0080
	s_addc_u32 s39, s39, 0
	s_add_u32 s66, s40, 0x100
	s_addc_u32 s67, s41, 0
	s_mov_b32 s68, -2
	ds_read_b128 v[128:131], v201
	ds_read_b128 v[132:135], v201 offset:1024
	ds_read_b128 v[136:139], v201 offset:2048
	ds_read_b128 v[140:143], v201 offset:3072
	ds_read_b128 v[144:147], v202
	ds_read_b128 v[148:151], v202 offset:1024
	ds_read_b128 v[152:155], v202 offset:2048
	ds_read_b128 v[156:159], v202 offset:3072
	s_add_u32 s40, s38, 0xfff50080
	s_addc_u32 s41, s39, -1
	s_cmp_eq_u32 s68, 40
	s_cselect_b32 s43, s7, s41
	s_cselect_b32 s42, s6, s40
	s_cselect_b32 s41, s37, s67
	s_cselect_b32 s40, s36, s66
	v_lshl_add_u64 v[196:197], s[38:39], 0, v[176:177]
	s_add_i32 m0, s49, 0xc000
	ds_read_b128 v[160:163], v203
	ds_read_b128 v[164:167], v203 offset:1024
	ds_read_b128 v[184:187], v203 offset:2048
	ds_read_b128 v[188:191], v203 offset:3072
	ds_read_b128 v[192:195], v203 offset:4096
	ds_read_b128 v[204:207], v203 offset:5120
	ds_read_b128 v[208:211], v203 offset:6144
	ds_read_b128 v[212:215], v203 offset:7168
	global_load_lds_dwordx4 v[196:197], off
	v_lshl_add_u64 v[196:197], s[38:39], 0, v[178:179]
	s_add_i32 m0, s49, 0xe000
	s_nop 0
	global_load_lds_dwordx4 v[196:197], off
	s_waitcnt vmcnt(8)
	s_waitcnt lgkmcnt(0)
	s_barrier
	v_mfma_f32_16x16x32_bf16 v[124:127], v[128:131], v[160:163], 0
	v_mfma_f32_16x16x32_bf16 v[120:123], v[136:139], v[160:163], 0
	v_mfma_f32_16x16x32_bf16 v[116:119], v[128:131], v[184:187], 0
	v_mfma_f32_16x16x32_bf16 v[104:107], v[136:139], v[184:187], 0
	v_mfma_f32_16x16x32_bf16 v[92:95], v[128:131], v[192:195], 0
	v_mfma_f32_16x16x32_bf16 v[88:91], v[136:139], v[192:195], 0
	v_mfma_f32_16x16x32_bf16 v[76:79], v[128:131], v[208:211], 0
	v_mfma_f32_16x16x32_bf16 v[72:75], v[136:139], v[208:211], 0
	v_mfma_f32_16x16x32_bf16 v[124:127], v[132:135], v[164:167], v[124:127]
	v_mfma_f32_16x16x32_bf16 v[120:123], v[140:143], v[164:167], v[120:123]
	v_mfma_f32_16x16x32_bf16 v[116:119], v[132:135], v[188:191], v[116:119]
	v_mfma_f32_16x16x32_bf16 v[104:107], v[140:143], v[188:191], v[104:107]
	v_mfma_f32_16x16x32_bf16 v[92:95], v[132:135], v[204:207], v[92:95]
	v_mfma_f32_16x16x32_bf16 v[88:91], v[140:143], v[204:207], v[88:91]
	v_mfma_f32_16x16x32_bf16 v[76:79], v[132:135], v[212:215], v[76:79]
	v_mfma_f32_16x16x32_bf16 v[72:75], v[140:143], v[212:215], v[72:75]
	v_mfma_f32_16x16x32_bf16 v[112:115], v[144:147], v[160:163], 0
	v_mfma_f32_16x16x32_bf16 v[108:111], v[152:155], v[160:163], 0
	v_mfma_f32_16x16x32_bf16 v[100:103], v[144:147], v[184:187], 0
	v_mfma_f32_16x16x32_bf16 v[96:99], v[152:155], v[184:187], 0
	v_mfma_f32_16x16x32_bf16 v[84:87], v[144:147], v[192:195], 0
	v_mfma_f32_16x16x32_bf16 v[80:83], v[152:155], v[192:195], 0
	v_mfma_f32_16x16x32_bf16 v[68:71], v[144:147], v[208:211], 0
	v_mfma_f32_16x16x32_bf16 v[64:67], v[152:155], v[208:211], 0
	v_mfma_f32_16x16x32_bf16 v[112:115], v[148:151], v[164:167], v[112:115]
	v_mfma_f32_16x16x32_bf16 v[108:111], v[156:159], v[164:167], v[108:111]
	v_mfma_f32_16x16x32_bf16 v[100:103], v[148:151], v[188:191], v[100:103]
	v_mfma_f32_16x16x32_bf16 v[96:99], v[156:159], v[188:191], v[96:99]
	v_mfma_f32_16x16x32_bf16 v[84:87], v[148:151], v[204:207], v[84:87]
	v_mfma_f32_16x16x32_bf16 v[80:83], v[156:159], v[204:207], v[80:83]
	v_mfma_f32_16x16x32_bf16 v[68:71], v[148:151], v[212:215], v[68:71]
	v_mfma_f32_16x16x32_bf16 v[64:67], v[156:159], v[212:215], v[64:67]
	s_barrier
	s_add_i32 s69, s57, s48
	v_lshl_add_u64 v[196:197], s[40:41], 0, v[170:171]
	s_mov_b32 m0, s69
	ds_read_b128 v[160:163], v203 offset:16384
	ds_read_b128 v[164:167], v203 offset:17408
	ds_read_b128 v[184:187], v203 offset:18432
	ds_read_b128 v[188:191], v203 offset:19456
	ds_read_b128 v[192:195], v203 offset:20480
	ds_read_b128 v[204:207], v203 offset:21504
	ds_read_b128 v[208:211], v203 offset:22528
	ds_read_b128 v[212:215], v203 offset:23552
	global_load_lds_dwordx4 v[196:197], off
	s_add_i32 m0, s69, 0x2000
	s_add_u32 s70, s40, 0xb0000
	v_lshl_add_u64 v[216:217], s[40:41], 0, v[174:175]
	s_addc_u32 s71, s41, 0
	s_add_i32 s69, s58, s48
	global_load_lds_dwordx4 v[216:217], off
	v_lshl_add_u64 v[218:219], s[70:71], 0, v[170:171]
	s_mov_b32 m0, s69
	v_lshl_add_u64 v[220:221], s[42:43], 0, v[172:173]
	global_load_lds_dwordx4 v[218:219], off
	v_lshl_add_u64 v[218:219], s[70:71], 0, v[174:175]
	s_add_i32 m0, s69, 0x2000
	s_nop 0
	global_load_lds_dwordx4 v[218:219], off
	v_lshl_add_u64 v[218:219], s[42:43], 0, v[168:169]
	s_mov_b32 m0, s49
	s_nop 0
	global_load_lds_dwordx4 v[218:219], off
	s_mov_b32 m0, s50
	s_nop 0
	global_load_lds_dwordx4 v[220:221], off
	s_waitcnt vmcnt(8)
	s_waitcnt lgkmcnt(0)
	s_barrier
; #define PG8_STAGE(bufoff, gbase, voff) do { _Pragma("unroll") for (int _i = 0; _i < 2; ++_i) \
;         __builtin_amdgcn_global_load_lds((const unsigned*)((const char*)(gbase) + (voff)[_i]), (PG8_LAS unsigned*)(lds + (bufoff) + ldsw + _i * 8192), 16, 0, 0); } while (0)
; #define PG8_LDA(dst, b, h) do { _Pragma("unroll") for (int m = 0; m < 4; ++m) _Pragma("unroll") for (int k = 0; k < 2; ++k) dst[m][k] = *(const PG8_LAS bf16x8*)(lds + PG8_SA(b, h) + aoff + m * 2048 + k * 1024); } while (0)
; #define PG8_LDB(dst, b, h) do { _Pragma("unroll") for (int n = 0; n < 2; ++n) _Pragma("unroll") for (int k = 0; k < 2; ++k) dst[n][k] = *(const PG8_LAS bf16x8*)(lds + PG8_SB(b, h) + boff + n * 2048 + k * 1024); } while (0)
; #define PG8_MMA(ai, bj, At, Bt) do { __builtin_amdgcn_s_setprio(1); _Pragma("unroll") for (int m = 0; m < 4; ++m) _Pragma("unroll") for (int n = 0; n < 2; ++n) _Pragma("unroll") for (int k = 0; k < 2; ++k) \
;         acc[ai][bj][m][n] = __builtin_amdgcn_mfma_f32_16x16x32_bf16(Bt[n][k], At[m][k], acc[ai][bj][m][n], 0, 0, 0); __builtin_amdgcn_s_setprio(0); } while (0)
; #define PG8_WAIT_V(n) asm volatile("s_waitcnt vmcnt(" #n ")" ::: "memory")
; #define PG8_WAIT_L(n) asm volatile("s_waitcnt lgkmcnt(" #n ")" ::: "memory")
; #define PG8_BAR __builtin_amdgcn_s_barrier()
; #define PG8_SCHED __builtin_amdgcn_sched_barrier(0)
; template <class Epi, class Sched, bool ALIGN_EPI = false, bool SP2 = false>
; __device__ __forceinline__ void gemm_phase(PG8_LAS unsigned char* lds, const Gemm g, const Sched& S, const Epi& E) {
;     ...
;             PG8_WAIT_V(8); PG8_WAIT_L(0); PG8_BAR; PG8_MMA(1, 0, At, B0); PG8_MMA(1, 1, At, B1); PG8_BAR; PG8_SCHED;
;             PG8_LDB(B0, 1, 0); PG8_LDB(B1, 1, 1); PG8_SCHED; PG8_LDA(At, 1, 0); PG8_STAGE(PG8_SA(0, 1), a2 + hstep, voffA);
;             PG8_WAIT_V(8); PG8_WAIT_L(0); PG8_BAR; PG8_MMA(0, 0, At, B0); PG8_MMA(0, 1, At, B1); PG8_BAR; PG8_SCHED;
	v_mfma_f32_16x16x32_bf16 v[60:63], v[128:131], v[160:163], 0
	v_mfma_f32_16x16x32_bf16 v[56:59], v[136:139], v[160:163], 0
	v_mfma_f32_16x16x32_bf16 v[44:47], v[128:131], v[184:187], 0
	v_mfma_f32_16x16x32_bf16 v[40:43], v[136:139], v[184:187], 0
	v_mfma_f32_16x16x32_bf16 v[28:31], v[128:131], v[192:195], 0
	v_mfma_f32_16x16x32_bf16 v[24:27], v[136:139], v[192:195], 0
	v_mfma_f32_16x16x32_bf16 v[12:15], v[128:131], v[208:211], 0
	v_mfma_f32_16x16x32_bf16 v[8:11], v[136:139], v[208:211], 0
	v_mfma_f32_16x16x32_bf16 v[60:63], v[132:135], v[164:167], v[60:63]
	v_mfma_f32_16x16x32_bf16 v[56:59], v[140:143], v[164:167], v[56:59]
	v_mfma_f32_16x16x32_bf16 v[44:47], v[132:135], v[188:191], v[44:47]
	v_mfma_f32_16x16x32_bf16 v[40:43], v[140:143], v[188:191], v[40:43]
	v_mfma_f32_16x16x32_bf16 v[28:31], v[132:135], v[204:207], v[28:31]
	v_mfma_f32_16x16x32_bf16 v[24:27], v[140:143], v[204:207], v[24:27]
	v_mfma_f32_16x16x32_bf16 v[12:15], v[132:135], v[212:215], v[12:15]
	v_mfma_f32_16x16x32_bf16 v[8:11], v[140:143], v[212:215], v[8:11]
	v_mfma_f32_16x16x32_bf16 v[52:55], v[144:147], v[160:163], 0
	v_mfma_f32_16x16x32_bf16 v[48:51], v[152:155], v[160:163], 0
	v_mfma_f32_16x16x32_bf16 v[36:39], v[144:147], v[184:187], 0
	v_mfma_f32_16x16x32_bf16 v[32:35], v[152:155], v[184:187], 0
	v_mfma_f32_16x16x32_bf16 v[20:23], v[144:147], v[192:195], 0
	v_mfma_f32_16x16x32_bf16 v[16:19], v[152:155], v[192:195], 0
	v_mfma_f32_16x16x32_bf16 v[4:7], v[144:147], v[208:211], 0
	v_mfma_f32_16x16x32_bf16 v[0:3], v[152:155], v[208:211], 0
	v_mfma_f32_16x16x32_bf16 v[52:55], v[148:151], v[164:167], v[52:55]
	v_mfma_f32_16x16x32_bf16 v[48:51], v[156:159], v[164:167], v[48:51]
	v_mfma_f32_16x16x32_bf16 v[36:39], v[148:151], v[188:191], v[36:39]
	v_mfma_f32_16x16x32_bf16 v[32:35], v[156:159], v[188:191], v[32:35]
	v_mfma_f32_16x16x32_bf16 v[20:23], v[148:151], v[204:207], v[20:23]
	v_mfma_f32_16x16x32_bf16 v[16:19], v[156:159], v[204:207], v[16:19]
	v_mfma_f32_16x16x32_bf16 v[4:7], v[148:151], v[212:215], v[4:7]
	v_mfma_f32_16x16x32_bf16 v[0:3], v[156:159], v[212:215], v[0:3]
	s_barrier
	s_add_i32 s69, 0, 0x18000
	s_add_i32 s70, 0, 0x1c000
	v_add_u32_e32 v140, s69, v199
	v_add_u32_e32 v156, s70, v199
	ds_read_b128 v[128:131], v140
	ds_read_b128 v[132:135], v140 offset:1024
	ds_read_b128 v[136:139], v140 offset:2048
	ds_read_b128 v[140:143], v140 offset:3072
	ds_read_b128 v[144:147], v156
	ds_read_b128 v[148:151], v156 offset:1024
	ds_read_b128 v[152:155], v156 offset:2048
	ds_read_b128 v[156:159], v156 offset:3072
	s_add_u32 s42, s42, 0xb0000
	s_addc_u32 s43, s43, 0
	s_mov_b32 m0, s51
	v_lshl_add_u64 v[222:223], s[42:43], 0, v[168:169]
	ds_read_b128 v[160:163], v203 offset:32768
	ds_read_b128 v[164:167], v203 offset:33792
	ds_read_b128 v[184:187], v203 offset:34816
	ds_read_b128 v[188:191], v203 offset:35840
	ds_read_b128 v[192:195], v203 offset:36864
	ds_read_b128 v[204:207], v203 offset:37888
	ds_read_b128 v[208:211], v203 offset:38912
	ds_read_b128 v[212:215], v203 offset:39936
	global_load_lds_dwordx4 v[222:223], off
	v_lshl_add_u64 v[222:223], s[42:43], 0, v[172:173]
	s_mov_b32 m0, s52
	s_nop 0
	global_load_lds_dwordx4 v[222:223], off
	s_waitcnt vmcnt(8)
	s_waitcnt lgkmcnt(0)
	s_barrier
	v_mfma_f32_16x16x32_bf16 v[124:127], v[128:131], v[160:163], v[124:127]
	v_mfma_f32_16x16x32_bf16 v[120:123], v[136:139], v[160:163], v[120:123]
	v_mfma_f32_16x16x32_bf16 v[116:119], v[128:131], v[184:187], v[116:119]
	v_mfma_f32_16x16x32_bf16 v[104:107], v[136:139], v[184:187], v[104:107]
	v_mfma_f32_16x16x32_bf16 v[92:95], v[128:131], v[192:195], v[92:95]
	v_mfma_f32_16x16x32_bf16 v[88:91], v[136:139], v[192:195], v[88:91]
	v_mfma_f32_16x16x32_bf16 v[76:79], v[128:131], v[208:211], v[76:79]
	v_mfma_f32_16x16x32_bf16 v[72:75], v[136:139], v[208:211], v[72:75]
	v_mfma_f32_16x16x32_bf16 v[124:127], v[132:135], v[164:167], v[124:127]
	v_mfma_f32_16x16x32_bf16 v[120:123], v[140:143], v[164:167], v[120:123]
	v_mfma_f32_16x16x32_bf16 v[116:119], v[132:135], v[188:191], v[116:119]
	v_mfma_f32_16x16x32_bf16 v[104:107], v[140:143], v[188:191], v[104:107]
	v_mfma_f32_16x16x32_bf16 v[92:95], v[132:135], v[204:207], v[92:95]
	v_mfma_f32_16x16x32_bf16 v[88:91], v[140:143], v[204:207], v[88:91]
	v_mfma_f32_16x16x32_bf16 v[76:79], v[132:135], v[212:215], v[76:79]
	v_mfma_f32_16x16x32_bf16 v[72:75], v[140:143], v[212:215], v[72:75]
	v_mfma_f32_16x16x32_bf16 v[112:115], v[144:147], v[160:163], v[112:115]
	v_mfma_f32_16x16x32_bf16 v[108:111], v[152:155], v[160:163], v[108:111]
	v_mfma_f32_16x16x32_bf16 v[100:103], v[144:147], v[184:187], v[100:103]
	v_mfma_f32_16x16x32_bf16 v[96:99], v[152:155], v[184:187], v[96:99]
	v_mfma_f32_16x16x32_bf16 v[84:87], v[144:147], v[192:195], v[84:87]
	v_mfma_f32_16x16x32_bf16 v[80:83], v[152:155], v[192:195], v[80:83]
	v_mfma_f32_16x16x32_bf16 v[68:71], v[144:147], v[208:211], v[68:71]
	v_mfma_f32_16x16x32_bf16 v[64:67], v[152:155], v[208:211], v[64:67]
	v_mfma_f32_16x16x32_bf16 v[112:115], v[148:151], v[164:167], v[112:115]
	v_mfma_f32_16x16x32_bf16 v[108:111], v[156:159], v[164:167], v[108:111]
	v_mfma_f32_16x16x32_bf16 v[100:103], v[148:151], v[188:191], v[100:103]
	v_mfma_f32_16x16x32_bf16 v[96:99], v[156:159], v[188:191], v[96:99]
	v_mfma_f32_16x16x32_bf16 v[84:87], v[148:151], v[204:207], v[84:87]
	v_mfma_f32_16x16x32_bf16 v[80:83], v[156:159], v[204:207], v[80:83]
	v_mfma_f32_16x16x32_bf16 v[68:71], v[148:151], v[212:215], v[68:71]
	v_mfma_f32_16x16x32_bf16 v[64:67], v[156:159], v[212:215], v[64:67]
	s_barrier
; #define PG8_STAGE(bufoff, gbase, voff) do { _Pragma("unroll") for (int _i = 0; _i < 2; ++_i) \
;         __builtin_amdgcn_global_load_lds((const unsigned*)((const char*)(gbase) + (voff)[_i]), (PG8_LAS unsigned*)(lds + (bufoff) + ldsw + _i * 8192), 16, 0, 0); } while (0)
; #define PG8_LDA(dst, b, h) do { _Pragma("unroll") for (int m = 0; m < 4; ++m) _Pragma("unroll") for (int k = 0; k < 2; ++k) dst[m][k] = *(const PG8_LAS bf16x8*)(lds + PG8_SA(b, h) + aoff + m * 2048 + k * 1024); } while (0)
; #define PG8_MMA(ai, bj, At, Bt) do { __builtin_amdgcn_s_setprio(1); _Pragma("unroll") for (int m = 0; m < 4; ++m) _Pragma("unroll") for (int n = 0; n < 2; ++n) _Pragma("unroll") for (int k = 0; k < 2; ++k) \
;         acc[ai][bj][m][n] = __builtin_amdgcn_mfma_f32_16x16x32_bf16(Bt[n][k], At[m][k], acc[ai][bj][m][n], 0, 0, 0); __builtin_amdgcn_s_setprio(0); } while (0)
; #define PG8_WAIT_V(n) asm volatile("s_waitcnt vmcnt(" #n ")" ::: "memory")
; #define PG8_WAIT_L(n) asm volatile("s_waitcnt lgkmcnt(" #n ")" ::: "memory")
; #define PG8_BAR __builtin_amdgcn_s_barrier()
; #define PG8_SCHED __builtin_amdgcn_sched_barrier(0)
; template <class Epi, class Sched, bool ALIGN_EPI = false, bool SP2 = false>
; __device__ __forceinline__ void gemm_phase(PG8_LAS unsigned char* lds, const Gemm g, const Sched& S, const Epi& E) {
;     ...
;         for (int t = 0; t < nt; t += 2) {
;     ...
;             PG8_LDA(At, 1, 1); PG8_STAGE(PG8_SB(1, 0), b3, voffB); PG8_STAGE(PG8_SB(1, 1), b3 + hstep, voffB); PG8_STAGE(PG8_SA(1, 0), a3, voffA);
;             PG8_WAIT_V(8); PG8_WAIT_L(0); PG8_BAR; PG8_MMA(1, 0, At, B0); PG8_MMA(1, 1, At, B1); PG8_BAR; PG8_SCHED;
	s_add_i32 s42, s69, s48
	v_lshl_add_u64 v[196:197], v[196:197], 0, s[14:15]
	s_mov_b32 m0, s42
	ds_read_b128 v[160:163], v203 offset:49152
	ds_read_b128 v[164:167], v203 offset:50176
	ds_read_b128 v[184:187], v203 offset:51200
	ds_read_b128 v[188:191], v203 offset:52224
	ds_read_b128 v[192:195], v203 offset:53248
	ds_read_b128 v[204:207], v203 offset:54272
	ds_read_b128 v[208:211], v203 offset:55296
	ds_read_b128 v[212:215], v203 offset:56320
	global_load_lds_dwordx4 v[196:197], off
	s_add_i32 m0, s42, 0x2000
	s_add_u32 s40, s40, 0xb0080
	v_lshl_add_u64 v[196:197], v[216:217], 0, s[14:15]
	s_addc_u32 s41, s41, 0
	s_add_i32 s42, s70, s48
	global_load_lds_dwordx4 v[196:197], off
	v_lshl_add_u64 v[196:197], s[40:41], 0, v[170:171]
	s_mov_b32 m0, s42
	s_nop 0
	global_load_lds_dwordx4 v[196:197], off
	v_lshl_add_u64 v[196:197], s[40:41], 0, v[174:175]
	s_add_i32 m0, s42, 0x2000
	s_nop 0
	global_load_lds_dwordx4 v[196:197], off
	v_lshl_add_u64 v[196:197], v[218:219], 0, s[14:15]
	s_mov_b32 m0, s54
	s_nop 0
	global_load_lds_dwordx4 v[196:197], off
	v_lshl_add_u64 v[196:197], v[220:221], 0, s[14:15]
	s_mov_b32 m0, s55
	s_nop 0
	global_load_lds_dwordx4 v[196:197], off
	s_waitcnt vmcnt(8)
	s_waitcnt lgkmcnt(0)
	s_barrier
	v_mfma_f32_16x16x32_bf16 v[60:63], v[128:131], v[160:163], v[60:63]
	v_mfma_f32_16x16x32_bf16 v[56:59], v[136:139], v[160:163], v[56:59]
	v_mfma_f32_16x16x32_bf16 v[44:47], v[128:131], v[184:187], v[44:47]
	v_mfma_f32_16x16x32_bf16 v[40:43], v[136:139], v[184:187], v[40:43]
	v_mfma_f32_16x16x32_bf16 v[28:31], v[128:131], v[192:195], v[28:31]
	v_mfma_f32_16x16x32_bf16 v[24:27], v[136:139], v[192:195], v[24:27]
	v_mfma_f32_16x16x32_bf16 v[12:15], v[128:131], v[208:211], v[12:15]
	v_mfma_f32_16x16x32_bf16 v[8:11], v[136:139], v[208:211], v[8:11]
	v_mfma_f32_16x16x32_bf16 v[60:63], v[132:135], v[164:167], v[60:63]
	v_mfma_f32_16x16x32_bf16 v[56:59], v[140:143], v[164:167], v[56:59]
	v_mfma_f32_16x16x32_bf16 v[44:47], v[132:135], v[188:191], v[44:47]
	v_mfma_f32_16x16x32_bf16 v[40:43], v[140:143], v[188:191], v[40:43]
	v_mfma_f32_16x16x32_bf16 v[28:31], v[132:135], v[204:207], v[28:31]
	v_mfma_f32_16x16x32_bf16 v[24:27], v[140:143], v[204:207], v[24:27]
	v_mfma_f32_16x16x32_bf16 v[12:15], v[132:135], v[212:215], v[12:15]
	v_mfma_f32_16x16x32_bf16 v[8:11], v[140:143], v[212:215], v[8:11]
	v_mfma_f32_16x16x32_bf16 v[52:55], v[144:147], v[160:163], v[52:55]
	v_mfma_f32_16x16x32_bf16 v[48:51], v[152:155], v[160:163], v[48:51]
	v_mfma_f32_16x16x32_bf16 v[36:39], v[144:147], v[184:187], v[36:39]
	v_mfma_f32_16x16x32_bf16 v[32:35], v[152:155], v[184:187], v[32:35]
	v_mfma_f32_16x16x32_bf16 v[20:23], v[144:147], v[192:195], v[20:23]
	v_mfma_f32_16x16x32_bf16 v[16:19], v[152:155], v[192:195], v[16:19]
	v_mfma_f32_16x16x32_bf16 v[4:7], v[144:147], v[208:211], v[4:7]
	v_mfma_f32_16x16x32_bf16 v[0:3], v[152:155], v[208:211], v[0:3]
	v_mfma_f32_16x16x32_bf16 v[52:55], v[148:151], v[164:167], v[52:55]
	v_mfma_f32_16x16x32_bf16 v[48:51], v[156:159], v[164:167], v[48:51]
	v_mfma_f32_16x16x32_bf16 v[36:39], v[148:151], v[188:191], v[36:39]
	v_mfma_f32_16x16x32_bf16 v[32:35], v[156:159], v[188:191], v[32:35]
	v_mfma_f32_16x16x32_bf16 v[20:23], v[148:151], v[204:207], v[20:23]
	v_mfma_f32_16x16x32_bf16 v[16:19], v[156:159], v[204:207], v[16:19]
	v_mfma_f32_16x16x32_bf16 v[4:7], v[148:151], v[212:215], v[4:7]
	v_mfma_f32_16x16x32_bf16 v[0:3], v[156:159], v[212:215], v[0:3]
	s_barrier
	s_add_i32 s68, s68, 2
	s_add_u32 s38, s38, 0x100
	s_addc_u32 s39, s39, 0
	s_add_u32 s66, s66, 0x100
	s_addc_u32 s67, s67, 0

; __device__ __forceinline__ void run_phase(const int ph, const Args& a, LAS unsigned char* lds, unsigned char* ldsg, const bool dummy = false) {
;     ...
;         } else if (EN_FIN) {
;             const float* gfin = a.in[25];
;             const int perm_ = M / ngrp;
;             for (int mi = 2 * (gj * 8 + wave); mi < perm_; mi += 2 * gsize * 8) { const int m = gx * perm_ + mi;
;                 const u32x2* hr = (const u32x2*)(HB + (size_t)m * D) + lane; u32x2 hv[8];
; #pragma unroll
;                 for (int j = 0; j < 8; ++j) hv[j] = hr[64 * j];
;                 f32x4 v[8]; float s0 = 0.f, s1 = 0.f;
; #pragma unroll
;                 for (int j = 0; j < 8; ++j) { v[j] = (f32x4){__uint_as_float(hv[j].x << 16), __uint_as_float(hv[j].x & 0xffff0000u), __uint_as_float(hv[j].y << 16), __uint_as_float(hv[j].y & 0xffff0000u)};
;                     const float q = (v[j].x * v[j].x + v[j].y * v[j].y) + (v[j].z * v[j].z + v[j].w * v[j].w); if (j < 4) s0 += q; else s1 += q; }
;                 const float r0 = __builtin_amdgcn_rsqf(wave_sum(s0) * (1.0f / 1024.0f) + 1e-6f), r1 = __builtin_amdgcn_rsqf(wave_sum(s1) * (1.0f / 1024.0f) + 1e-6f);
;                 f32x4* xr = (f32x4*)(a.out + (size_t)m * D) + lane;
; #pragma unroll
;                 for (int j = 0; j < 8; ++j) { const f32x4 gg = *((const f32x4*)gfin + lane + 64 * (j & 3)); xr[64 * j] = v[j] * (j < 4 ? r0 : r1) * gg; } }
.LBB0_2750:
	s_waitcnt lgkmcnt(0)
	s_setprio 0
	s_cmp_lt_i32 s6, 16
	s_cselect_b64 s[4:5], -1, 0
	s_cmp_gt_i32 s7, 15
	s_cselect_b64 s[8:9], -1, 0
	s_and_b64 s[4:5], s[4:5], s[8:9]
	s_andn2_b64 vcc, exec, s[4:5]
	s_cbranch_vccnz .LBB0_2901
	s_and_b64 s[4:5], s[30:31], exec
	s_cselect_b32 s14, 8, 1
	v_cvt_f32_ubyte0_e32 v0, s14
	v_rcp_iflag_f32_e32 v0, v0
	s_sub_i32 s15, 0, s14
	s_abs_i32 s4, s2
	s_ashr_i32 s3, s2, 31
	v_mul_f32_e32 v0, 0x4f7ffffe, v0
	v_cvt_u32_f32_e32 v0, v0
	v_readfirstlane_b32 s6, v242
	v_readfirstlane_b32 s5, v0
	s_mul_i32 s8, s15, s5
	s_mul_hi_u32 s8, s5, s8
	s_add_i32 s5, s5, s8
	s_mul_hi_u32 s5, s4, s5
	s_mul_i32 s8, s5, s14
	s_sub_i32 s4, s4, s8
	s_add_i32 s9, s5, 1
	s_sub_i32 s8, s4, s14
	s_cmp_ge_u32 s4, s14
	s_cselect_b32 s5, s9, s5
	s_cselect_b32 s4, s8, s4
	s_add_i32 s8, s5, 1
	s_cmp_ge_u32 s4, s14
	s_cselect_b32 s4, s8, s5
	s_xor_b32 s12, s4, s3
	s_sub_i32 s16, s12, s3
	s_movk_i32 s8, 0x1000
	s_and_b64 s[4:5], s[30:31], exec
	s_cselect_b32 s8, s8, 0x8000
	s_lshr_b32 s5, s6, 5
	s_lshl_b32 s4, s16, 4
	s_and_b32 s13, s5, 0x7fffffe
	s_add_i32 s9, s4, s13
	s_cmp_ge_i32 s9, s8
	s_cbranch_scc1 .LBB0_2755
	v_readfirstlane_b32 s20, v0
	v_mbcnt_lo_u32_b32 v0, -1, 0
	v_mbcnt_hi_u32_b32 v0, -1, v0
	v_and_b32_e32 v1, 64, v0
	v_add_u32_e32 v1, 64, v1
	v_xor_b32_e32 v3, 1, v0
	v_cmp_lt_i32_e32 vcc, v3, v1
	s_mul_i32 s15, s15, s20
	s_mul_hi_u32 s15, s20, s15
	v_cndmask_b32_e32 v3, v0, v3, vcc
	v_lshlrev_b32_e32 v14, 2, v3
	v_xor_b32_e32 v3, 2, v0
	s_abs_i32 s17, s61
	s_add_i32 s20, s20, s15
	v_cmp_lt_i32_e32 vcc, v3, v1
	s_mul_hi_u32 s15, s17, s20
	s_mul_i32 s20, s15, s14
	v_cndmask_b32_e32 v3, v0, v3, vcc
	v_lshlrev_b32_e32 v15, 2, v3
	v_xor_b32_e32 v3, 4, v0
	s_mul_i32 s16, s16, s14
	s_sub_i32 s17, s17, s20
	v_cmp_lt_i32_e32 vcc, v3, v1
	s_sub_i32 s2, s2, s16
	s_ashr_i32 s16, s61, 31
	s_add_i32 s20, s15, 1
	s_sub_i32 s21, s17, s14
	v_cndmask_b32_e32 v3, v0, v3, vcc
	s_cmp_ge_u32 s17, s14
	v_lshlrev_b32_e32 v16, 2, v3
	v_xor_b32_e32 v3, 8, v0
	s_cselect_b32 s15, s20, s15
	v_cmp_lt_i32_e32 vcc, v3, v1
	s_cselect_b32 s17, s21, s17
	s_add_i32 s20, s15, 1
	v_cndmask_b32_e32 v3, v0, v3, vcc
	s_cmp_ge_u32 s17, s14
	v_lshlrev_b32_e32 v17, 2, v3
	v_xor_b32_e32 v3, 16, v0
	s_cselect_b32 s14, s20, s15
	v_cmp_lt_i32_e32 vcc, v3, v1
	s_load_dwordx4 s[4:7], s[0:1], 0xc8
	s_load_dwordx2 s[18:19], s[0:1], 0xd8
	s_xor_b32 s14, s14, s16
	v_cndmask_b32_e32 v3, v0, v3, vcc
	s_sub_i32 s16, s14, s16
	v_lshlrev_b32_e32 v18, 2, v3
	v_xor_b32_e32 v3, 32, v0
	v_and_b32_e32 v2, 63, v242
	s_and_b64 s[14:15], s[30:31], exec
	v_cmp_lt_i32_e32 vcc, v3, v1
	s_cselect_b32 s14, 12, 15
	v_lshlrev_b32_e32 v4, 4, v2
	v_cndmask_b32_e32 v0, v0, v3, vcc
	v_mov_b32_e32 v5, 0
	s_lshl_b32 s14, s2, s14
	v_lshlrev_b32_e32 v19, 2, v0
	s_waitcnt lgkmcnt(0)
	v_lshl_add_u64 v[0:1], s[4:5], 0, v[4:5]
	s_lshl_b32 s4, s12, 4
	s_add_i32 s4, s14, s4
	s_add_i32 s4, s4, s13
	s_lshl_b32 s3, s3, 4
	s_sub_i32 s12, s4, s3
	s_ashr_i32 s13, s12, 31
	s_lshl_b32 s2, s16, 4
	s_lshl_b64 s[4:5], s[12:13], 11
	s_add_u32 s4, s18, s4
	v_lshlrev_b32_e32 v2, 3, v2
	v_mov_b32_e32 v3, v5
	s_addc_u32 s5, s19, s5
	v_lshl_add_u64 v[2:3], s[4:5], 0, v[2:3]
	s_mov_b64 s[4:5], 0x6000000
	s_ashr_i32 s3, s2, 31
	v_lshl_add_u64 v[2:3], v[2:3], 0, s[4:5]
	s_lshl_b64 s[4:5], s[2:3], 11
	s_lshl_b64 s[12:13], s[12:13], 12
	s_add_u32 s6, s6, s12
	s_addc_u32 s7, s7, s13
	v_lshl_add_u64 v[4:5], s[6:7], 0, v[4:5]
	s_mov_b64 s[6:7], 0x1000
	v_lshl_add_u64 v[4:5], v[4:5], 0, s[6:7]
	s_lshl_b64 s[6:7], s[2:3], 12
	v_mov_b32_e32 v20, 0x358637bd
